# v16 variant: progressive A-fragment hoist extended by one read (the read whose last user is MFMA 15 is issued before the group-closing barrier)
# baseline (speedup 1.0000x reference)
; #define PG8_STAGE(bufoff, gbase, voff) do { _Pragma("unroll") for (int _i = 0; _i < 2; ++_i) \
;         __builtin_amdgcn_global_load_lds((const unsigned*)((const char*)(gbase) + (voff)[_i]), (LAS unsigned*)(lds + (bufoff) + ldsw + _i * 8192), 16, 0, 0); } while (0)
; #define PG8_LDA(dst, b, h) do { _Pragma("unroll") for (int m = 0; m < 4; ++m) _Pragma("unroll") for (int k = 0; k < 2; ++k) dst[m][k] = *(const LAS bf16x8*)(lds + PG8_SA(b, h) + aoff + m * 2048 + k * 1024); } while (0)
; #define PG8_LDB(dst, b, h) do { _Pragma("unroll") for (int n = 0; n < 2; ++n) _Pragma("unroll") for (int k = 0; k < 2; ++k) dst[n][k] = *(const LAS bf16x8*)(lds + PG8_SB(b, h) + boff + n * 2048 + k * 1024); } while (0)
; #define PG8_WAIT_V(n) asm volatile("s_waitcnt vmcnt(" #n ")" ::: "memory")
; #define PG8_WAIT_L(n) asm volatile("s_waitcnt lgkmcnt(" #n ")" ::: "memory")
; #define PG8_BAR __builtin_amdgcn_s_barrier()
; #define PG8_SCHED __builtin_amdgcn_sched_barrier(0)
; template <class Epi, class Sched>
; __device__ __forceinline__ void gemm_phase(LAS unsigned char* lds, const Gemm g, const Sched& S, const Epi& E) {
;     ...
;         const bool has_next = S.next(ui + 1, nxt);
;         const char* nA = has_next ? PG8_APANEL(nxt.pm) : cA; const char* nB = has_next ? (const char*)g.Bt + (size_t)nxt.pn * tstep : cB;
;         for (int t = 0; t < nt; t += 2) {
;             const bool last = (t == nt - 2);
;             const char* a1 = cA + (size_t)(t + 1) * kstep;
;             const char* a2 = last ? nA : cA + (size_t)(t + 2) * kstep; const char* b2 = last ? nB : cB + (size_t)(t + 2) * kstep;
;             const char* a3 = a2 + kstep; const char* b3 = b2 + kstep;
;             PG8_LDB(B0, 0, 0); PG8_SCHED; PG8_LDA(At, 0, 0); PG8_STAGE(PG8_SA(1, 1), a1 + hstep, voffA);
;             PG8_WAIT_L(8); PG8_BAR; PG8_WAIT_L(0); PG8_MMA(0, 0, At, B0); PG8_BAR; PG8_SCHED;
;             PG8_LDB(B1, 0, 1); PG8_STAGE(PG8_SB(0, 0), b2, voffB);
;             PG8_BAR; PG8_WAIT_L(0); PG8_MMA(0, 1, At, B1); PG8_BAR;
;             PG8_LDA(At, 0, 1); PG8_STAGE(PG8_SA(0, 0), a2, voffA);
;             PG8_BAR; PG8_WAIT_L(0); PG8_MMA(1, 0, At, B0); PG8_BAR; PG8_SCHED;
;             PG8_STAGE(PG8_SB(0, 1), b2 + hstep, voffB);
;             PG8_WAIT_V(6); PG8_BAR; PG8_MMA(1, 1, At, B1); PG8_BAR;
.LBB0_164:
	s_cmp_lt_i32 s44, 0x100000
	s_cselect_b32 s24, s20, 0xffffff80
	s_cselect_b32 s25, s11, 0
	s_ashr_i32 s45, s44, 31
	s_lshl_b64 s[34:35], s[44:45], 19
	v_cmp_lt_i64_e32 vcc, s[46:47], v[152:153]
	s_add_u32 s46, s25, s34
	s_addc_u32 s47, s24, s35
	s_and_b64 s[34:35], vcc, exec
	s_cselect_b32 s34, s47, s49
	s_cselect_b32 s45, s46, s48
	s_ashr_i32 s43, s42, 31
	s_lshl_b64 s[60:61], s[42:43], 19
	s_add_u32 s76, s16, s60
	s_addc_u32 s77, s92, s61
	s_and_b64 s[60:61], vcc, exec
	s_cselect_b32 s43, s77, s39
	s_cselect_b32 s79, s76, s38
	s_add_u32 vcc_lo, s38, 0x100
	s_addc_u32 s35, s39, 0
	s_add_u32 s38, s48, 0x40080
	s_addc_u32 s39, s49, 0
	s_mov_b32 s50, -2
	v_add_u32_e32 v249, 0x10000, v167
	ds_read_b128 v[142:145], v249
	ds_read_b128 v[162:165], v249 offset:1024
	ds_read_b128 v[182:185], v249 offset:2048
	ds_read_b128 v[186:189], v249 offset:3072
	ds_read_b128 v[190:193], v169
	ds_read_b128 v[194:197], v169 offset:1024
	ds_read_b128 v[198:201], v169 offset:2048
	ds_read_b128 v[202:205], v169 offset:3072
	ds_read_b128 v[206:209], v169 offset:4096
	ds_read_b128 v[210:213], v169 offset:5120
	ds_read_b128 v[214:217], v169 offset:6144
	s_add_u32 s24, s38, 0xfffc0080
	s_addc_u32 s25, s39, -1
	s_add_i32 vcc_hi, 0, 0x10000
	s_cmp_eq_u32 s50, 12
	s_cselect_b32 s61, s34, s25
	s_cselect_b32 s60, s45, s24
	s_cselect_b32 s49, s43, s35
	s_cselect_b32 s48, s79, vcc_lo
	s_add_i32 m0, s93, 0xc000
	ds_read_b128 v[218:221], v169 offset:7168
	global_load_lds_dwordx4 v140, s[38:39]
	s_add_i32 m0, s93, 0xe000
	s_nop 0
	global_load_lds_dwordx4 v138, s[38:39]
	s_waitcnt lgkmcnt(8)
	s_barrier
	s_waitcnt lgkmcnt(0)
	s_setprio 1
	s_waitcnt lgkmcnt(0)
	v_mfma_f32_16x16x32_bf16 v[126:129], v[142:145], v[190:193], 0
	v_mfma_f32_16x16x32_bf16 v[126:129], v[162:165], v[194:197], v[126:129]
	v_mfma_f32_16x16x32_bf16 v[122:125], v[182:185], v[190:193], 0
	v_mfma_f32_16x16x32_bf16 v[122:125], v[186:189], v[194:197], v[122:125]
	v_mfma_f32_16x16x32_bf16 v[110:113], v[142:145], v[198:201], 0
	v_mfma_f32_16x16x32_bf16 v[110:113], v[162:165], v[202:205], v[110:113]
	v_mfma_f32_16x16x32_bf16 v[106:109], v[182:185], v[198:201], 0
	v_mfma_f32_16x16x32_bf16 v[106:109], v[186:189], v[202:205], v[106:109]
	v_mfma_f32_16x16x32_bf16 v[94:97], v[142:145], v[206:209], 0
	v_mfma_f32_16x16x32_bf16 v[94:97], v[162:165], v[210:213], v[94:97]
	v_mfma_f32_16x16x32_bf16 v[90:93], v[182:185], v[206:209], 0
	v_mfma_f32_16x16x32_bf16 v[90:93], v[186:189], v[210:213], v[90:93]
	v_mfma_f32_16x16x32_bf16 v[78:81], v[142:145], v[214:217], 0
	v_mfma_f32_16x16x32_bf16 v[78:81], v[162:165], v[218:221], v[78:81]
	v_mfma_f32_16x16x32_bf16 v[74:77], v[182:185], v[214:217], 0
	s_barrier
	v_mfma_f32_16x16x32_bf16 v[74:77], v[186:189], v[218:221], v[74:77]
	s_setprio 0
	s_add_i32 s51, 0, 0x14000
	s_add_i32 s24, vcc_hi, s86
	s_mov_b32 m0, s24
	ds_read_b128 v[222:225], v249 offset:16384
	ds_read_b128 v[226:229], v249 offset:17408
	ds_read_b128 v[230:233], v249 offset:18432
	ds_read_b128 v[234:237], v249 offset:19456
	global_load_lds_dwordx4 v134, s[48:49]
	s_add_i32 m0, s24, 0x2000
	s_nop 0
	global_load_lds_dwordx4 v130, s[48:49]
	s_barrier
	s_waitcnt lgkmcnt(0)
	s_setprio 1
	s_waitcnt lgkmcnt(0)
	v_mfma_f32_16x16x32_bf16 v[118:121], v[222:225], v[190:193], 0
	v_mfma_f32_16x16x32_bf16 v[118:121], v[226:229], v[194:197], v[118:121]
	v_mfma_f32_16x16x32_bf16 v[114:117], v[230:233], v[190:193], 0
	v_mfma_f32_16x16x32_bf16 v[114:117], v[234:237], v[194:197], v[114:117]
	v_mfma_f32_16x16x32_bf16 v[102:105], v[222:225], v[198:201], 0
	v_mfma_f32_16x16x32_bf16 v[102:105], v[226:229], v[202:205], v[102:105]
	v_mfma_f32_16x16x32_bf16 v[98:101], v[230:233], v[198:201], 0
	v_mfma_f32_16x16x32_bf16 v[98:101], v[234:237], v[202:205], v[98:101]
	v_mfma_f32_16x16x32_bf16 v[86:89], v[222:225], v[206:209], 0
	v_mfma_f32_16x16x32_bf16 v[86:89], v[226:229], v[210:213], v[86:89]
	v_mfma_f32_16x16x32_bf16 v[82:85], v[230:233], v[206:209], 0
	v_mfma_f32_16x16x32_bf16 v[82:85], v[234:237], v[210:213], v[82:85]
	v_mfma_f32_16x16x32_bf16 v[70:73], v[222:225], v[214:217], 0
	v_mfma_f32_16x16x32_bf16 v[70:73], v[226:229], v[218:221], v[70:73]
	v_mfma_f32_16x16x32_bf16 v[66:69], v[230:233], v[214:217], 0
	s_barrier
	v_mfma_f32_16x16x32_bf16 v[66:69], v[234:237], v[218:221], v[66:69]
	s_setprio 0
	s_mov_b32 m0, s93
	s_mov_b64 s[100:101], s[60:61]
	ds_read_b128 v[190:193], v169 offset:16384
	ds_read_b128 v[194:197], v169 offset:17408
	ds_read_b128 v[198:201], v169 offset:18432
	ds_read_b128 v[202:205], v169 offset:19456
	ds_read_b128 v[206:209], v169 offset:20480
	ds_read_b128 v[210:213], v169 offset:21504
	ds_read_b128 v[214:217], v169 offset:22528
	ds_read_b128 v[218:221], v169 offset:23552
	global_load_lds_dwordx4 v136, s[60:61]
	s_mov_b64 s[100:101], s[60:61]
	s_mov_b32 m0, s98
	s_nop 0
	global_load_lds_dwordx4 v132, s[60:61]
	s_waitcnt vmcnt(8)
	s_barrier
	s_waitcnt lgkmcnt(0)
	s_setprio 1
	s_waitcnt lgkmcnt(0)
	v_mfma_f32_16x16x32_bf16 v[62:65], v[142:145], v[190:193], 0
	v_mfma_f32_16x16x32_bf16 v[62:65], v[162:165], v[194:197], v[62:65]
	v_mfma_f32_16x16x32_bf16 v[58:61], v[182:185], v[190:193], 0
	v_mfma_f32_16x16x32_bf16 v[58:61], v[186:189], v[194:197], v[58:61]
	v_mfma_f32_16x16x32_bf16 v[46:49], v[142:145], v[198:201], 0
	v_mfma_f32_16x16x32_bf16 v[46:49], v[162:165], v[202:205], v[46:49]
	v_mfma_f32_16x16x32_bf16 v[42:45], v[182:185], v[198:201], 0
	v_mfma_f32_16x16x32_bf16 v[42:45], v[186:189], v[202:205], v[42:45]
	v_mfma_f32_16x16x32_bf16 v[30:33], v[142:145], v[206:209], 0
	v_mfma_f32_16x16x32_bf16 v[30:33], v[162:165], v[210:213], v[30:33]
	v_mfma_f32_16x16x32_bf16 v[26:29], v[182:185], v[206:209], 0
	v_mfma_f32_16x16x32_bf16 v[26:29], v[186:189], v[210:213], v[26:29]
	v_mfma_f32_16x16x32_bf16 v[14:17], v[142:145], v[214:217], 0
	v_mfma_f32_16x16x32_bf16 v[14:17], v[162:165], v[218:221], v[14:17]
	v_mfma_f32_16x16x32_bf16 v[10:13], v[182:185], v[214:217], 0
	s_barrier
; #define PG8_STAGE(bufoff, gbase, voff) do { _Pragma("unroll") for (int _i = 0; _i < 2; ++_i) \
;         __builtin_amdgcn_global_load_lds((const unsigned*)((const char*)(gbase) + (voff)[_i]), (LAS unsigned*)(lds + (bufoff) + ldsw + _i * 8192), 16, 0, 0); } while (0)
; #define PG8_LDA(dst, b, h) do { _Pragma("unroll") for (int m = 0; m < 4; ++m) _Pragma("unroll") for (int k = 0; k < 2; ++k) dst[m][k] = *(const LAS bf16x8*)(lds + PG8_SA(b, h) + aoff + m * 2048 + k * 1024); } while (0)
; #define PG8_LDB(dst, b, h) do { _Pragma("unroll") for (int n = 0; n < 2; ++n) _Pragma("unroll") for (int k = 0; k < 2; ++k) dst[n][k] = *(const LAS bf16x8*)(lds + PG8_SB(b, h) + boff + n * 2048 + k * 1024); } while (0)
; #define PG8_MMA(ai, bj, At, Bt) do { __builtin_amdgcn_s_setprio(1); _Pragma("unroll") for (int m = 0; m < 4; ++m) _Pragma("unroll") for (int n = 0; n < 2; ++n) _Pragma("unroll") for (int k = 0; k < 2; ++k) \
;         acc[ai][bj][m][n] = __builtin_amdgcn_mfma_f32_16x16x32_bf16(Bt[n][k], At[m][k], acc[ai][bj][m][n], 0, 0, 0); __builtin_amdgcn_s_setprio(0); } while (0)
; #define PG8_WAIT_V(n) asm volatile("s_waitcnt vmcnt(" #n ")" ::: "memory")
; #define PG8_WAIT_L(n) asm volatile("s_waitcnt lgkmcnt(" #n ")" ::: "memory")
; #define PG8_BAR __builtin_amdgcn_s_barrier()
; #define PG8_SCHED __builtin_amdgcn_sched_barrier(0)
; template <class Epi, class Sched>
; __device__ __forceinline__ void gemm_phase(LAS unsigned char* lds, const Gemm g, const Sched& S, const Epi& E) {
;     ...
;             PG8_WAIT_V(6); PG8_BAR; PG8_MMA(1, 1, At, B1); PG8_BAR;
;             PG8_LDB(B0, 1, 0); PG8_SCHED; PG8_LDA(At, 1, 0); PG8_STAGE(PG8_SA(0, 1), a2 + hstep, voffA);
;             PG8_WAIT_L(8); PG8_BAR; PG8_WAIT_L(0); PG8_MMA(0, 0, At, B0); PG8_BAR; PG8_SCHED;
;             PG8_LDB(B1, 1, 1); PG8_STAGE(PG8_SB(1, 0), b3, voffB);
;             PG8_BAR; PG8_WAIT_L(0); PG8_MMA(0, 1, At, B1); PG8_BAR;
;             PG8_LDA(At, 1, 1); PG8_STAGE(PG8_SA(1, 0), a3, voffA);
;             PG8_BAR; PG8_WAIT_L(0); PG8_MMA(1, 0, At, B0); PG8_BAR; PG8_SCHED;
	v_mfma_f32_16x16x32_bf16 v[10:13], v[186:189], v[218:221], v[10:13]
	s_setprio 0
	s_add_u32 s24, s48, 0x40000
	s_addc_u32 s25, s49, 0
	s_add_i32 s51, s51, s86
	s_mov_b32 m0, s51
	s_nop 0
	global_load_lds_dwordx4 v134, s[24:25]
	s_add_i32 m0, s51, 0x2000
	s_nop 0
	global_load_lds_dwordx4 v130, s[24:25]
	s_waitcnt vmcnt(6)
	s_barrier
	s_setprio 1
	v_mfma_f32_16x16x32_bf16 v[54:57], v[222:225], v[190:193], 0
	ds_read_b128 v[142:145], v249 offset:32768
	ds_read_b128 v[162:165], v249 offset:33792
	v_mfma_f32_16x16x32_bf16 v[54:57], v[226:229], v[194:197], v[54:57]
	ds_read_b128 v[182:185], v249 offset:34816
	ds_read_b128 v[186:189], v249 offset:35840
	v_mfma_f32_16x16x32_bf16 v[50:53], v[230:233], v[190:193], 0
	ds_read_b128 v[190:193], v169 offset:32768
	v_mfma_f32_16x16x32_bf16 v[50:53], v[234:237], v[194:197], v[50:53]
	ds_read_b128 v[194:197], v169 offset:33792
	v_mfma_f32_16x16x32_bf16 v[38:41], v[222:225], v[198:201], 0
	v_mfma_f32_16x16x32_bf16 v[38:41], v[226:229], v[202:205], v[38:41]
	v_mfma_f32_16x16x32_bf16 v[34:37], v[230:233], v[198:201], 0
	ds_read_b128 v[198:201], v169 offset:34816
	v_mfma_f32_16x16x32_bf16 v[34:37], v[234:237], v[202:205], v[34:37]
	ds_read_b128 v[202:205], v169 offset:35840
	v_mfma_f32_16x16x32_bf16 v[22:25], v[222:225], v[206:209], 0
	v_mfma_f32_16x16x32_bf16 v[22:25], v[226:229], v[210:213], v[22:25]
	v_mfma_f32_16x16x32_bf16 v[18:21], v[230:233], v[206:209], 0
	ds_read_b128 v[206:209], v169 offset:36864
	v_mfma_f32_16x16x32_bf16 v[18:21], v[234:237], v[210:213], v[18:21]
	ds_read_b128 v[210:213], v169 offset:37888
	v_mfma_f32_16x16x32_bf16 v[6:9], v[222:225], v[214:217], 0
	v_mfma_f32_16x16x32_bf16 v[6:9], v[226:229], v[218:221], v[6:9]
	v_mfma_f32_16x16x32_bf16 v[2:5], v[230:233], v[214:217], 0
	ds_read_b128 v[214:217], v169 offset:38912
	s_barrier
	v_mfma_f32_16x16x32_bf16 v[2:5], v[234:237], v[218:221], v[2:5]
	s_setprio 0
	s_add_i32 s51, 0, 0x18000
	s_add_u32 s24, s60, 0x40000
	s_addc_u32 s25, s61, 0
	s_mov_b32 m0, s99
	ds_read_b128 v[218:221], v169 offset:39936
	global_load_lds_dwordx4 v136, s[24:25]
	s_mov_b32 m0, s94
	s_nop 0
	global_load_lds_dwordx4 v132, s[24:25]
	s_waitcnt lgkmcnt(8)
	s_barrier
	s_waitcnt lgkmcnt(0)
	s_setprio 1
	s_waitcnt lgkmcnt(0)
	v_mfma_f32_16x16x32_bf16 v[126:129], v[142:145], v[190:193], v[126:129]
	v_mfma_f32_16x16x32_bf16 v[126:129], v[162:165], v[194:197], v[126:129]
	v_mfma_f32_16x16x32_bf16 v[122:125], v[182:185], v[190:193], v[122:125]
	v_mfma_f32_16x16x32_bf16 v[122:125], v[186:189], v[194:197], v[122:125]
	v_mfma_f32_16x16x32_bf16 v[110:113], v[142:145], v[198:201], v[110:113]
	v_mfma_f32_16x16x32_bf16 v[110:113], v[162:165], v[202:205], v[110:113]
	v_mfma_f32_16x16x32_bf16 v[106:109], v[182:185], v[198:201], v[106:109]
	v_mfma_f32_16x16x32_bf16 v[106:109], v[186:189], v[202:205], v[106:109]
	v_mfma_f32_16x16x32_bf16 v[94:97], v[142:145], v[206:209], v[94:97]
	v_mfma_f32_16x16x32_bf16 v[94:97], v[162:165], v[210:213], v[94:97]
	v_mfma_f32_16x16x32_bf16 v[90:93], v[182:185], v[206:209], v[90:93]
	v_mfma_f32_16x16x32_bf16 v[90:93], v[186:189], v[210:213], v[90:93]
	v_mfma_f32_16x16x32_bf16 v[78:81], v[142:145], v[214:217], v[78:81]
	v_mfma_f32_16x16x32_bf16 v[78:81], v[162:165], v[218:221], v[78:81]
	v_mfma_f32_16x16x32_bf16 v[74:77], v[182:185], v[214:217], v[74:77]
	s_barrier
	v_mfma_f32_16x16x32_bf16 v[74:77], v[186:189], v[218:221], v[74:77]
	s_setprio 0
	s_add_i32 s60, 0, 0x1c000
	s_add_i32 s24, s51, s86
	s_add_i32 m0, s24, 0xffffff80
	ds_read_b128 v[222:225], v249 offset:49152
	ds_read_b128 v[226:229], v249 offset:50176
	ds_read_b128 v[230:233], v249 offset:51200
	ds_read_b128 v[234:237], v249 offset:52224
	global_load_lds_dwordx4 v134, s[48:49] offset:128
	s_add_i32 m0, s24, 0x1f80
	s_nop 0
	global_load_lds_dwordx4 v130, s[48:49] offset:128
	s_barrier
	s_waitcnt lgkmcnt(0)
	s_setprio 1
	s_waitcnt lgkmcnt(0)
	v_mfma_f32_16x16x32_bf16 v[118:121], v[222:225], v[190:193], v[118:121]
	v_mfma_f32_16x16x32_bf16 v[118:121], v[226:229], v[194:197], v[118:121]
	v_mfma_f32_16x16x32_bf16 v[114:117], v[230:233], v[190:193], v[114:117]
	v_mfma_f32_16x16x32_bf16 v[114:117], v[234:237], v[194:197], v[114:117]
	v_mfma_f32_16x16x32_bf16 v[102:105], v[222:225], v[198:201], v[102:105]
	v_mfma_f32_16x16x32_bf16 v[102:105], v[226:229], v[202:205], v[102:105]
	v_mfma_f32_16x16x32_bf16 v[98:101], v[230:233], v[198:201], v[98:101]
	v_mfma_f32_16x16x32_bf16 v[98:101], v[234:237], v[202:205], v[98:101]
	v_mfma_f32_16x16x32_bf16 v[86:89], v[222:225], v[206:209], v[86:89]
	v_mfma_f32_16x16x32_bf16 v[86:89], v[226:229], v[210:213], v[86:89]
	v_mfma_f32_16x16x32_bf16 v[82:85], v[230:233], v[206:209], v[82:85]
	v_mfma_f32_16x16x32_bf16 v[82:85], v[234:237], v[210:213], v[82:85]
	v_mfma_f32_16x16x32_bf16 v[70:73], v[222:225], v[214:217], v[70:73]
	v_mfma_f32_16x16x32_bf16 v[70:73], v[226:229], v[218:221], v[70:73]
	v_mfma_f32_16x16x32_bf16 v[66:69], v[230:233], v[214:217], v[66:69]
	s_barrier
	v_mfma_f32_16x16x32_bf16 v[66:69], v[234:237], v[218:221], v[66:69]
	s_setprio 0
	s_add_i32 m0, s95, 0xffffff80
	ds_read_b128 v[190:193], v169 offset:49152
	ds_read_b128 v[194:197], v169 offset:50176
	ds_read_b128 v[198:201], v169 offset:51200
	ds_read_b128 v[202:205], v169 offset:52224
	ds_read_b128 v[206:209], v169 offset:53248
	ds_read_b128 v[210:213], v169 offset:54272
	ds_read_b128 v[214:217], v169 offset:55296
	ds_read_b128 v[218:221], v169 offset:56320
	global_load_lds_dwordx4 v136, s[100:101] offset:128
	s_add_i32 m0, s96, 0xffffff80
	s_nop 0
	global_load_lds_dwordx4 v132, s[100:101] offset:128
	s_waitcnt vmcnt(8)
	s_barrier
; #define PG8_STAGE(bufoff, gbase, voff) do { _Pragma("unroll") for (int _i = 0; _i < 2; ++_i) \
;         __builtin_amdgcn_global_load_lds((const unsigned*)((const char*)(gbase) + (voff)[_i]), (LAS unsigned*)(lds + (bufoff) + ldsw + _i * 8192), 16, 0, 0); } while (0)
; #define PG8_LDA(dst, b, h) do { _Pragma("unroll") for (int m = 0; m < 4; ++m) _Pragma("unroll") for (int k = 0; k < 2; ++k) dst[m][k] = *(const LAS bf16x8*)(lds + PG8_SA(b, h) + aoff + m * 2048 + k * 1024); } while (0)
; #define PG8_LDB(dst, b, h) do { _Pragma("unroll") for (int n = 0; n < 2; ++n) _Pragma("unroll") for (int k = 0; k < 2; ++k) dst[n][k] = *(const LAS bf16x8*)(lds + PG8_SB(b, h) + boff + n * 2048 + k * 1024); } while (0)
; #define PG8_MMA(ai, bj, At, Bt) do { __builtin_amdgcn_s_setprio(1); _Pragma("unroll") for (int m = 0; m < 4; ++m) _Pragma("unroll") for (int n = 0; n < 2; ++n) _Pragma("unroll") for (int k = 0; k < 2; ++k) \
;         acc[ai][bj][m][n] = __builtin_amdgcn_mfma_f32_16x16x32_bf16(Bt[n][k], At[m][k], acc[ai][bj][m][n], 0, 0, 0); __builtin_amdgcn_s_setprio(0); } while (0)
; #define PG8_WAIT_V(n) asm volatile("s_waitcnt vmcnt(" #n ")" ::: "memory")
; #define PG8_WAIT_L(n) asm volatile("s_waitcnt lgkmcnt(" #n ")" ::: "memory")
; #define PG8_BAR __builtin_amdgcn_s_barrier()
; #define PG8_SCHED __builtin_amdgcn_sched_barrier(0)
; template <class Epi, class Sched>
; __device__ __forceinline__ void gemm_phase(LAS unsigned char* lds, const Gemm g, const Sched& S, const Epi& E) {
;     ...
;             const bool last = (t == nt - 2);
;             const char* a1 = cA + (size_t)(t + 1) * kstep;
;             const char* a2 = last ? nA : cA + (size_t)(t + 2) * kstep; const char* b2 = last ? nB : cB + (size_t)(t + 2) * kstep;
;             const char* a3 = a2 + kstep; const char* b3 = b2 + kstep;
;             PG8_LDB(B0, 0, 0); PG8_SCHED; PG8_LDA(At, 0, 0); PG8_STAGE(PG8_SA(1, 1), a1 + hstep, voffA);
;             PG8_WAIT_L(8); PG8_BAR; PG8_WAIT_L(0); PG8_MMA(0, 0, At, B0); PG8_BAR; PG8_SCHED;
;             PG8_LDB(B1, 0, 1); PG8_STAGE(PG8_SB(0, 0), b2, voffB);
;     ...
;             PG8_BAR; PG8_WAIT_L(0); PG8_MMA(1, 0, At, B0); PG8_BAR; PG8_SCHED;
;             PG8_STAGE(PG8_SB(1, 1), b3 + hstep, voffB);
;             PG8_WAIT_V(6); PG8_BAR; PG8_MMA(1, 1, At, B1); PG8_BAR;
	s_waitcnt lgkmcnt(0)
	s_setprio 1
	s_waitcnt lgkmcnt(0)
	v_mfma_f32_16x16x32_bf16 v[62:65], v[142:145], v[190:193], v[62:65]
	v_mfma_f32_16x16x32_bf16 v[62:65], v[162:165], v[194:197], v[62:65]
	v_mfma_f32_16x16x32_bf16 v[58:61], v[182:185], v[190:193], v[58:61]
	v_mfma_f32_16x16x32_bf16 v[58:61], v[186:189], v[194:197], v[58:61]
	v_mfma_f32_16x16x32_bf16 v[46:49], v[142:145], v[198:201], v[46:49]
	v_mfma_f32_16x16x32_bf16 v[46:49], v[162:165], v[202:205], v[46:49]
	v_mfma_f32_16x16x32_bf16 v[42:45], v[182:185], v[198:201], v[42:45]
	v_mfma_f32_16x16x32_bf16 v[42:45], v[186:189], v[202:205], v[42:45]
	v_mfma_f32_16x16x32_bf16 v[30:33], v[142:145], v[206:209], v[30:33]
	v_mfma_f32_16x16x32_bf16 v[30:33], v[162:165], v[210:213], v[30:33]
	v_mfma_f32_16x16x32_bf16 v[26:29], v[182:185], v[206:209], v[26:29]
	v_mfma_f32_16x16x32_bf16 v[26:29], v[186:189], v[210:213], v[26:29]
	v_mfma_f32_16x16x32_bf16 v[14:17], v[142:145], v[214:217], v[14:17]
	v_mfma_f32_16x16x32_bf16 v[14:17], v[162:165], v[218:221], v[14:17]
	v_mfma_f32_16x16x32_bf16 v[10:13], v[182:185], v[214:217], v[10:13]
	s_barrier
	v_mfma_f32_16x16x32_bf16 v[10:13], v[186:189], v[218:221], v[10:13]
	s_setprio 0
	s_add_u32 s24, s48, 0x40080
	s_addc_u32 s25, s49, 0
	s_add_i32 s48, s60, s86
	s_mov_b32 m0, s48
	s_nop 0
	global_load_lds_dwordx4 v134, s[24:25]
	s_add_i32 m0, s48, 0x2000
	s_nop 0
	global_load_lds_dwordx4 v130, s[24:25]
	s_waitcnt vmcnt(6)
	s_barrier
	s_setprio 1
	v_mfma_f32_16x16x32_bf16 v[54:57], v[222:225], v[190:193], v[54:57]
	ds_read_b128 v[142:145], v249
	ds_read_b128 v[162:165], v249 offset:1024
	v_mfma_f32_16x16x32_bf16 v[54:57], v[226:229], v[194:197], v[54:57]
	ds_read_b128 v[182:185], v249 offset:2048
	ds_read_b128 v[186:189], v249 offset:3072
	v_mfma_f32_16x16x32_bf16 v[50:53], v[230:233], v[190:193], v[50:53]
	ds_read_b128 v[190:193], v169
	v_mfma_f32_16x16x32_bf16 v[50:53], v[234:237], v[194:197], v[50:53]
	ds_read_b128 v[194:197], v169 offset:1024
	v_mfma_f32_16x16x32_bf16 v[38:41], v[222:225], v[198:201], v[38:41]
	v_mfma_f32_16x16x32_bf16 v[38:41], v[226:229], v[202:205], v[38:41]
	v_mfma_f32_16x16x32_bf16 v[34:37], v[230:233], v[198:201], v[34:37]
	ds_read_b128 v[198:201], v169 offset:2048
	v_mfma_f32_16x16x32_bf16 v[34:37], v[234:237], v[202:205], v[34:37]
	ds_read_b128 v[202:205], v169 offset:3072
	v_mfma_f32_16x16x32_bf16 v[22:25], v[222:225], v[206:209], v[22:25]
	v_mfma_f32_16x16x32_bf16 v[22:25], v[226:229], v[210:213], v[22:25]
	v_mfma_f32_16x16x32_bf16 v[18:21], v[230:233], v[206:209], v[18:21]
	ds_read_b128 v[206:209], v169 offset:4096
	v_mfma_f32_16x16x32_bf16 v[18:21], v[234:237], v[210:213], v[18:21]
	ds_read_b128 v[210:213], v169 offset:5120
	v_mfma_f32_16x16x32_bf16 v[6:9], v[222:225], v[214:217], v[6:9]
	v_mfma_f32_16x16x32_bf16 v[6:9], v[226:229], v[218:221], v[6:9]
	v_mfma_f32_16x16x32_bf16 v[2:5], v[230:233], v[214:217], v[2:5]
	ds_read_b128 v[214:217], v169 offset:6144
	s_barrier
	v_mfma_f32_16x16x32_bf16 v[2:5], v[234:237], v[218:221], v[2:5]
	s_setprio 0
	s_add_i32 s50, s50, 2
	s_add_u32 vcc_lo, vcc_lo, 0x100
	s_addc_u32 s35, s35, 0
	s_add_u32 s38, s38, 0x100
	s_addc_u32 s39, s39, 0
	s_cmp_gt_u32 s50, 13
.LBB0_165:
	s_add_u32 s24, s38, 0xfffc0080
	s_addc_u32 s25, s39, -1
	s_add_i32 vcc_hi, 0, 0x10000
	s_cmp_eq_u32 s50, 12
	s_cselect_b32 s61, s34, s25
	s_cselect_b32 s60, s45, s24
	s_cselect_b32 s49, s43, s35
	s_cselect_b32 s48, s79, vcc_lo
	s_add_i32 m0, s93, 0xc000
	ds_read_b128 v[218:221], v169 offset:7168
	global_load_lds_dwordx4 v140, s[38:39]
	s_add_i32 m0, s93, 0xe000
	s_nop 0
	global_load_lds_dwordx4 v138, s[38:39]
	s_waitcnt lgkmcnt(8)
	s_barrier
	s_waitcnt lgkmcnt(0)
	s_setprio 1
	s_waitcnt lgkmcnt(0)
	v_mfma_f32_16x16x32_bf16 v[126:129], v[142:145], v[190:193], v[126:129]
	v_mfma_f32_16x16x32_bf16 v[126:129], v[162:165], v[194:197], v[126:129]
	v_mfma_f32_16x16x32_bf16 v[122:125], v[182:185], v[190:193], v[122:125]
	v_mfma_f32_16x16x32_bf16 v[122:125], v[186:189], v[194:197], v[122:125]
	v_mfma_f32_16x16x32_bf16 v[110:113], v[142:145], v[198:201], v[110:113]
	v_mfma_f32_16x16x32_bf16 v[110:113], v[162:165], v[202:205], v[110:113]
	v_mfma_f32_16x16x32_bf16 v[106:109], v[182:185], v[198:201], v[106:109]
	v_mfma_f32_16x16x32_bf16 v[106:109], v[186:189], v[202:205], v[106:109]
	v_mfma_f32_16x16x32_bf16 v[94:97], v[142:145], v[206:209], v[94:97]
	v_mfma_f32_16x16x32_bf16 v[94:97], v[162:165], v[210:213], v[94:97]
	v_mfma_f32_16x16x32_bf16 v[90:93], v[182:185], v[206:209], v[90:93]
	v_mfma_f32_16x16x32_bf16 v[90:93], v[186:189], v[210:213], v[90:93]
	v_mfma_f32_16x16x32_bf16 v[78:81], v[142:145], v[214:217], v[78:81]
	v_mfma_f32_16x16x32_bf16 v[78:81], v[162:165], v[218:221], v[78:81]
	v_mfma_f32_16x16x32_bf16 v[74:77], v[182:185], v[214:217], v[74:77]
	s_barrier
	v_mfma_f32_16x16x32_bf16 v[74:77], v[186:189], v[218:221], v[74:77]
	s_setprio 0
	s_add_i32 s51, 0, 0x14000
	s_add_i32 s24, vcc_hi, s86
	s_mov_b32 m0, s24
	ds_read_b128 v[222:225], v249 offset:16384
	ds_read_b128 v[226:229], v249 offset:17408
	ds_read_b128 v[230:233], v249 offset:18432
	ds_read_b128 v[234:237], v249 offset:19456
	global_load_lds_dwordx4 v134, s[48:49]
	s_add_i32 m0, s24, 0x2000
	s_nop 0
	global_load_lds_dwordx4 v130, s[48:49]
	s_barrier
; #define PG8_STAGE(bufoff, gbase, voff) do { _Pragma("unroll") for (int _i = 0; _i < 2; ++_i) \
;         __builtin_amdgcn_global_load_lds((const unsigned*)((const char*)(gbase) + (voff)[_i]), (LAS unsigned*)(lds + (bufoff) + ldsw + _i * 8192), 16, 0, 0); } while (0)
; #define PG8_LDA(dst, b, h) do { _Pragma("unroll") for (int m = 0; m < 4; ++m) _Pragma("unroll") for (int k = 0; k < 2; ++k) dst[m][k] = *(const LAS bf16x8*)(lds + PG8_SA(b, h) + aoff + m * 2048 + k * 1024); } while (0)
; #define PG8_LDB(dst, b, h) do { _Pragma("unroll") for (int n = 0; n < 2; ++n) _Pragma("unroll") for (int k = 0; k < 2; ++k) dst[n][k] = *(const LAS bf16x8*)(lds + PG8_SB(b, h) + boff + n * 2048 + k * 1024); } while (0)
; #define PG8_MMA(ai, bj, At, Bt) do { __builtin_amdgcn_s_setprio(1); _Pragma("unroll") for (int m = 0; m < 4; ++m) _Pragma("unroll") for (int n = 0; n < 2; ++n) _Pragma("unroll") for (int k = 0; k < 2; ++k) \
;         acc[ai][bj][m][n] = __builtin_amdgcn_mfma_f32_16x16x32_bf16(Bt[n][k], At[m][k], acc[ai][bj][m][n], 0, 0, 0); __builtin_amdgcn_s_setprio(0); } while (0)
; #define PG8_WAIT_V(n) asm volatile("s_waitcnt vmcnt(" #n ")" ::: "memory")
; #define PG8_WAIT_L(n) asm volatile("s_waitcnt lgkmcnt(" #n ")" ::: "memory")
; #define PG8_BAR __builtin_amdgcn_s_barrier()
; #define PG8_SCHED __builtin_amdgcn_sched_barrier(0)
; template <class Epi, class Sched>
; __device__ __forceinline__ void gemm_phase(LAS unsigned char* lds, const Gemm g, const Sched& S, const Epi& E) {
;     ...
;             PG8_BAR; PG8_WAIT_L(0); PG8_MMA(0, 1, At, B1); PG8_BAR;
;             PG8_LDA(At, 0, 1); PG8_STAGE(PG8_SA(0, 0), a2, voffA);
;             PG8_BAR; PG8_WAIT_L(0); PG8_MMA(1, 0, At, B0); PG8_BAR; PG8_SCHED;
;             PG8_STAGE(PG8_SB(0, 1), b2 + hstep, voffB);
;             PG8_WAIT_V(6); PG8_BAR; PG8_MMA(1, 1, At, B1); PG8_BAR;
;             PG8_LDB(B0, 1, 0); PG8_SCHED; PG8_LDA(At, 1, 0); PG8_STAGE(PG8_SA(0, 1), a2 + hstep, voffA);
;             PG8_WAIT_L(8); PG8_BAR; PG8_WAIT_L(0); PG8_MMA(0, 0, At, B0); PG8_BAR; PG8_SCHED;
	s_waitcnt lgkmcnt(0)
	s_setprio 1
	s_waitcnt lgkmcnt(0)
	v_mfma_f32_16x16x32_bf16 v[118:121], v[222:225], v[190:193], v[118:121]
	v_mfma_f32_16x16x32_bf16 v[118:121], v[226:229], v[194:197], v[118:121]
	v_mfma_f32_16x16x32_bf16 v[114:117], v[230:233], v[190:193], v[114:117]
	v_mfma_f32_16x16x32_bf16 v[114:117], v[234:237], v[194:197], v[114:117]
	v_mfma_f32_16x16x32_bf16 v[102:105], v[222:225], v[198:201], v[102:105]
	v_mfma_f32_16x16x32_bf16 v[102:105], v[226:229], v[202:205], v[102:105]
	v_mfma_f32_16x16x32_bf16 v[98:101], v[230:233], v[198:201], v[98:101]
	v_mfma_f32_16x16x32_bf16 v[98:101], v[234:237], v[202:205], v[98:101]
	v_mfma_f32_16x16x32_bf16 v[86:89], v[222:225], v[206:209], v[86:89]
	v_mfma_f32_16x16x32_bf16 v[86:89], v[226:229], v[210:213], v[86:89]
	v_mfma_f32_16x16x32_bf16 v[82:85], v[230:233], v[206:209], v[82:85]
	v_mfma_f32_16x16x32_bf16 v[82:85], v[234:237], v[210:213], v[82:85]
	v_mfma_f32_16x16x32_bf16 v[70:73], v[222:225], v[214:217], v[70:73]
	v_mfma_f32_16x16x32_bf16 v[70:73], v[226:229], v[218:221], v[70:73]
	v_mfma_f32_16x16x32_bf16 v[66:69], v[230:233], v[214:217], v[66:69]
	s_barrier
	v_mfma_f32_16x16x32_bf16 v[66:69], v[234:237], v[218:221], v[66:69]
	s_setprio 0
	s_mov_b32 m0, s93
	s_mov_b64 s[100:101], s[60:61]
	ds_read_b128 v[190:193], v169 offset:16384
	ds_read_b128 v[194:197], v169 offset:17408
	ds_read_b128 v[198:201], v169 offset:18432
	ds_read_b128 v[202:205], v169 offset:19456
	ds_read_b128 v[206:209], v169 offset:20480
	ds_read_b128 v[210:213], v169 offset:21504
	ds_read_b128 v[214:217], v169 offset:22528
	ds_read_b128 v[218:221], v169 offset:23552
	global_load_lds_dwordx4 v136, s[60:61]
	s_mov_b64 s[100:101], s[60:61]
	s_mov_b32 m0, s98
	s_nop 0
	global_load_lds_dwordx4 v132, s[60:61]
	s_waitcnt vmcnt(8)
	s_barrier
	s_waitcnt lgkmcnt(0)
	s_setprio 1
	s_waitcnt lgkmcnt(0)
	v_mfma_f32_16x16x32_bf16 v[62:65], v[142:145], v[190:193], v[62:65]
	v_mfma_f32_16x16x32_bf16 v[62:65], v[162:165], v[194:197], v[62:65]
	v_mfma_f32_16x16x32_bf16 v[58:61], v[182:185], v[190:193], v[58:61]
	v_mfma_f32_16x16x32_bf16 v[58:61], v[186:189], v[194:197], v[58:61]
	v_mfma_f32_16x16x32_bf16 v[46:49], v[142:145], v[198:201], v[46:49]
	v_mfma_f32_16x16x32_bf16 v[46:49], v[162:165], v[202:205], v[46:49]
	v_mfma_f32_16x16x32_bf16 v[42:45], v[182:185], v[198:201], v[42:45]
	v_mfma_f32_16x16x32_bf16 v[42:45], v[186:189], v[202:205], v[42:45]
	v_mfma_f32_16x16x32_bf16 v[30:33], v[142:145], v[206:209], v[30:33]
	v_mfma_f32_16x16x32_bf16 v[30:33], v[162:165], v[210:213], v[30:33]
	v_mfma_f32_16x16x32_bf16 v[26:29], v[182:185], v[206:209], v[26:29]
	v_mfma_f32_16x16x32_bf16 v[26:29], v[186:189], v[210:213], v[26:29]
	v_mfma_f32_16x16x32_bf16 v[14:17], v[142:145], v[214:217], v[14:17]
	v_mfma_f32_16x16x32_bf16 v[14:17], v[162:165], v[218:221], v[14:17]
	v_mfma_f32_16x16x32_bf16 v[10:13], v[182:185], v[214:217], v[10:13]
	s_barrier
	v_mfma_f32_16x16x32_bf16 v[10:13], v[186:189], v[218:221], v[10:13]
	s_setprio 0
	s_add_u32 s24, s48, 0x40000
	s_addc_u32 s25, s49, 0
	s_add_i32 s51, s51, s86
	s_mov_b32 m0, s51
	s_nop 0
	global_load_lds_dwordx4 v134, s[24:25]
	s_add_i32 m0, s51, 0x2000
	s_nop 0
	global_load_lds_dwordx4 v130, s[24:25]
	s_waitcnt vmcnt(6)
	s_barrier
	s_setprio 1
	v_mfma_f32_16x16x32_bf16 v[54:57], v[222:225], v[190:193], v[54:57]
	ds_read_b128 v[142:145], v249 offset:32768
	ds_read_b128 v[162:165], v249 offset:33792
	v_mfma_f32_16x16x32_bf16 v[54:57], v[226:229], v[194:197], v[54:57]
	ds_read_b128 v[182:185], v249 offset:34816
	ds_read_b128 v[186:189], v249 offset:35840
	v_mfma_f32_16x16x32_bf16 v[50:53], v[230:233], v[190:193], v[50:53]
	ds_read_b128 v[190:193], v169 offset:32768
	v_mfma_f32_16x16x32_bf16 v[50:53], v[234:237], v[194:197], v[50:53]
	ds_read_b128 v[194:197], v169 offset:33792
	v_mfma_f32_16x16x32_bf16 v[38:41], v[222:225], v[198:201], v[38:41]
	v_mfma_f32_16x16x32_bf16 v[38:41], v[226:229], v[202:205], v[38:41]
	v_mfma_f32_16x16x32_bf16 v[34:37], v[230:233], v[198:201], v[34:37]
	ds_read_b128 v[198:201], v169 offset:34816
	v_mfma_f32_16x16x32_bf16 v[34:37], v[234:237], v[202:205], v[34:37]
	ds_read_b128 v[202:205], v169 offset:35840
	v_mfma_f32_16x16x32_bf16 v[22:25], v[222:225], v[206:209], v[22:25]
	v_mfma_f32_16x16x32_bf16 v[22:25], v[226:229], v[210:213], v[22:25]
	v_mfma_f32_16x16x32_bf16 v[18:21], v[230:233], v[206:209], v[18:21]
	ds_read_b128 v[206:209], v169 offset:36864
	v_mfma_f32_16x16x32_bf16 v[18:21], v[234:237], v[210:213], v[18:21]
	ds_read_b128 v[210:213], v169 offset:37888
	v_mfma_f32_16x16x32_bf16 v[6:9], v[222:225], v[214:217], v[6:9]
	v_mfma_f32_16x16x32_bf16 v[6:9], v[226:229], v[218:221], v[6:9]
	v_mfma_f32_16x16x32_bf16 v[2:5], v[230:233], v[214:217], v[2:5]
	ds_read_b128 v[214:217], v169 offset:38912
	s_barrier
	v_mfma_f32_16x16x32_bf16 v[2:5], v[234:237], v[218:221], v[2:5]
	s_setprio 0
	s_add_i32 s51, 0, 0x18000
	s_add_u32 s24, s60, 0x40000
	s_addc_u32 s25, s61, 0
	s_mov_b32 m0, s99
	ds_read_b128 v[218:221], v169 offset:39936
	global_load_lds_dwordx4 v136, s[24:25]
	s_mov_b32 m0, s94
	s_nop 0
	global_load_lds_dwordx4 v132, s[24:25]
	s_waitcnt lgkmcnt(8)
	s_barrier
; #define PG8_STAGE(bufoff, gbase, voff) do { _Pragma("unroll") for (int _i = 0; _i < 2; ++_i) \
;         __builtin_amdgcn_global_load_lds((const unsigned*)((const char*)(gbase) + (voff)[_i]), (LAS unsigned*)(lds + (bufoff) + ldsw + _i * 8192), 16, 0, 0); } while (0)
; #define PG8_LDA(dst, b, h) do { _Pragma("unroll") for (int m = 0; m < 4; ++m) _Pragma("unroll") for (int k = 0; k < 2; ++k) dst[m][k] = *(const LAS bf16x8*)(lds + PG8_SA(b, h) + aoff + m * 2048 + k * 1024); } while (0)
; #define PG8_LDB(dst, b, h) do { _Pragma("unroll") for (int n = 0; n < 2; ++n) _Pragma("unroll") for (int k = 0; k < 2; ++k) dst[n][k] = *(const LAS bf16x8*)(lds + PG8_SB(b, h) + boff + n * 2048 + k * 1024); } while (0)
; #define PG8_MMA(ai, bj, At, Bt) do { __builtin_amdgcn_s_setprio(1); _Pragma("unroll") for (int m = 0; m < 4; ++m) _Pragma("unroll") for (int n = 0; n < 2; ++n) _Pragma("unroll") for (int k = 0; k < 2; ++k) \
;         acc[ai][bj][m][n] = __builtin_amdgcn_mfma_f32_16x16x32_bf16(Bt[n][k], At[m][k], acc[ai][bj][m][n], 0, 0, 0); __builtin_amdgcn_s_setprio(0); } while (0)
; #define PG8_WAIT_V(n) asm volatile("s_waitcnt vmcnt(" #n ")" ::: "memory")
; #define PG8_WAIT_L(n) asm volatile("s_waitcnt lgkmcnt(" #n ")" ::: "memory")
; #define PG8_BAR __builtin_amdgcn_s_barrier()
; #define PG8_SCHED __builtin_amdgcn_sched_barrier(0)
; template <class Epi, class Sched>
; __device__ __forceinline__ void gemm_phase(LAS unsigned char* lds, const Gemm g, const Sched& S, const Epi& E) {
;     ...
;             PG8_WAIT_L(8); PG8_BAR; PG8_WAIT_L(0); PG8_MMA(0, 0, At, B0); PG8_BAR; PG8_SCHED;
;             PG8_LDB(B1, 1, 1); PG8_STAGE(PG8_SB(1, 0), b3, voffB);
;             PG8_BAR; PG8_WAIT_L(0); PG8_MMA(0, 1, At, B1); PG8_BAR;
;             PG8_LDA(At, 1, 1); PG8_STAGE(PG8_SA(1, 0), a3, voffA);
;             PG8_BAR; PG8_WAIT_L(0); PG8_MMA(1, 0, At, B0); PG8_BAR; PG8_SCHED;
;             PG8_STAGE(PG8_SB(1, 1), b3 + hstep, voffB);
;             PG8_WAIT_V(6); PG8_BAR; PG8_MMA(1, 1, At, B1); PG8_BAR;
;         }
;         if (wr == 0) PG8_BAR;
	s_waitcnt lgkmcnt(0)
	s_setprio 1
	s_waitcnt lgkmcnt(0)
	v_mfma_f32_16x16x32_bf16 v[126:129], v[142:145], v[190:193], v[126:129]
	v_mfma_f32_16x16x32_bf16 v[126:129], v[162:165], v[194:197], v[126:129]
	v_mfma_f32_16x16x32_bf16 v[122:125], v[182:185], v[190:193], v[122:125]
	v_mfma_f32_16x16x32_bf16 v[122:125], v[186:189], v[194:197], v[122:125]
	v_mfma_f32_16x16x32_bf16 v[110:113], v[142:145], v[198:201], v[110:113]
	v_mfma_f32_16x16x32_bf16 v[110:113], v[162:165], v[202:205], v[110:113]
	v_mfma_f32_16x16x32_bf16 v[106:109], v[182:185], v[198:201], v[106:109]
	v_mfma_f32_16x16x32_bf16 v[106:109], v[186:189], v[202:205], v[106:109]
	v_mfma_f32_16x16x32_bf16 v[94:97], v[142:145], v[206:209], v[94:97]
	v_mfma_f32_16x16x32_bf16 v[94:97], v[162:165], v[210:213], v[94:97]
	v_mfma_f32_16x16x32_bf16 v[90:93], v[182:185], v[206:209], v[90:93]
	v_mfma_f32_16x16x32_bf16 v[90:93], v[186:189], v[210:213], v[90:93]
	v_mfma_f32_16x16x32_bf16 v[78:81], v[142:145], v[214:217], v[78:81]
	v_mfma_f32_16x16x32_bf16 v[78:81], v[162:165], v[218:221], v[78:81]
	v_mfma_f32_16x16x32_bf16 v[74:77], v[182:185], v[214:217], v[74:77]
	s_barrier
	v_mfma_f32_16x16x32_bf16 v[74:77], v[186:189], v[218:221], v[74:77]
	s_setprio 0
	s_add_i32 s60, 0, 0x1c000
	s_add_i32 s24, s51, s86
	s_add_i32 m0, s24, 0xffffff80
	ds_read_b128 v[222:225], v249 offset:49152
	ds_read_b128 v[226:229], v249 offset:50176
	ds_read_b128 v[230:233], v249 offset:51200
	ds_read_b128 v[234:237], v249 offset:52224
	global_load_lds_dwordx4 v134, s[48:49] offset:128
	s_add_i32 m0, s24, 0x1f80
	s_nop 0
	global_load_lds_dwordx4 v130, s[48:49] offset:128
	s_barrier
	s_waitcnt lgkmcnt(0)
	s_setprio 1
	s_waitcnt lgkmcnt(0)
	v_mfma_f32_16x16x32_bf16 v[118:121], v[222:225], v[190:193], v[118:121]
	v_mfma_f32_16x16x32_bf16 v[118:121], v[226:229], v[194:197], v[118:121]
	v_mfma_f32_16x16x32_bf16 v[114:117], v[230:233], v[190:193], v[114:117]
	v_mfma_f32_16x16x32_bf16 v[114:117], v[234:237], v[194:197], v[114:117]
	v_mfma_f32_16x16x32_bf16 v[102:105], v[222:225], v[198:201], v[102:105]
	v_mfma_f32_16x16x32_bf16 v[102:105], v[226:229], v[202:205], v[102:105]
	v_mfma_f32_16x16x32_bf16 v[98:101], v[230:233], v[198:201], v[98:101]
	v_mfma_f32_16x16x32_bf16 v[98:101], v[234:237], v[202:205], v[98:101]
	v_mfma_f32_16x16x32_bf16 v[86:89], v[222:225], v[206:209], v[86:89]
	v_mfma_f32_16x16x32_bf16 v[86:89], v[226:229], v[210:213], v[86:89]
	v_mfma_f32_16x16x32_bf16 v[82:85], v[230:233], v[206:209], v[82:85]
	v_mfma_f32_16x16x32_bf16 v[82:85], v[234:237], v[210:213], v[82:85]
	v_mfma_f32_16x16x32_bf16 v[70:73], v[222:225], v[214:217], v[70:73]
	v_mfma_f32_16x16x32_bf16 v[70:73], v[226:229], v[218:221], v[70:73]
	v_mfma_f32_16x16x32_bf16 v[66:69], v[230:233], v[214:217], v[66:69]
	s_barrier
	v_mfma_f32_16x16x32_bf16 v[66:69], v[234:237], v[218:221], v[66:69]
	s_setprio 0
	s_add_i32 m0, s95, 0xffffff80
	ds_read_b128 v[190:193], v169 offset:49152
	ds_read_b128 v[194:197], v169 offset:50176
	ds_read_b128 v[198:201], v169 offset:51200
	ds_read_b128 v[202:205], v169 offset:52224
	ds_read_b128 v[206:209], v169 offset:53248
	ds_read_b128 v[210:213], v169 offset:54272
	ds_read_b128 v[214:217], v169 offset:55296
	ds_read_b128 v[218:221], v169 offset:56320
	global_load_lds_dwordx4 v136, s[100:101] offset:128
	s_add_i32 m0, s96, 0xffffff80
	s_nop 0
	global_load_lds_dwordx4 v132, s[100:101] offset:128
	s_waitcnt vmcnt(8)
	s_barrier
	s_waitcnt lgkmcnt(0)
	s_setprio 1
	s_waitcnt lgkmcnt(0)
	v_mfma_f32_16x16x32_bf16 v[62:65], v[142:145], v[190:193], v[62:65]
	v_mfma_f32_16x16x32_bf16 v[62:65], v[162:165], v[194:197], v[62:65]
	v_mfma_f32_16x16x32_bf16 v[58:61], v[182:185], v[190:193], v[58:61]
	v_mfma_f32_16x16x32_bf16 v[58:61], v[186:189], v[194:197], v[58:61]
	v_mfma_f32_16x16x32_bf16 v[46:49], v[142:145], v[198:201], v[46:49]
	v_mfma_f32_16x16x32_bf16 v[46:49], v[162:165], v[202:205], v[46:49]
	v_mfma_f32_16x16x32_bf16 v[42:45], v[182:185], v[198:201], v[42:45]
	v_mfma_f32_16x16x32_bf16 v[42:45], v[186:189], v[202:205], v[42:45]
	v_mfma_f32_16x16x32_bf16 v[30:33], v[142:145], v[206:209], v[30:33]
	v_mfma_f32_16x16x32_bf16 v[30:33], v[162:165], v[210:213], v[30:33]
	v_mfma_f32_16x16x32_bf16 v[26:29], v[182:185], v[206:209], v[26:29]
	v_mfma_f32_16x16x32_bf16 v[26:29], v[186:189], v[210:213], v[26:29]
	v_mfma_f32_16x16x32_bf16 v[14:17], v[142:145], v[214:217], v[14:17]
	v_mfma_f32_16x16x32_bf16 v[14:17], v[162:165], v[218:221], v[14:17]
	v_mfma_f32_16x16x32_bf16 v[10:13], v[182:185], v[214:217], v[10:13]
	s_barrier
	v_mfma_f32_16x16x32_bf16 v[10:13], v[186:189], v[218:221], v[10:13]
	s_setprio 0
	s_add_u32 s24, s48, 0x40080
	s_addc_u32 s25, s49, 0
	s_add_i32 s48, s60, s86
	s_mov_b32 m0, s48
	s_nop 0
	global_load_lds_dwordx4 v134, s[24:25]
	s_add_i32 m0, s48, 0x2000
	s_nop 0
	global_load_lds_dwordx4 v130, s[24:25]
	s_waitcnt vmcnt(6)
	s_barrier
	s_setprio 1
	v_mfma_f32_16x16x32_bf16 v[54:57], v[222:225], v[190:193], v[54:57]
	ds_read_b128 v[142:145], v249
	ds_read_b128 v[162:165], v249 offset:1024
	v_mfma_f32_16x16x32_bf16 v[54:57], v[226:229], v[194:197], v[54:57]
	ds_read_b128 v[182:185], v249 offset:2048
	ds_read_b128 v[186:189], v249 offset:3072
	v_mfma_f32_16x16x32_bf16 v[50:53], v[230:233], v[190:193], v[50:53]
	ds_read_b128 v[190:193], v169
	v_mfma_f32_16x16x32_bf16 v[50:53], v[234:237], v[194:197], v[50:53]
	ds_read_b128 v[194:197], v169 offset:1024
	v_mfma_f32_16x16x32_bf16 v[38:41], v[222:225], v[198:201], v[38:41]
	v_mfma_f32_16x16x32_bf16 v[38:41], v[226:229], v[202:205], v[38:41]
	v_mfma_f32_16x16x32_bf16 v[34:37], v[230:233], v[198:201], v[34:37]
	ds_read_b128 v[198:201], v169 offset:2048
	v_mfma_f32_16x16x32_bf16 v[34:37], v[234:237], v[202:205], v[34:37]
	ds_read_b128 v[202:205], v169 offset:3072
	v_mfma_f32_16x16x32_bf16 v[22:25], v[222:225], v[206:209], v[22:25]
	v_mfma_f32_16x16x32_bf16 v[22:25], v[226:229], v[210:213], v[22:25]
	v_mfma_f32_16x16x32_bf16 v[18:21], v[230:233], v[206:209], v[18:21]
	ds_read_b128 v[206:209], v169 offset:4096
	v_mfma_f32_16x16x32_bf16 v[18:21], v[234:237], v[210:213], v[18:21]
	ds_read_b128 v[210:213], v169 offset:5120
	v_mfma_f32_16x16x32_bf16 v[6:9], v[222:225], v[214:217], v[6:9]
	v_mfma_f32_16x16x32_bf16 v[6:9], v[226:229], v[218:221], v[6:9]
	v_mfma_f32_16x16x32_bf16 v[2:5], v[230:233], v[214:217], v[2:5]
	ds_read_b128 v[214:217], v169 offset:6144
	s_barrier
	v_mfma_f32_16x16x32_bf16 v[2:5], v[234:237], v[218:221], v[2:5]
	s_setprio 0
	s_add_i32 s50, s50, 2
	s_add_u32 vcc_lo, vcc_lo, 0x100
	s_addc_u32 s35, s35, 0
	s_add_u32 s38, s38, 0x100
	s_addc_u32 s39, s39, 0
	s_cmp_gt_u32 s50, 13
	s_cbranch_scc0 .LBB0_165
	s_waitcnt lgkmcnt(0)
	s_and_b64 vcc, exec, s[40:41]
	s_cbranch_vccz .LBB0_168
	s_barrier

; #define PG8_STAGE(bufoff, gbase, voff) do { _Pragma("unroll") for (int _i = 0; _i < 2; ++_i) \
;         __builtin_amdgcn_global_load_lds((const unsigned*)((const char*)(gbase) + (voff)[_i]), (LAS unsigned*)(lds + (bufoff) + ldsw + _i * 8192), 16, 0, 0); } while (0)
; #define PG8_LDA(dst, b, h) do { _Pragma("unroll") for (int m = 0; m < 4; ++m) _Pragma("unroll") for (int k = 0; k < 2; ++k) dst[m][k] = *(const LAS bf16x8*)(lds + PG8_SA(b, h) + aoff + m * 2048 + k * 1024); } while (0)
; #define PG8_LDB(dst, b, h) do { _Pragma("unroll") for (int n = 0; n < 2; ++n) _Pragma("unroll") for (int k = 0; k < 2; ++k) dst[n][k] = *(const LAS bf16x8*)(lds + PG8_SB(b, h) + boff + n * 2048 + k * 1024); } while (0)
; #define PG8_MMA(ai, bj, At, Bt) do { __builtin_amdgcn_s_setprio(1); _Pragma("unroll") for (int m = 0; m < 4; ++m) _Pragma("unroll") for (int n = 0; n < 2; ++n) _Pragma("unroll") for (int k = 0; k < 2; ++k) \
;         acc[ai][bj][m][n] = __builtin_amdgcn_mfma_f32_16x16x32_bf16(Bt[n][k], At[m][k], acc[ai][bj][m][n], 0, 0, 0); __builtin_amdgcn_s_setprio(0); } while (0)
; #define PG8_WAIT_L(n) asm volatile("s_waitcnt lgkmcnt(" #n ")" ::: "memory")
; template <class Epi, class Sched>
; __device__ __forceinline__ void gemm_phase(LAS unsigned char* lds, const Gemm g, const Sched& S, const Epi& E) {
;     ...
;         const bool has_next = S.next(ui + 1, nxt);
;         const char* nA = has_next ? PG8_APANEL(nxt.pm) : cA; const char* nB = has_next ? (const char*)g.Bt + (size_t)nxt.pn * tstep : cB;
;         for (int t = 0; t < nt; t += 2) {
;             const bool last = (t == nt - 2);
;             const char* a1 = cA + (size_t)(t + 1) * kstep;
;             const char* a2 = last ? nA : cA + (size_t)(t + 2) * kstep; const char* b2 = last ? nB : cB + (size_t)(t + 2) * kstep;
;             const char* a3 = a2 + kstep; const char* b3 = b2 + kstep;
;             PG8_LDB(B0, 0, 0); PG8_SCHED; PG8_LDA(At, 0, 0); PG8_STAGE(PG8_SA(1, 1), a1 + hstep, voffA);
;             PG8_WAIT_L(8); PG8_BAR; PG8_WAIT_L(0); PG8_MMA(0, 0, At, B0); PG8_BAR; PG8_SCHED;
;             PG8_LDB(B1, 0, 1); PG8_STAGE(PG8_SB(0, 0), b2, voffB);
;             PG8_BAR; PG8_WAIT_L(0); PG8_MMA(0, 1, At, B1); PG8_BAR;
;             PG8_LDA(At, 0, 1); PG8_STAGE(PG8_SA(0, 0), a2, voffA);
;             PG8_BAR; PG8_WAIT_L(0); PG8_MMA(1, 0, At, B0); PG8_BAR; PG8_SCHED;
.LBB0_415:
	s_ashr_i32 s47, s46, 31
	s_lshl_b64 s[24:25], s[46:47], 19
	s_add_u32 s48, s82, s24
	s_addc_u32 s49, s83, s25
	s_and_b64 s[0:1], s[0:1], exec
	s_cselect_b32 s47, s49, s37
	s_cselect_b32 s61, s48, s36
	s_add_u32 s35, s36, 0x100
	s_addc_u32 s50, s37, 0
	s_add_u32 s0, s38, 0x40080
	s_addc_u32 s1, s39, 0
	s_mov_b32 s38, -2
	v_add_u32_e32 v249, 0x10000, v144
	ds_read_b128 v[164:167], v249
	ds_read_b128 v[182:185], v249 offset:1024
	ds_read_b128 v[186:189], v249 offset:2048
	ds_read_b128 v[190:193], v249 offset:3072
	ds_read_b128 v[194:197], v162
	ds_read_b128 v[198:201], v162 offset:1024
	ds_read_b128 v[202:205], v162 offset:2048
	ds_read_b128 v[206:209], v162 offset:3072
	ds_read_b128 v[210:213], v162 offset:4096
	ds_read_b128 v[214:217], v162 offset:5120
	ds_read_b128 v[218:221], v162 offset:6144
	s_add_u32 s24, s0, 0xfffc0080
	s_addc_u32 s25, s1, -1
	s_add_i32 s39, 0, 0x10000
	s_cmp_eq_u32 s38, 12
	s_cselect_b32 vcc_hi, s77, s25
	s_cselect_b32 vcc_lo, s76, s24
	s_cselect_b32 s37, s47, s50
	s_cselect_b32 s36, s61, s35
	s_add_i32 m0, s93, 0xc000
	ds_read_b128 v[222:225], v162 offset:7168
	global_load_lds_dwordx4 v140, s[0:1]
	s_add_i32 m0, s93, 0xe000
	s_nop 0
	global_load_lds_dwordx4 v138, s[0:1]
	s_waitcnt lgkmcnt(8)
	s_barrier
	s_waitcnt lgkmcnt(0)
	s_setprio 1
	s_waitcnt lgkmcnt(0)
	v_mfma_f32_16x16x32_bf16 v[126:129], v[164:167], v[194:197], 0
	v_mfma_f32_16x16x32_bf16 v[126:129], v[182:185], v[198:201], v[126:129]
	v_mfma_f32_16x16x32_bf16 v[122:125], v[186:189], v[194:197], 0
	v_mfma_f32_16x16x32_bf16 v[122:125], v[190:193], v[198:201], v[122:125]
	v_mfma_f32_16x16x32_bf16 v[118:121], v[164:167], v[202:205], 0
	v_mfma_f32_16x16x32_bf16 v[118:121], v[182:185], v[206:209], v[118:121]
	v_mfma_f32_16x16x32_bf16 v[110:113], v[186:189], v[202:205], 0
	v_mfma_f32_16x16x32_bf16 v[110:113], v[190:193], v[206:209], v[110:113]
	v_mfma_f32_16x16x32_bf16 v[102:105], v[164:167], v[210:213], 0
	v_mfma_f32_16x16x32_bf16 v[102:105], v[182:185], v[214:217], v[102:105]
	v_mfma_f32_16x16x32_bf16 v[94:97], v[186:189], v[210:213], 0
	v_mfma_f32_16x16x32_bf16 v[94:97], v[190:193], v[214:217], v[94:97]
	v_mfma_f32_16x16x32_bf16 v[86:89], v[164:167], v[218:221], 0
	v_mfma_f32_16x16x32_bf16 v[86:89], v[182:185], v[222:225], v[86:89]
	v_mfma_f32_16x16x32_bf16 v[78:81], v[186:189], v[218:221], 0
	s_barrier
	v_mfma_f32_16x16x32_bf16 v[78:81], v[190:193], v[222:225], v[78:81]
	s_setprio 0
	s_add_i32 s51, 0, 0x14000
	s_add_i32 s24, s39, s86
	ds_read_b128 v[226:229], v249 offset:16384
	ds_read_b128 v[230:233], v249 offset:17408
	ds_read_b128 v[234:237], v249 offset:18432
	ds_read_b128 v[238:241], v249 offset:19456
	s_mov_b32 m0, s24
	global_load_lds_dwordx4 v134, s[36:37]
	s_add_i32 m0, s24, 0x2000
	s_nop 0
	global_load_lds_dwordx4 v130, s[36:37]
	s_barrier
	s_waitcnt lgkmcnt(0)
	s_setprio 1
	s_waitcnt lgkmcnt(0)
	v_mfma_f32_16x16x32_bf16 v[114:117], v[226:229], v[194:197], 0
	v_mfma_f32_16x16x32_bf16 v[114:117], v[230:233], v[198:201], v[114:117]
	v_mfma_f32_16x16x32_bf16 v[106:109], v[234:237], v[194:197], 0
	v_mfma_f32_16x16x32_bf16 v[106:109], v[238:241], v[198:201], v[106:109]
	v_mfma_f32_16x16x32_bf16 v[98:101], v[226:229], v[202:205], 0
	v_mfma_f32_16x16x32_bf16 v[98:101], v[230:233], v[206:209], v[98:101]
	v_mfma_f32_16x16x32_bf16 v[90:93], v[234:237], v[202:205], 0
	v_mfma_f32_16x16x32_bf16 v[90:93], v[238:241], v[206:209], v[90:93]
	v_mfma_f32_16x16x32_bf16 v[82:85], v[226:229], v[210:213], 0
	v_mfma_f32_16x16x32_bf16 v[82:85], v[230:233], v[214:217], v[82:85]
	v_mfma_f32_16x16x32_bf16 v[74:77], v[234:237], v[210:213], 0
	v_mfma_f32_16x16x32_bf16 v[74:77], v[238:241], v[214:217], v[74:77]
	v_mfma_f32_16x16x32_bf16 v[70:73], v[226:229], v[218:221], 0
	v_mfma_f32_16x16x32_bf16 v[70:73], v[230:233], v[222:225], v[70:73]
	v_mfma_f32_16x16x32_bf16 v[66:69], v[234:237], v[218:221], 0
	s_barrier
	v_mfma_f32_16x16x32_bf16 v[66:69], v[238:241], v[222:225], v[66:69]
	s_setprio 0
	s_mov_b32 m0, s93
	ds_read_b128 v[194:197], v162 offset:16384
	ds_read_b128 v[198:201], v162 offset:17408
	ds_read_b128 v[202:205], v162 offset:18432
	ds_read_b128 v[206:209], v162 offset:19456
	ds_read_b128 v[210:213], v162 offset:20480
	ds_read_b128 v[214:217], v162 offset:21504
	ds_read_b128 v[218:221], v162 offset:22528
	ds_read_b128 v[222:225], v162 offset:23552
	global_load_lds_dwordx4 v136, vcc
	s_mov_b32 m0, s94
	s_nop 0
	global_load_lds_dwordx4 v132, vcc
	s_waitcnt vmcnt(8)
	s_barrier
	s_waitcnt lgkmcnt(0)
	s_setprio 1
	s_waitcnt lgkmcnt(0)
	v_mfma_f32_16x16x32_bf16 v[62:65], v[164:167], v[194:197], 0
	v_mfma_f32_16x16x32_bf16 v[62:65], v[182:185], v[198:201], v[62:65]
	v_mfma_f32_16x16x32_bf16 v[58:61], v[186:189], v[194:197], 0
	v_mfma_f32_16x16x32_bf16 v[58:61], v[190:193], v[198:201], v[58:61]
	v_mfma_f32_16x16x32_bf16 v[54:57], v[164:167], v[202:205], 0
	v_mfma_f32_16x16x32_bf16 v[54:57], v[182:185], v[206:209], v[54:57]
	v_mfma_f32_16x16x32_bf16 v[46:49], v[186:189], v[202:205], 0
	v_mfma_f32_16x16x32_bf16 v[46:49], v[190:193], v[206:209], v[46:49]
	v_mfma_f32_16x16x32_bf16 v[38:41], v[164:167], v[210:213], 0
	v_mfma_f32_16x16x32_bf16 v[38:41], v[182:185], v[214:217], v[38:41]
	v_mfma_f32_16x16x32_bf16 v[30:33], v[186:189], v[210:213], 0
	v_mfma_f32_16x16x32_bf16 v[30:33], v[190:193], v[214:217], v[30:33]
	v_mfma_f32_16x16x32_bf16 v[22:25], v[164:167], v[218:221], 0
	v_mfma_f32_16x16x32_bf16 v[22:25], v[182:185], v[222:225], v[22:25]
	v_mfma_f32_16x16x32_bf16 v[14:17], v[186:189], v[218:221], 0
	s_barrier
; #define PG8_STAGE(bufoff, gbase, voff) do { _Pragma("unroll") for (int _i = 0; _i < 2; ++_i) \
;         __builtin_amdgcn_global_load_lds((const unsigned*)((const char*)(gbase) + (voff)[_i]), (LAS unsigned*)(lds + (bufoff) + ldsw + _i * 8192), 16, 0, 0); } while (0)
; #define PG8_LDA(dst, b, h) do { _Pragma("unroll") for (int m = 0; m < 4; ++m) _Pragma("unroll") for (int k = 0; k < 2; ++k) dst[m][k] = *(const LAS bf16x8*)(lds + PG8_SA(b, h) + aoff + m * 2048 + k * 1024); } while (0)
; #define PG8_LDB(dst, b, h) do { _Pragma("unroll") for (int n = 0; n < 2; ++n) _Pragma("unroll") for (int k = 0; k < 2; ++k) dst[n][k] = *(const LAS bf16x8*)(lds + PG8_SB(b, h) + boff + n * 2048 + k * 1024); } while (0)
; #define PG8_MMA(ai, bj, At, Bt) do { __builtin_amdgcn_s_setprio(1); _Pragma("unroll") for (int m = 0; m < 4; ++m) _Pragma("unroll") for (int n = 0; n < 2; ++n) _Pragma("unroll") for (int k = 0; k < 2; ++k) \
;         acc[ai][bj][m][n] = __builtin_amdgcn_mfma_f32_16x16x32_bf16(Bt[n][k], At[m][k], acc[ai][bj][m][n], 0, 0, 0); __builtin_amdgcn_s_setprio(0); } while (0)
; #define PG8_WAIT_V(n) asm volatile("s_waitcnt vmcnt(" #n ")" ::: "memory")
; #define PG8_WAIT_L(n) asm volatile("s_waitcnt lgkmcnt(" #n ")" ::: "memory")
; #define PG8_BAR __builtin_amdgcn_s_barrier()
; #define PG8_SCHED __builtin_amdgcn_sched_barrier(0)
; template <class Epi, class Sched>
; __device__ __forceinline__ void gemm_phase(LAS unsigned char* lds, const Gemm g, const Sched& S, const Epi& E) {
;     ...
;             PG8_BAR; PG8_WAIT_L(0); PG8_MMA(1, 0, At, B0); PG8_BAR; PG8_SCHED;
;             PG8_STAGE(PG8_SB(0, 1), b2 + hstep, voffB);
;             PG8_WAIT_V(6); PG8_BAR; PG8_MMA(1, 1, At, B1); PG8_BAR;
;             PG8_LDB(B0, 1, 0); PG8_SCHED; PG8_LDA(At, 1, 0); PG8_STAGE(PG8_SA(0, 1), a2 + hstep, voffA);
;             PG8_WAIT_L(8); PG8_BAR; PG8_WAIT_L(0); PG8_MMA(0, 0, At, B0); PG8_BAR; PG8_SCHED;
;             PG8_LDB(B1, 1, 1); PG8_STAGE(PG8_SB(1, 0), b3, voffB);
;             PG8_BAR; PG8_WAIT_L(0); PG8_MMA(0, 1, At, B1); PG8_BAR;
;             PG8_LDA(At, 1, 1); PG8_STAGE(PG8_SA(1, 0), a3, voffA);
	v_mfma_f32_16x16x32_bf16 v[14:17], v[190:193], v[222:225], v[14:17]
	s_setprio 0
	s_add_u32 s24, s36, 0x40000
	s_addc_u32 s25, s37, 0
	s_add_i32 s39, s51, s86
	s_mov_b32 m0, s39
	s_nop 0
	global_load_lds_dwordx4 v134, s[24:25]
	s_add_i32 m0, s39, 0x2000
	s_nop 0
	global_load_lds_dwordx4 v130, s[24:25]
	s_waitcnt vmcnt(6)
	s_barrier
	s_setprio 1
	v_mfma_f32_16x16x32_bf16 v[50:53], v[226:229], v[194:197], 0
	ds_read_b128 v[164:167], v249 offset:32768
	ds_read_b128 v[182:185], v249 offset:33792
	v_mfma_f32_16x16x32_bf16 v[50:53], v[230:233], v[198:201], v[50:53]
	ds_read_b128 v[186:189], v249 offset:34816
	ds_read_b128 v[190:193], v249 offset:35840
	v_mfma_f32_16x16x32_bf16 v[42:45], v[234:237], v[194:197], 0
	ds_read_b128 v[194:197], v162 offset:32768
	v_mfma_f32_16x16x32_bf16 v[42:45], v[238:241], v[198:201], v[42:45]
	ds_read_b128 v[198:201], v162 offset:33792
	v_mfma_f32_16x16x32_bf16 v[34:37], v[226:229], v[202:205], 0
	v_mfma_f32_16x16x32_bf16 v[34:37], v[230:233], v[206:209], v[34:37]
	v_mfma_f32_16x16x32_bf16 v[26:29], v[234:237], v[202:205], 0
	ds_read_b128 v[202:205], v162 offset:34816
	v_mfma_f32_16x16x32_bf16 v[26:29], v[238:241], v[206:209], v[26:29]
	ds_read_b128 v[206:209], v162 offset:35840
	v_mfma_f32_16x16x32_bf16 v[18:21], v[226:229], v[210:213], 0
	v_mfma_f32_16x16x32_bf16 v[18:21], v[230:233], v[214:217], v[18:21]
	v_mfma_f32_16x16x32_bf16 v[10:13], v[234:237], v[210:213], 0
	ds_read_b128 v[210:213], v162 offset:36864
	v_mfma_f32_16x16x32_bf16 v[10:13], v[238:241], v[214:217], v[10:13]
	ds_read_b128 v[214:217], v162 offset:37888
	v_mfma_f32_16x16x32_bf16 v[6:9], v[226:229], v[218:221], 0
	v_mfma_f32_16x16x32_bf16 v[6:9], v[230:233], v[222:225], v[6:9]
	v_mfma_f32_16x16x32_bf16 v[2:5], v[234:237], v[218:221], 0
	ds_read_b128 v[218:221], v162 offset:38912
	s_barrier
	v_mfma_f32_16x16x32_bf16 v[2:5], v[238:241], v[222:225], v[2:5]
	s_setprio 0
	s_add_i32 s39, 0, 0x18000
	s_add_u32 s24, vcc_lo, 0x40000
	s_addc_u32 s25, vcc_hi, 0
	s_mov_b32 m0, s95
	ds_read_b128 v[222:225], v162 offset:39936
	global_load_lds_dwordx4 v136, s[24:25]
	s_mov_b32 m0, s96
	s_nop 0
	global_load_lds_dwordx4 v132, s[24:25]
	s_waitcnt lgkmcnt(8)
	s_barrier
	s_waitcnt lgkmcnt(0)
	s_setprio 1
	s_waitcnt lgkmcnt(0)
	v_mfma_f32_16x16x32_bf16 v[126:129], v[164:167], v[194:197], v[126:129]
	v_mfma_f32_16x16x32_bf16 v[126:129], v[182:185], v[198:201], v[126:129]
	v_mfma_f32_16x16x32_bf16 v[122:125], v[186:189], v[194:197], v[122:125]
	v_mfma_f32_16x16x32_bf16 v[122:125], v[190:193], v[198:201], v[122:125]
	v_mfma_f32_16x16x32_bf16 v[118:121], v[164:167], v[202:205], v[118:121]
	v_mfma_f32_16x16x32_bf16 v[118:121], v[182:185], v[206:209], v[118:121]
	v_mfma_f32_16x16x32_bf16 v[110:113], v[186:189], v[202:205], v[110:113]
	v_mfma_f32_16x16x32_bf16 v[110:113], v[190:193], v[206:209], v[110:113]
	v_mfma_f32_16x16x32_bf16 v[102:105], v[164:167], v[210:213], v[102:105]
	v_mfma_f32_16x16x32_bf16 v[102:105], v[182:185], v[214:217], v[102:105]
	v_mfma_f32_16x16x32_bf16 v[94:97], v[186:189], v[210:213], v[94:97]
	v_mfma_f32_16x16x32_bf16 v[94:97], v[190:193], v[214:217], v[94:97]
	v_mfma_f32_16x16x32_bf16 v[86:89], v[164:167], v[218:221], v[86:89]
	v_mfma_f32_16x16x32_bf16 v[86:89], v[182:185], v[222:225], v[86:89]
	v_mfma_f32_16x16x32_bf16 v[78:81], v[186:189], v[218:221], v[78:81]
	s_barrier
	v_mfma_f32_16x16x32_bf16 v[78:81], v[190:193], v[222:225], v[78:81]
	s_setprio 0
	s_add_i32 s51, 0, 0x1c000
	s_add_i32 s24, s39, s86
	s_add_i32 m0, s24, 0xffffff80
	ds_read_b128 v[226:229], v249 offset:49152
	ds_read_b128 v[230:233], v249 offset:50176
	ds_read_b128 v[234:237], v249 offset:51200
	ds_read_b128 v[238:241], v249 offset:52224
	global_load_lds_dwordx4 v134, s[36:37] offset:128
	s_add_i32 m0, s24, 0x1f80
	s_nop 0
	global_load_lds_dwordx4 v130, s[36:37] offset:128
	s_barrier
	s_waitcnt lgkmcnt(0)
	s_setprio 1
	s_waitcnt lgkmcnt(0)
	v_mfma_f32_16x16x32_bf16 v[114:117], v[226:229], v[194:197], v[114:117]
	v_mfma_f32_16x16x32_bf16 v[114:117], v[230:233], v[198:201], v[114:117]
	v_mfma_f32_16x16x32_bf16 v[106:109], v[234:237], v[194:197], v[106:109]
	v_mfma_f32_16x16x32_bf16 v[106:109], v[238:241], v[198:201], v[106:109]
	v_mfma_f32_16x16x32_bf16 v[98:101], v[226:229], v[202:205], v[98:101]
	v_mfma_f32_16x16x32_bf16 v[98:101], v[230:233], v[206:209], v[98:101]
	v_mfma_f32_16x16x32_bf16 v[90:93], v[234:237], v[202:205], v[90:93]
	v_mfma_f32_16x16x32_bf16 v[90:93], v[238:241], v[206:209], v[90:93]
	v_mfma_f32_16x16x32_bf16 v[82:85], v[226:229], v[210:213], v[82:85]
	v_mfma_f32_16x16x32_bf16 v[82:85], v[230:233], v[214:217], v[82:85]
	v_mfma_f32_16x16x32_bf16 v[74:77], v[234:237], v[210:213], v[74:77]
	v_mfma_f32_16x16x32_bf16 v[74:77], v[238:241], v[214:217], v[74:77]
	v_mfma_f32_16x16x32_bf16 v[70:73], v[226:229], v[218:221], v[70:73]
	v_mfma_f32_16x16x32_bf16 v[70:73], v[230:233], v[222:225], v[70:73]
	v_mfma_f32_16x16x32_bf16 v[66:69], v[234:237], v[218:221], v[66:69]
	s_barrier
	v_mfma_f32_16x16x32_bf16 v[66:69], v[238:241], v[222:225], v[66:69]
	s_setprio 0
	s_add_i32 m0, s97, 0xffffff80
	ds_read_b128 v[194:197], v162 offset:49152
	ds_read_b128 v[198:201], v162 offset:50176
	ds_read_b128 v[202:205], v162 offset:51200
	ds_read_b128 v[206:209], v162 offset:52224
	ds_read_b128 v[210:213], v162 offset:53248
	ds_read_b128 v[214:217], v162 offset:54272
	ds_read_b128 v[218:221], v162 offset:55296
	ds_read_b128 v[222:225], v162 offset:56320
	global_load_lds_dwordx4 v136, vcc offset:128
	s_add_i32 m0, s98, 0xffffff80
	s_nop 0
	global_load_lds_dwordx4 v132, vcc offset:128
	s_waitcnt vmcnt(8)
	s_barrier
; #define PG8_STAGE(bufoff, gbase, voff) do { _Pragma("unroll") for (int _i = 0; _i < 2; ++_i) \
;         __builtin_amdgcn_global_load_lds((const unsigned*)((const char*)(gbase) + (voff)[_i]), (LAS unsigned*)(lds + (bufoff) + ldsw + _i * 8192), 16, 0, 0); } while (0)
; #define PG8_LDA(dst, b, h) do { _Pragma("unroll") for (int m = 0; m < 4; ++m) _Pragma("unroll") for (int k = 0; k < 2; ++k) dst[m][k] = *(const LAS bf16x8*)(lds + PG8_SA(b, h) + aoff + m * 2048 + k * 1024); } while (0)
; #define PG8_LDB(dst, b, h) do { _Pragma("unroll") for (int n = 0; n < 2; ++n) _Pragma("unroll") for (int k = 0; k < 2; ++k) dst[n][k] = *(const LAS bf16x8*)(lds + PG8_SB(b, h) + boff + n * 2048 + k * 1024); } while (0)
; #define PG8_WAIT_V(n) asm volatile("s_waitcnt vmcnt(" #n ")" ::: "memory")
; #define PG8_WAIT_L(n) asm volatile("s_waitcnt lgkmcnt(" #n ")" ::: "memory")
; #define PG8_BAR __builtin_amdgcn_s_barrier()
; #define PG8_SCHED __builtin_amdgcn_sched_barrier(0)
; template <class Epi, class Sched>
; __device__ __forceinline__ void gemm_phase(LAS unsigned char* lds, const Gemm g, const Sched& S, const Epi& E) {
;     ...
;             const bool last = (t == nt - 2);
;             const char* a1 = cA + (size_t)(t + 1) * kstep;
;             const char* a2 = last ? nA : cA + (size_t)(t + 2) * kstep; const char* b2 = last ? nB : cB + (size_t)(t + 2) * kstep;
;             const char* a3 = a2 + kstep; const char* b3 = b2 + kstep;
;             PG8_LDB(B0, 0, 0); PG8_SCHED; PG8_LDA(At, 0, 0); PG8_STAGE(PG8_SA(1, 1), a1 + hstep, voffA);
;             PG8_WAIT_L(8); PG8_BAR; PG8_WAIT_L(0); PG8_MMA(0, 0, At, B0); PG8_BAR; PG8_SCHED;
;             PG8_LDB(B1, 0, 1); PG8_STAGE(PG8_SB(0, 0), b2, voffB);
;     ...
;             PG8_LDB(B0, 1, 0); PG8_SCHED; PG8_LDA(At, 1, 0); PG8_STAGE(PG8_SA(0, 1), a2 + hstep, voffA);
;             PG8_WAIT_L(8); PG8_BAR; PG8_WAIT_L(0); PG8_MMA(0, 0, At, B0); PG8_BAR; PG8_SCHED;
;             PG8_LDB(B1, 1, 1); PG8_STAGE(PG8_SB(1, 0), b3, voffB);
;             PG8_BAR; PG8_WAIT_L(0); PG8_MMA(0, 1, At, B1); PG8_BAR;
;             PG8_LDA(At, 1, 1); PG8_STAGE(PG8_SA(1, 0), a3, voffA);
;             PG8_BAR; PG8_WAIT_L(0); PG8_MMA(1, 0, At, B0); PG8_BAR; PG8_SCHED;
;             PG8_STAGE(PG8_SB(1, 1), b3 + hstep, voffB);
;             PG8_WAIT_V(6); PG8_BAR; PG8_MMA(1, 1, At, B1); PG8_BAR;
	s_waitcnt lgkmcnt(0)
	s_setprio 1
	s_waitcnt lgkmcnt(0)
	v_mfma_f32_16x16x32_bf16 v[62:65], v[164:167], v[194:197], v[62:65]
	v_mfma_f32_16x16x32_bf16 v[62:65], v[182:185], v[198:201], v[62:65]
	v_mfma_f32_16x16x32_bf16 v[58:61], v[186:189], v[194:197], v[58:61]
	v_mfma_f32_16x16x32_bf16 v[58:61], v[190:193], v[198:201], v[58:61]
	v_mfma_f32_16x16x32_bf16 v[54:57], v[164:167], v[202:205], v[54:57]
	v_mfma_f32_16x16x32_bf16 v[54:57], v[182:185], v[206:209], v[54:57]
	v_mfma_f32_16x16x32_bf16 v[46:49], v[186:189], v[202:205], v[46:49]
	v_mfma_f32_16x16x32_bf16 v[46:49], v[190:193], v[206:209], v[46:49]
	v_mfma_f32_16x16x32_bf16 v[38:41], v[164:167], v[210:213], v[38:41]
	v_mfma_f32_16x16x32_bf16 v[38:41], v[182:185], v[214:217], v[38:41]
	v_mfma_f32_16x16x32_bf16 v[30:33], v[186:189], v[210:213], v[30:33]
	v_mfma_f32_16x16x32_bf16 v[30:33], v[190:193], v[214:217], v[30:33]
	v_mfma_f32_16x16x32_bf16 v[22:25], v[164:167], v[218:221], v[22:25]
	v_mfma_f32_16x16x32_bf16 v[22:25], v[182:185], v[222:225], v[22:25]
	v_mfma_f32_16x16x32_bf16 v[14:17], v[186:189], v[218:221], v[14:17]
	s_barrier
	v_mfma_f32_16x16x32_bf16 v[14:17], v[190:193], v[222:225], v[14:17]
	s_setprio 0
	s_add_u32 s24, s36, 0x40080
	s_addc_u32 s25, s37, 0
	s_add_i32 s36, s51, s86
	s_mov_b32 m0, s36
	s_nop 0
	global_load_lds_dwordx4 v134, s[24:25]
	s_add_i32 m0, s36, 0x2000
	s_nop 0
	global_load_lds_dwordx4 v130, s[24:25]
	s_waitcnt vmcnt(6)
	s_barrier
	s_setprio 1
	v_mfma_f32_16x16x32_bf16 v[50:53], v[226:229], v[194:197], v[50:53]
	ds_read_b128 v[164:167], v249
	ds_read_b128 v[182:185], v249 offset:1024
	v_mfma_f32_16x16x32_bf16 v[50:53], v[230:233], v[198:201], v[50:53]
	ds_read_b128 v[186:189], v249 offset:2048
	ds_read_b128 v[190:193], v249 offset:3072
	v_mfma_f32_16x16x32_bf16 v[42:45], v[234:237], v[194:197], v[42:45]
	ds_read_b128 v[194:197], v162
	v_mfma_f32_16x16x32_bf16 v[42:45], v[238:241], v[198:201], v[42:45]
	ds_read_b128 v[198:201], v162 offset:1024
	v_mfma_f32_16x16x32_bf16 v[34:37], v[226:229], v[202:205], v[34:37]
	v_mfma_f32_16x16x32_bf16 v[34:37], v[230:233], v[206:209], v[34:37]
	v_mfma_f32_16x16x32_bf16 v[26:29], v[234:237], v[202:205], v[26:29]
	ds_read_b128 v[202:205], v162 offset:2048
	v_mfma_f32_16x16x32_bf16 v[26:29], v[238:241], v[206:209], v[26:29]
	ds_read_b128 v[206:209], v162 offset:3072
	v_mfma_f32_16x16x32_bf16 v[18:21], v[226:229], v[210:213], v[18:21]
	v_mfma_f32_16x16x32_bf16 v[18:21], v[230:233], v[214:217], v[18:21]
	v_mfma_f32_16x16x32_bf16 v[10:13], v[234:237], v[210:213], v[10:13]
	ds_read_b128 v[210:213], v162 offset:4096
	v_mfma_f32_16x16x32_bf16 v[10:13], v[238:241], v[214:217], v[10:13]
	ds_read_b128 v[214:217], v162 offset:5120
	v_mfma_f32_16x16x32_bf16 v[6:9], v[226:229], v[218:221], v[6:9]
	v_mfma_f32_16x16x32_bf16 v[6:9], v[230:233], v[222:225], v[6:9]
	v_mfma_f32_16x16x32_bf16 v[2:5], v[234:237], v[218:221], v[2:5]
	ds_read_b128 v[218:221], v162 offset:6144
	s_barrier
	v_mfma_f32_16x16x32_bf16 v[2:5], v[238:241], v[222:225], v[2:5]
	s_setprio 0
	s_add_i32 s38, s38, 2
	s_add_u32 s35, s35, 0x100
	s_addc_u32 s50, s50, 0
	s_add_u32 s0, s0, 0x100
	s_addc_u32 s1, s1, 0
	s_cmp_gt_u32 s38, 13
.LBB0_416:
	s_add_u32 s24, s0, 0xfffc0080
	s_addc_u32 s25, s1, -1
	s_add_i32 s39, 0, 0x10000
	s_cmp_eq_u32 s38, 12
	s_cselect_b32 vcc_hi, s77, s25
	s_cselect_b32 vcc_lo, s76, s24
	s_cselect_b32 s37, s47, s50
	s_cselect_b32 s36, s61, s35
	s_add_i32 m0, s93, 0xc000
	ds_read_b128 v[222:225], v162 offset:7168
	global_load_lds_dwordx4 v140, s[0:1]
	s_add_i32 m0, s93, 0xe000
	s_nop 0
	global_load_lds_dwordx4 v138, s[0:1]
	s_waitcnt lgkmcnt(8)
	s_barrier
	s_waitcnt lgkmcnt(0)
	s_setprio 1
	s_waitcnt lgkmcnt(0)
	v_mfma_f32_16x16x32_bf16 v[126:129], v[164:167], v[194:197], v[126:129]
	v_mfma_f32_16x16x32_bf16 v[126:129], v[182:185], v[198:201], v[126:129]
	v_mfma_f32_16x16x32_bf16 v[122:125], v[186:189], v[194:197], v[122:125]
	v_mfma_f32_16x16x32_bf16 v[122:125], v[190:193], v[198:201], v[122:125]
	v_mfma_f32_16x16x32_bf16 v[118:121], v[164:167], v[202:205], v[118:121]
	v_mfma_f32_16x16x32_bf16 v[118:121], v[182:185], v[206:209], v[118:121]
	v_mfma_f32_16x16x32_bf16 v[110:113], v[186:189], v[202:205], v[110:113]
	v_mfma_f32_16x16x32_bf16 v[110:113], v[190:193], v[206:209], v[110:113]
	v_mfma_f32_16x16x32_bf16 v[102:105], v[164:167], v[210:213], v[102:105]
	v_mfma_f32_16x16x32_bf16 v[102:105], v[182:185], v[214:217], v[102:105]
	v_mfma_f32_16x16x32_bf16 v[94:97], v[186:189], v[210:213], v[94:97]
	v_mfma_f32_16x16x32_bf16 v[94:97], v[190:193], v[214:217], v[94:97]
	v_mfma_f32_16x16x32_bf16 v[86:89], v[164:167], v[218:221], v[86:89]
	v_mfma_f32_16x16x32_bf16 v[86:89], v[182:185], v[222:225], v[86:89]
	v_mfma_f32_16x16x32_bf16 v[78:81], v[186:189], v[218:221], v[78:81]
	s_barrier
	v_mfma_f32_16x16x32_bf16 v[78:81], v[190:193], v[222:225], v[78:81]
	s_setprio 0
	s_add_i32 s51, 0, 0x14000
	s_add_i32 s24, s39, s86
	ds_read_b128 v[226:229], v249 offset:16384
	ds_read_b128 v[230:233], v249 offset:17408
	ds_read_b128 v[234:237], v249 offset:18432
	ds_read_b128 v[238:241], v249 offset:19456
	s_mov_b32 m0, s24
	global_load_lds_dwordx4 v134, s[36:37]
	s_add_i32 m0, s24, 0x2000
	s_nop 0
	global_load_lds_dwordx4 v130, s[36:37]
	s_barrier
; #define PG8_STAGE(bufoff, gbase, voff) do { _Pragma("unroll") for (int _i = 0; _i < 2; ++_i) \
;         __builtin_amdgcn_global_load_lds((const unsigned*)((const char*)(gbase) + (voff)[_i]), (LAS unsigned*)(lds + (bufoff) + ldsw + _i * 8192), 16, 0, 0); } while (0)
; #define PG8_LDA(dst, b, h) do { _Pragma("unroll") for (int m = 0; m < 4; ++m) _Pragma("unroll") for (int k = 0; k < 2; ++k) dst[m][k] = *(const LAS bf16x8*)(lds + PG8_SA(b, h) + aoff + m * 2048 + k * 1024); } while (0)
; #define PG8_LDB(dst, b, h) do { _Pragma("unroll") for (int n = 0; n < 2; ++n) _Pragma("unroll") for (int k = 0; k < 2; ++k) dst[n][k] = *(const LAS bf16x8*)(lds + PG8_SB(b, h) + boff + n * 2048 + k * 1024); } while (0)
; #define PG8_MMA(ai, bj, At, Bt) do { __builtin_amdgcn_s_setprio(1); _Pragma("unroll") for (int m = 0; m < 4; ++m) _Pragma("unroll") for (int n = 0; n < 2; ++n) _Pragma("unroll") for (int k = 0; k < 2; ++k) \
;         acc[ai][bj][m][n] = __builtin_amdgcn_mfma_f32_16x16x32_bf16(Bt[n][k], At[m][k], acc[ai][bj][m][n], 0, 0, 0); __builtin_amdgcn_s_setprio(0); } while (0)
; #define PG8_WAIT_V(n) asm volatile("s_waitcnt vmcnt(" #n ")" ::: "memory")
; #define PG8_WAIT_L(n) asm volatile("s_waitcnt lgkmcnt(" #n ")" ::: "memory")
; #define PG8_BAR __builtin_amdgcn_s_barrier()
; #define PG8_SCHED __builtin_amdgcn_sched_barrier(0)
; template <class Epi, class Sched>
; __device__ __forceinline__ void gemm_phase(LAS unsigned char* lds, const Gemm g, const Sched& S, const Epi& E) {
;     ...
;             PG8_BAR; PG8_WAIT_L(0); PG8_MMA(0, 1, At, B1); PG8_BAR;
;             PG8_LDA(At, 0, 1); PG8_STAGE(PG8_SA(0, 0), a2, voffA);
;             PG8_BAR; PG8_WAIT_L(0); PG8_MMA(1, 0, At, B0); PG8_BAR; PG8_SCHED;
;             PG8_STAGE(PG8_SB(0, 1), b2 + hstep, voffB);
;             PG8_WAIT_V(6); PG8_BAR; PG8_MMA(1, 1, At, B1); PG8_BAR;
;             PG8_LDB(B0, 1, 0); PG8_SCHED; PG8_LDA(At, 1, 0); PG8_STAGE(PG8_SA(0, 1), a2 + hstep, voffA);
;             PG8_WAIT_L(8); PG8_BAR; PG8_WAIT_L(0); PG8_MMA(0, 0, At, B0); PG8_BAR; PG8_SCHED;
	s_waitcnt lgkmcnt(0)
	s_setprio 1
	s_waitcnt lgkmcnt(0)
	v_mfma_f32_16x16x32_bf16 v[114:117], v[226:229], v[194:197], v[114:117]
	v_mfma_f32_16x16x32_bf16 v[114:117], v[230:233], v[198:201], v[114:117]
	v_mfma_f32_16x16x32_bf16 v[106:109], v[234:237], v[194:197], v[106:109]
	v_mfma_f32_16x16x32_bf16 v[106:109], v[238:241], v[198:201], v[106:109]
	v_mfma_f32_16x16x32_bf16 v[98:101], v[226:229], v[202:205], v[98:101]
	v_mfma_f32_16x16x32_bf16 v[98:101], v[230:233], v[206:209], v[98:101]
	v_mfma_f32_16x16x32_bf16 v[90:93], v[234:237], v[202:205], v[90:93]
	v_mfma_f32_16x16x32_bf16 v[90:93], v[238:241], v[206:209], v[90:93]
	v_mfma_f32_16x16x32_bf16 v[82:85], v[226:229], v[210:213], v[82:85]
	v_mfma_f32_16x16x32_bf16 v[82:85], v[230:233], v[214:217], v[82:85]
	v_mfma_f32_16x16x32_bf16 v[74:77], v[234:237], v[210:213], v[74:77]
	v_mfma_f32_16x16x32_bf16 v[74:77], v[238:241], v[214:217], v[74:77]
	v_mfma_f32_16x16x32_bf16 v[70:73], v[226:229], v[218:221], v[70:73]
	v_mfma_f32_16x16x32_bf16 v[70:73], v[230:233], v[222:225], v[70:73]
	v_mfma_f32_16x16x32_bf16 v[66:69], v[234:237], v[218:221], v[66:69]
	s_barrier
	v_mfma_f32_16x16x32_bf16 v[66:69], v[238:241], v[222:225], v[66:69]
	s_setprio 0
	s_mov_b32 m0, s93
	ds_read_b128 v[194:197], v162 offset:16384
	ds_read_b128 v[198:201], v162 offset:17408
	ds_read_b128 v[202:205], v162 offset:18432
	ds_read_b128 v[206:209], v162 offset:19456
	ds_read_b128 v[210:213], v162 offset:20480
	ds_read_b128 v[214:217], v162 offset:21504
	ds_read_b128 v[218:221], v162 offset:22528
	ds_read_b128 v[222:225], v162 offset:23552
	global_load_lds_dwordx4 v136, vcc
	s_mov_b32 m0, s94
	s_nop 0
	global_load_lds_dwordx4 v132, vcc
	s_waitcnt vmcnt(8)
	s_barrier
	s_waitcnt lgkmcnt(0)
	s_setprio 1
	s_waitcnt lgkmcnt(0)
	v_mfma_f32_16x16x32_bf16 v[62:65], v[164:167], v[194:197], v[62:65]
	v_mfma_f32_16x16x32_bf16 v[62:65], v[182:185], v[198:201], v[62:65]
	v_mfma_f32_16x16x32_bf16 v[58:61], v[186:189], v[194:197], v[58:61]
	v_mfma_f32_16x16x32_bf16 v[58:61], v[190:193], v[198:201], v[58:61]
	v_mfma_f32_16x16x32_bf16 v[54:57], v[164:167], v[202:205], v[54:57]
	v_mfma_f32_16x16x32_bf16 v[54:57], v[182:185], v[206:209], v[54:57]
	v_mfma_f32_16x16x32_bf16 v[46:49], v[186:189], v[202:205], v[46:49]
	v_mfma_f32_16x16x32_bf16 v[46:49], v[190:193], v[206:209], v[46:49]
	v_mfma_f32_16x16x32_bf16 v[38:41], v[164:167], v[210:213], v[38:41]
	v_mfma_f32_16x16x32_bf16 v[38:41], v[182:185], v[214:217], v[38:41]
	v_mfma_f32_16x16x32_bf16 v[30:33], v[186:189], v[210:213], v[30:33]
	v_mfma_f32_16x16x32_bf16 v[30:33], v[190:193], v[214:217], v[30:33]
	v_mfma_f32_16x16x32_bf16 v[22:25], v[164:167], v[218:221], v[22:25]
	v_mfma_f32_16x16x32_bf16 v[22:25], v[182:185], v[222:225], v[22:25]
	v_mfma_f32_16x16x32_bf16 v[14:17], v[186:189], v[218:221], v[14:17]
	s_barrier
	v_mfma_f32_16x16x32_bf16 v[14:17], v[190:193], v[222:225], v[14:17]
	s_setprio 0
	s_add_u32 s24, s36, 0x40000
	s_addc_u32 s25, s37, 0
	s_add_i32 s39, s51, s86
	s_mov_b32 m0, s39
	s_nop 0
	global_load_lds_dwordx4 v134, s[24:25]
	s_add_i32 m0, s39, 0x2000
	s_nop 0
	global_load_lds_dwordx4 v130, s[24:25]
	s_waitcnt vmcnt(6)
	s_barrier
	s_setprio 1
	v_mfma_f32_16x16x32_bf16 v[50:53], v[226:229], v[194:197], v[50:53]
	ds_read_b128 v[164:167], v249 offset:32768
	ds_read_b128 v[182:185], v249 offset:33792
	v_mfma_f32_16x16x32_bf16 v[50:53], v[230:233], v[198:201], v[50:53]
	ds_read_b128 v[186:189], v249 offset:34816
	ds_read_b128 v[190:193], v249 offset:35840
	v_mfma_f32_16x16x32_bf16 v[42:45], v[234:237], v[194:197], v[42:45]
	ds_read_b128 v[194:197], v162 offset:32768
	v_mfma_f32_16x16x32_bf16 v[42:45], v[238:241], v[198:201], v[42:45]
	ds_read_b128 v[198:201], v162 offset:33792
	v_mfma_f32_16x16x32_bf16 v[34:37], v[226:229], v[202:205], v[34:37]
	v_mfma_f32_16x16x32_bf16 v[34:37], v[230:233], v[206:209], v[34:37]
	v_mfma_f32_16x16x32_bf16 v[26:29], v[234:237], v[202:205], v[26:29]
	ds_read_b128 v[202:205], v162 offset:34816
	v_mfma_f32_16x16x32_bf16 v[26:29], v[238:241], v[206:209], v[26:29]
	ds_read_b128 v[206:209], v162 offset:35840
	v_mfma_f32_16x16x32_bf16 v[18:21], v[226:229], v[210:213], v[18:21]
	v_mfma_f32_16x16x32_bf16 v[18:21], v[230:233], v[214:217], v[18:21]
	v_mfma_f32_16x16x32_bf16 v[10:13], v[234:237], v[210:213], v[10:13]
	ds_read_b128 v[210:213], v162 offset:36864
	v_mfma_f32_16x16x32_bf16 v[10:13], v[238:241], v[214:217], v[10:13]
	ds_read_b128 v[214:217], v162 offset:37888
	v_mfma_f32_16x16x32_bf16 v[6:9], v[226:229], v[218:221], v[6:9]
	v_mfma_f32_16x16x32_bf16 v[6:9], v[230:233], v[222:225], v[6:9]
	v_mfma_f32_16x16x32_bf16 v[2:5], v[234:237], v[218:221], v[2:5]
	ds_read_b128 v[218:221], v162 offset:38912
	s_barrier
	v_mfma_f32_16x16x32_bf16 v[2:5], v[238:241], v[222:225], v[2:5]
	s_setprio 0
	s_add_i32 s39, 0, 0x18000
	s_add_u32 s24, vcc_lo, 0x40000
	s_addc_u32 s25, vcc_hi, 0
	s_mov_b32 m0, s95
	ds_read_b128 v[222:225], v162 offset:39936
	global_load_lds_dwordx4 v136, s[24:25]
	s_mov_b32 m0, s96
	s_nop 0
	global_load_lds_dwordx4 v132, s[24:25]
	s_waitcnt lgkmcnt(8)
	s_barrier
	s_waitcnt lgkmcnt(0)
	s_setprio 1
	s_waitcnt lgkmcnt(0)
	v_mfma_f32_16x16x32_bf16 v[126:129], v[164:167], v[194:197], v[126:129]
	v_mfma_f32_16x16x32_bf16 v[126:129], v[182:185], v[198:201], v[126:129]
	v_mfma_f32_16x16x32_bf16 v[122:125], v[186:189], v[194:197], v[122:125]
	v_mfma_f32_16x16x32_bf16 v[122:125], v[190:193], v[198:201], v[122:125]
	v_mfma_f32_16x16x32_bf16 v[118:121], v[164:167], v[202:205], v[118:121]
	v_mfma_f32_16x16x32_bf16 v[118:121], v[182:185], v[206:209], v[118:121]
	v_mfma_f32_16x16x32_bf16 v[110:113], v[186:189], v[202:205], v[110:113]
	v_mfma_f32_16x16x32_bf16 v[110:113], v[190:193], v[206:209], v[110:113]
	v_mfma_f32_16x16x32_bf16 v[102:105], v[164:167], v[210:213], v[102:105]
	v_mfma_f32_16x16x32_bf16 v[102:105], v[182:185], v[214:217], v[102:105]
	v_mfma_f32_16x16x32_bf16 v[94:97], v[186:189], v[210:213], v[94:97]
	v_mfma_f32_16x16x32_bf16 v[94:97], v[190:193], v[214:217], v[94:97]
	v_mfma_f32_16x16x32_bf16 v[86:89], v[164:167], v[218:221], v[86:89]
	v_mfma_f32_16x16x32_bf16 v[86:89], v[182:185], v[222:225], v[86:89]
	v_mfma_f32_16x16x32_bf16 v[78:81], v[186:189], v[218:221], v[78:81]
	s_barrier
; #define PG8_STAGE(bufoff, gbase, voff) do { _Pragma("unroll") for (int _i = 0; _i < 2; ++_i) \
;         __builtin_amdgcn_global_load_lds((const unsigned*)((const char*)(gbase) + (voff)[_i]), (LAS unsigned*)(lds + (bufoff) + ldsw + _i * 8192), 16, 0, 0); } while (0)
; #define PG8_LDA(dst, b, h) do { _Pragma("unroll") for (int m = 0; m < 4; ++m) _Pragma("unroll") for (int k = 0; k < 2; ++k) dst[m][k] = *(const LAS bf16x8*)(lds + PG8_SA(b, h) + aoff + m * 2048 + k * 1024); } while (0)
; #define PG8_LDB(dst, b, h) do { _Pragma("unroll") for (int n = 0; n < 2; ++n) _Pragma("unroll") for (int k = 0; k < 2; ++k) dst[n][k] = *(const LAS bf16x8*)(lds + PG8_SB(b, h) + boff + n * 2048 + k * 1024); } while (0)
; #define PG8_MMA(ai, bj, At, Bt) do { __builtin_amdgcn_s_setprio(1); _Pragma("unroll") for (int m = 0; m < 4; ++m) _Pragma("unroll") for (int n = 0; n < 2; ++n) _Pragma("unroll") for (int k = 0; k < 2; ++k) \
;         acc[ai][bj][m][n] = __builtin_amdgcn_mfma_f32_16x16x32_bf16(Bt[n][k], At[m][k], acc[ai][bj][m][n], 0, 0, 0); __builtin_amdgcn_s_setprio(0); } while (0)
; #define PG8_WAIT_V(n) asm volatile("s_waitcnt vmcnt(" #n ")" ::: "memory")
; #define PG8_WAIT_L(n) asm volatile("s_waitcnt lgkmcnt(" #n ")" ::: "memory")
; #define PG8_BAR __builtin_amdgcn_s_barrier()
; #define PG8_SCHED __builtin_amdgcn_sched_barrier(0)
; template <class Epi, class Sched>
; __device__ __forceinline__ void gemm_phase(LAS unsigned char* lds, const Gemm g, const Sched& S, const Epi& E) {
;     ...
;             PG8_WAIT_L(8); PG8_BAR; PG8_WAIT_L(0); PG8_MMA(0, 0, At, B0); PG8_BAR; PG8_SCHED;
;             PG8_LDB(B1, 1, 1); PG8_STAGE(PG8_SB(1, 0), b3, voffB);
;             PG8_BAR; PG8_WAIT_L(0); PG8_MMA(0, 1, At, B1); PG8_BAR;
;             PG8_LDA(At, 1, 1); PG8_STAGE(PG8_SA(1, 0), a3, voffA);
;             PG8_BAR; PG8_WAIT_L(0); PG8_MMA(1, 0, At, B0); PG8_BAR; PG8_SCHED;
;             PG8_STAGE(PG8_SB(1, 1), b3 + hstep, voffB);
;             PG8_WAIT_V(6); PG8_BAR; PG8_MMA(1, 1, At, B1); PG8_BAR;
;         }
;         if (wr == 0) PG8_BAR;
	v_mfma_f32_16x16x32_bf16 v[78:81], v[190:193], v[222:225], v[78:81]
	s_setprio 0
	s_add_i32 s51, 0, 0x1c000
	s_add_i32 s24, s39, s86
	s_add_i32 m0, s24, 0xffffff80
	ds_read_b128 v[226:229], v249 offset:49152
	ds_read_b128 v[230:233], v249 offset:50176
	ds_read_b128 v[234:237], v249 offset:51200
	ds_read_b128 v[238:241], v249 offset:52224
	global_load_lds_dwordx4 v134, s[36:37] offset:128
	s_add_i32 m0, s24, 0x1f80
	s_nop 0
	global_load_lds_dwordx4 v130, s[36:37] offset:128
	s_barrier
	s_waitcnt lgkmcnt(0)
	s_setprio 1
	s_waitcnt lgkmcnt(0)
	v_mfma_f32_16x16x32_bf16 v[114:117], v[226:229], v[194:197], v[114:117]
	v_mfma_f32_16x16x32_bf16 v[114:117], v[230:233], v[198:201], v[114:117]
	v_mfma_f32_16x16x32_bf16 v[106:109], v[234:237], v[194:197], v[106:109]
	v_mfma_f32_16x16x32_bf16 v[106:109], v[238:241], v[198:201], v[106:109]
	v_mfma_f32_16x16x32_bf16 v[98:101], v[226:229], v[202:205], v[98:101]
	v_mfma_f32_16x16x32_bf16 v[98:101], v[230:233], v[206:209], v[98:101]
	v_mfma_f32_16x16x32_bf16 v[90:93], v[234:237], v[202:205], v[90:93]
	v_mfma_f32_16x16x32_bf16 v[90:93], v[238:241], v[206:209], v[90:93]
	v_mfma_f32_16x16x32_bf16 v[82:85], v[226:229], v[210:213], v[82:85]
	v_mfma_f32_16x16x32_bf16 v[82:85], v[230:233], v[214:217], v[82:85]
	v_mfma_f32_16x16x32_bf16 v[74:77], v[234:237], v[210:213], v[74:77]
	v_mfma_f32_16x16x32_bf16 v[74:77], v[238:241], v[214:217], v[74:77]
	v_mfma_f32_16x16x32_bf16 v[70:73], v[226:229], v[218:221], v[70:73]
	v_mfma_f32_16x16x32_bf16 v[70:73], v[230:233], v[222:225], v[70:73]
	v_mfma_f32_16x16x32_bf16 v[66:69], v[234:237], v[218:221], v[66:69]
	s_barrier
	v_mfma_f32_16x16x32_bf16 v[66:69], v[238:241], v[222:225], v[66:69]
	s_setprio 0
	s_add_i32 m0, s97, 0xffffff80
	ds_read_b128 v[194:197], v162 offset:49152
	ds_read_b128 v[198:201], v162 offset:50176
	ds_read_b128 v[202:205], v162 offset:51200
	ds_read_b128 v[206:209], v162 offset:52224
	ds_read_b128 v[210:213], v162 offset:53248
	ds_read_b128 v[214:217], v162 offset:54272
	ds_read_b128 v[218:221], v162 offset:55296
	ds_read_b128 v[222:225], v162 offset:56320
	global_load_lds_dwordx4 v136, vcc offset:128
	s_add_i32 m0, s98, 0xffffff80
	s_nop 0
	global_load_lds_dwordx4 v132, vcc offset:128
	s_waitcnt vmcnt(8)
	s_barrier
	s_waitcnt lgkmcnt(0)
	s_setprio 1
	s_waitcnt lgkmcnt(0)
	v_mfma_f32_16x16x32_bf16 v[62:65], v[164:167], v[194:197], v[62:65]
	v_mfma_f32_16x16x32_bf16 v[62:65], v[182:185], v[198:201], v[62:65]
	v_mfma_f32_16x16x32_bf16 v[58:61], v[186:189], v[194:197], v[58:61]
	v_mfma_f32_16x16x32_bf16 v[58:61], v[190:193], v[198:201], v[58:61]
	v_mfma_f32_16x16x32_bf16 v[54:57], v[164:167], v[202:205], v[54:57]
	v_mfma_f32_16x16x32_bf16 v[54:57], v[182:185], v[206:209], v[54:57]
	v_mfma_f32_16x16x32_bf16 v[46:49], v[186:189], v[202:205], v[46:49]
	v_mfma_f32_16x16x32_bf16 v[46:49], v[190:193], v[206:209], v[46:49]
	v_mfma_f32_16x16x32_bf16 v[38:41], v[164:167], v[210:213], v[38:41]
	v_mfma_f32_16x16x32_bf16 v[38:41], v[182:185], v[214:217], v[38:41]
	v_mfma_f32_16x16x32_bf16 v[30:33], v[186:189], v[210:213], v[30:33]
	v_mfma_f32_16x16x32_bf16 v[30:33], v[190:193], v[214:217], v[30:33]
	v_mfma_f32_16x16x32_bf16 v[22:25], v[164:167], v[218:221], v[22:25]
	v_mfma_f32_16x16x32_bf16 v[22:25], v[182:185], v[222:225], v[22:25]
	v_mfma_f32_16x16x32_bf16 v[14:17], v[186:189], v[218:221], v[14:17]
	s_barrier
	v_mfma_f32_16x16x32_bf16 v[14:17], v[190:193], v[222:225], v[14:17]
	s_setprio 0
	s_add_u32 s24, s36, 0x40080
	s_addc_u32 s25, s37, 0
	s_add_i32 s36, s51, s86
	s_mov_b32 m0, s36
	s_nop 0
	global_load_lds_dwordx4 v134, s[24:25]
	s_add_i32 m0, s36, 0x2000
	s_nop 0
	global_load_lds_dwordx4 v130, s[24:25]
	s_waitcnt vmcnt(6)
	s_barrier
	s_setprio 1
	v_mfma_f32_16x16x32_bf16 v[50:53], v[226:229], v[194:197], v[50:53]
	ds_read_b128 v[164:167], v249
	ds_read_b128 v[182:185], v249 offset:1024
	v_mfma_f32_16x16x32_bf16 v[50:53], v[230:233], v[198:201], v[50:53]
	ds_read_b128 v[186:189], v249 offset:2048
	ds_read_b128 v[190:193], v249 offset:3072
	v_mfma_f32_16x16x32_bf16 v[42:45], v[234:237], v[194:197], v[42:45]
	ds_read_b128 v[194:197], v162
	v_mfma_f32_16x16x32_bf16 v[42:45], v[238:241], v[198:201], v[42:45]
	ds_read_b128 v[198:201], v162 offset:1024
	v_mfma_f32_16x16x32_bf16 v[34:37], v[226:229], v[202:205], v[34:37]
	v_mfma_f32_16x16x32_bf16 v[34:37], v[230:233], v[206:209], v[34:37]
	v_mfma_f32_16x16x32_bf16 v[26:29], v[234:237], v[202:205], v[26:29]
	ds_read_b128 v[202:205], v162 offset:2048
	v_mfma_f32_16x16x32_bf16 v[26:29], v[238:241], v[206:209], v[26:29]
	ds_read_b128 v[206:209], v162 offset:3072
	v_mfma_f32_16x16x32_bf16 v[18:21], v[226:229], v[210:213], v[18:21]
	v_mfma_f32_16x16x32_bf16 v[18:21], v[230:233], v[214:217], v[18:21]
	v_mfma_f32_16x16x32_bf16 v[10:13], v[234:237], v[210:213], v[10:13]
	ds_read_b128 v[210:213], v162 offset:4096
	v_mfma_f32_16x16x32_bf16 v[10:13], v[238:241], v[214:217], v[10:13]
	ds_read_b128 v[214:217], v162 offset:5120
	v_mfma_f32_16x16x32_bf16 v[6:9], v[226:229], v[218:221], v[6:9]
	v_mfma_f32_16x16x32_bf16 v[6:9], v[230:233], v[222:225], v[6:9]
	v_mfma_f32_16x16x32_bf16 v[2:5], v[234:237], v[218:221], v[2:5]
	ds_read_b128 v[218:221], v162 offset:6144
	s_barrier
	v_mfma_f32_16x16x32_bf16 v[2:5], v[238:241], v[222:225], v[2:5]
	s_setprio 0
	s_add_i32 s38, s38, 2
	s_add_u32 s35, s35, 0x100
	s_addc_u32 s50, s50, 0
	s_add_u32 s0, s0, 0x100
	s_addc_u32 s1, s1, 0
	s_cmp_gt_u32 s38, 13
	s_cbranch_scc0 .LBB0_416
	s_waitcnt lgkmcnt(0)
	s_and_b64 vcc, exec, s[44:45]
	s_cbranch_vccz .LBB0_419
	s_barrier

; #define PG8_STAGE(bufoff, gbase, voff) do { _Pragma("unroll") for (int _i = 0; _i < 2; ++_i) \
;         __builtin_amdgcn_global_load_lds((const unsigned*)((const char*)(gbase) + (voff)[_i]), (LAS unsigned*)(lds + (bufoff) + ldsw + _i * 8192), 16, 0, 0); } while (0)
; #define PG8_LDA(dst, b, h) do { _Pragma("unroll") for (int m = 0; m < 4; ++m) _Pragma("unroll") for (int k = 0; k < 2; ++k) dst[m][k] = *(const LAS bf16x8*)(lds + PG8_SA(b, h) + aoff + m * 2048 + k * 1024); } while (0)
; #define PG8_LDB(dst, b, h) do { _Pragma("unroll") for (int n = 0; n < 2; ++n) _Pragma("unroll") for (int k = 0; k < 2; ++k) dst[n][k] = *(const LAS bf16x8*)(lds + PG8_SB(b, h) + boff + n * 2048 + k * 1024); } while (0)
; #define PG8_MMA(ai, bj, At, Bt) do { __builtin_amdgcn_s_setprio(1); _Pragma("unroll") for (int m = 0; m < 4; ++m) _Pragma("unroll") for (int n = 0; n < 2; ++n) _Pragma("unroll") for (int k = 0; k < 2; ++k) \
;         acc[ai][bj][m][n] = __builtin_amdgcn_mfma_f32_16x16x32_bf16(Bt[n][k], At[m][k], acc[ai][bj][m][n], 0, 0, 0); __builtin_amdgcn_s_setprio(0); } while (0)
; #define PG8_WAIT_L(n) asm volatile("s_waitcnt lgkmcnt(" #n ")" ::: "memory")
; template <class Epi, class Sched>
; __device__ __forceinline__ void gemm_phase(LAS unsigned char* lds, const Gemm g, const Sched& S, const Epi& E) {
;     ...
;         const bool has_next = S.next(ui + 1, nxt);
;         const char* nA = has_next ? PG8_APANEL(nxt.pm) : cA; const char* nB = has_next ? (const char*)g.Bt + (size_t)nxt.pn * tstep : cB;
;         for (int t = 0; t < nt; t += 2) {
;             const bool last = (t == nt - 2);
;             const char* a1 = cA + (size_t)(t + 1) * kstep;
;             const char* a2 = last ? nA : cA + (size_t)(t + 2) * kstep; const char* b2 = last ? nB : cB + (size_t)(t + 2) * kstep;
;             const char* a3 = a2 + kstep; const char* b3 = b2 + kstep;
;             PG8_LDB(B0, 0, 0); PG8_SCHED; PG8_LDA(At, 0, 0); PG8_STAGE(PG8_SA(1, 1), a1 + hstep, voffA);
;             PG8_WAIT_L(8); PG8_BAR; PG8_WAIT_L(0); PG8_MMA(0, 0, At, B0); PG8_BAR; PG8_SCHED;
;             PG8_LDB(B1, 0, 1); PG8_STAGE(PG8_SB(0, 0), b2, voffB);
;             PG8_BAR; PG8_WAIT_L(0); PG8_MMA(0, 1, At, B1); PG8_BAR;
;             PG8_LDA(At, 0, 1); PG8_STAGE(PG8_SA(0, 0), a2, voffA);
;             PG8_BAR; PG8_WAIT_L(0); PG8_MMA(1, 0, At, B0); PG8_BAR; PG8_SCHED;
.LBB0_556:
	s_ashr_i32 s45, s44, 31
	s_lshl_b64 s[24:25], s[44:45], 19
	s_add_u32 s60, s86, s24
	s_addc_u32 s61, s93, s25
	s_and_b64 s[0:1], s[0:1], exec
	s_cselect_b32 s45, s61, s49
	s_cselect_b32 s47, s60, s48
	s_add_u32 s35, s48, 0x100
	s_addc_u32 s50, s49, 0
	s_add_u32 s0, s38, 0x40080
	s_addc_u32 s1, s39, 0
	s_mov_b32 s38, -2
	v_add_u32_e32 v249, 0x10000, v164
	ds_read_b128 v[142:145], v249
	ds_read_b128 v[182:185], v249 offset:1024
	ds_read_b128 v[186:189], v249 offset:2048
	ds_read_b128 v[190:193], v249 offset:3072
	ds_read_b128 v[194:197], v166
	ds_read_b128 v[198:201], v166 offset:1024
	ds_read_b128 v[202:205], v166 offset:2048
	ds_read_b128 v[206:209], v166 offset:3072
	ds_read_b128 v[210:213], v166 offset:4096
	ds_read_b128 v[214:217], v166 offset:5120
	ds_read_b128 v[218:221], v166 offset:6144
	s_add_u32 s24, s0, 0xfffc0080
	s_addc_u32 s25, s1, -1
	s_add_i32 s39, 0, 0x10000
	s_cmp_eq_u32 s38, 12
	s_cselect_b32 vcc_hi, s77, s25
	s_cselect_b32 vcc_lo, s76, s24
	s_cselect_b32 s49, s45, s50
	s_cselect_b32 s48, s47, s35
	s_add_i32 m0, s95, 0xc000
	ds_read_b128 v[222:225], v166 offset:7168
	global_load_lds_dwordx4 v140, s[0:1]
	s_add_i32 m0, s95, 0xe000
	s_nop 0
	global_load_lds_dwordx4 v138, s[0:1]
	s_waitcnt lgkmcnt(8)
	s_barrier
	s_waitcnt lgkmcnt(0)
	s_setprio 1
	s_waitcnt lgkmcnt(0)
	v_mfma_f32_16x16x32_bf16 v[126:129], v[142:145], v[194:197], 0
	v_mfma_f32_16x16x32_bf16 v[126:129], v[182:185], v[198:201], v[126:129]
	v_mfma_f32_16x16x32_bf16 v[122:125], v[186:189], v[194:197], 0
	v_mfma_f32_16x16x32_bf16 v[122:125], v[190:193], v[198:201], v[122:125]
	v_mfma_f32_16x16x32_bf16 v[110:113], v[142:145], v[202:205], 0
	v_mfma_f32_16x16x32_bf16 v[110:113], v[182:185], v[206:209], v[110:113]
	v_mfma_f32_16x16x32_bf16 v[106:109], v[186:189], v[202:205], 0
	v_mfma_f32_16x16x32_bf16 v[106:109], v[190:193], v[206:209], v[106:109]
	v_mfma_f32_16x16x32_bf16 v[94:97], v[142:145], v[210:213], 0
	v_mfma_f32_16x16x32_bf16 v[94:97], v[182:185], v[214:217], v[94:97]
	v_mfma_f32_16x16x32_bf16 v[90:93], v[186:189], v[210:213], 0
	v_mfma_f32_16x16x32_bf16 v[90:93], v[190:193], v[214:217], v[90:93]
	v_mfma_f32_16x16x32_bf16 v[78:81], v[142:145], v[218:221], 0
	v_mfma_f32_16x16x32_bf16 v[78:81], v[182:185], v[222:225], v[78:81]
	v_mfma_f32_16x16x32_bf16 v[74:77], v[186:189], v[218:221], 0
	s_barrier
	v_mfma_f32_16x16x32_bf16 v[74:77], v[190:193], v[222:225], v[74:77]
	s_setprio 0
	s_add_i32 s51, 0, 0x14000
	s_add_i32 s24, s39, s94
	ds_read_b128 v[226:229], v249 offset:16384
	ds_read_b128 v[230:233], v249 offset:17408
	ds_read_b128 v[234:237], v249 offset:18432
	ds_read_b128 v[238:241], v249 offset:19456
	s_mov_b32 m0, s24
	global_load_lds_dwordx4 v134, s[48:49]
	s_add_i32 m0, s24, 0x2000
	s_nop 0
	global_load_lds_dwordx4 v130, s[48:49]
	s_barrier
	s_waitcnt lgkmcnt(0)
	s_setprio 1
	s_waitcnt lgkmcnt(0)
	v_mfma_f32_16x16x32_bf16 v[118:121], v[226:229], v[194:197], 0
	v_mfma_f32_16x16x32_bf16 v[118:121], v[230:233], v[198:201], v[118:121]
	v_mfma_f32_16x16x32_bf16 v[114:117], v[234:237], v[194:197], 0
	v_mfma_f32_16x16x32_bf16 v[114:117], v[238:241], v[198:201], v[114:117]
	v_mfma_f32_16x16x32_bf16 v[102:105], v[226:229], v[202:205], 0
	v_mfma_f32_16x16x32_bf16 v[102:105], v[230:233], v[206:209], v[102:105]
	v_mfma_f32_16x16x32_bf16 v[98:101], v[234:237], v[202:205], 0
	v_mfma_f32_16x16x32_bf16 v[98:101], v[238:241], v[206:209], v[98:101]
	v_mfma_f32_16x16x32_bf16 v[86:89], v[226:229], v[210:213], 0
	v_mfma_f32_16x16x32_bf16 v[86:89], v[230:233], v[214:217], v[86:89]
	v_mfma_f32_16x16x32_bf16 v[82:85], v[234:237], v[210:213], 0
	v_mfma_f32_16x16x32_bf16 v[82:85], v[238:241], v[214:217], v[82:85]
	v_mfma_f32_16x16x32_bf16 v[70:73], v[226:229], v[218:221], 0
	v_mfma_f32_16x16x32_bf16 v[70:73], v[230:233], v[222:225], v[70:73]
	v_mfma_f32_16x16x32_bf16 v[66:69], v[234:237], v[218:221], 0
	s_barrier
	v_mfma_f32_16x16x32_bf16 v[66:69], v[238:241], v[222:225], v[66:69]
	s_setprio 0
	s_mov_b32 m0, s95
	ds_read_b128 v[194:197], v166 offset:16384
	ds_read_b128 v[198:201], v166 offset:17408
	ds_read_b128 v[202:205], v166 offset:18432
	ds_read_b128 v[206:209], v166 offset:19456
	ds_read_b128 v[210:213], v166 offset:20480
	ds_read_b128 v[214:217], v166 offset:21504
	ds_read_b128 v[218:221], v166 offset:22528
	ds_read_b128 v[222:225], v166 offset:23552
	global_load_lds_dwordx4 v136, vcc
	s_mov_b32 m0, s96
	s_nop 0
	global_load_lds_dwordx4 v132, vcc
	s_waitcnt vmcnt(8)
	s_barrier
	s_waitcnt lgkmcnt(0)
	s_setprio 1
	s_waitcnt lgkmcnt(0)
	v_mfma_f32_16x16x32_bf16 v[62:65], v[142:145], v[194:197], 0
	v_mfma_f32_16x16x32_bf16 v[62:65], v[182:185], v[198:201], v[62:65]
	v_mfma_f32_16x16x32_bf16 v[58:61], v[186:189], v[194:197], 0
	v_mfma_f32_16x16x32_bf16 v[58:61], v[190:193], v[198:201], v[58:61]
	v_mfma_f32_16x16x32_bf16 v[46:49], v[142:145], v[202:205], 0
	v_mfma_f32_16x16x32_bf16 v[46:49], v[182:185], v[206:209], v[46:49]
	v_mfma_f32_16x16x32_bf16 v[42:45], v[186:189], v[202:205], 0
	v_mfma_f32_16x16x32_bf16 v[42:45], v[190:193], v[206:209], v[42:45]
	v_mfma_f32_16x16x32_bf16 v[30:33], v[142:145], v[210:213], 0
	v_mfma_f32_16x16x32_bf16 v[30:33], v[182:185], v[214:217], v[30:33]
	v_mfma_f32_16x16x32_bf16 v[26:29], v[186:189], v[210:213], 0
	v_mfma_f32_16x16x32_bf16 v[26:29], v[190:193], v[214:217], v[26:29]
	v_mfma_f32_16x16x32_bf16 v[14:17], v[142:145], v[218:221], 0
	v_mfma_f32_16x16x32_bf16 v[14:17], v[182:185], v[222:225], v[14:17]
	v_mfma_f32_16x16x32_bf16 v[10:13], v[186:189], v[218:221], 0
	s_barrier
; #define PG8_STAGE(bufoff, gbase, voff) do { _Pragma("unroll") for (int _i = 0; _i < 2; ++_i) \
;         __builtin_amdgcn_global_load_lds((const unsigned*)((const char*)(gbase) + (voff)[_i]), (LAS unsigned*)(lds + (bufoff) + ldsw + _i * 8192), 16, 0, 0); } while (0)
; #define PG8_LDA(dst, b, h) do { _Pragma("unroll") for (int m = 0; m < 4; ++m) _Pragma("unroll") for (int k = 0; k < 2; ++k) dst[m][k] = *(const LAS bf16x8*)(lds + PG8_SA(b, h) + aoff + m * 2048 + k * 1024); } while (0)
; #define PG8_LDB(dst, b, h) do { _Pragma("unroll") for (int n = 0; n < 2; ++n) _Pragma("unroll") for (int k = 0; k < 2; ++k) dst[n][k] = *(const LAS bf16x8*)(lds + PG8_SB(b, h) + boff + n * 2048 + k * 1024); } while (0)
; #define PG8_MMA(ai, bj, At, Bt) do { __builtin_amdgcn_s_setprio(1); _Pragma("unroll") for (int m = 0; m < 4; ++m) _Pragma("unroll") for (int n = 0; n < 2; ++n) _Pragma("unroll") for (int k = 0; k < 2; ++k) \
;         acc[ai][bj][m][n] = __builtin_amdgcn_mfma_f32_16x16x32_bf16(Bt[n][k], At[m][k], acc[ai][bj][m][n], 0, 0, 0); __builtin_amdgcn_s_setprio(0); } while (0)
; #define PG8_WAIT_V(n) asm volatile("s_waitcnt vmcnt(" #n ")" ::: "memory")
; #define PG8_WAIT_L(n) asm volatile("s_waitcnt lgkmcnt(" #n ")" ::: "memory")
; #define PG8_BAR __builtin_amdgcn_s_barrier()
; #define PG8_SCHED __builtin_amdgcn_sched_barrier(0)
; template <class Epi, class Sched>
; __device__ __forceinline__ void gemm_phase(LAS unsigned char* lds, const Gemm g, const Sched& S, const Epi& E) {
;     ...
;             PG8_BAR; PG8_WAIT_L(0); PG8_MMA(1, 0, At, B0); PG8_BAR; PG8_SCHED;
;             PG8_STAGE(PG8_SB(0, 1), b2 + hstep, voffB);
;             PG8_WAIT_V(6); PG8_BAR; PG8_MMA(1, 1, At, B1); PG8_BAR;
;             PG8_LDB(B0, 1, 0); PG8_SCHED; PG8_LDA(At, 1, 0); PG8_STAGE(PG8_SA(0, 1), a2 + hstep, voffA);
;             PG8_WAIT_L(8); PG8_BAR; PG8_WAIT_L(0); PG8_MMA(0, 0, At, B0); PG8_BAR; PG8_SCHED;
;             PG8_LDB(B1, 1, 1); PG8_STAGE(PG8_SB(1, 0), b3, voffB);
;             PG8_BAR; PG8_WAIT_L(0); PG8_MMA(0, 1, At, B1); PG8_BAR;
;             PG8_LDA(At, 1, 1); PG8_STAGE(PG8_SA(1, 0), a3, voffA);
	v_mfma_f32_16x16x32_bf16 v[10:13], v[190:193], v[222:225], v[10:13]
	s_setprio 0
	s_add_u32 s24, s48, 0x40000
	s_addc_u32 s25, s49, 0
	s_add_i32 s39, s51, s94
	s_mov_b32 m0, s39
	s_nop 0
	global_load_lds_dwordx4 v134, s[24:25]
	s_add_i32 m0, s39, 0x2000
	s_nop 0
	global_load_lds_dwordx4 v130, s[24:25]
	s_waitcnt vmcnt(6)
	s_barrier
	s_setprio 1
	v_mfma_f32_16x16x32_bf16 v[54:57], v[226:229], v[194:197], 0
	ds_read_b128 v[142:145], v249 offset:32768
	ds_read_b128 v[182:185], v249 offset:33792
	v_mfma_f32_16x16x32_bf16 v[54:57], v[230:233], v[198:201], v[54:57]
	ds_read_b128 v[186:189], v249 offset:34816
	ds_read_b128 v[190:193], v249 offset:35840
	v_mfma_f32_16x16x32_bf16 v[50:53], v[234:237], v[194:197], 0
	ds_read_b128 v[194:197], v166 offset:32768
	v_mfma_f32_16x16x32_bf16 v[50:53], v[238:241], v[198:201], v[50:53]
	ds_read_b128 v[198:201], v166 offset:33792
	v_mfma_f32_16x16x32_bf16 v[38:41], v[226:229], v[202:205], 0
	v_mfma_f32_16x16x32_bf16 v[38:41], v[230:233], v[206:209], v[38:41]
	v_mfma_f32_16x16x32_bf16 v[34:37], v[234:237], v[202:205], 0
	ds_read_b128 v[202:205], v166 offset:34816
	v_mfma_f32_16x16x32_bf16 v[34:37], v[238:241], v[206:209], v[34:37]
	ds_read_b128 v[206:209], v166 offset:35840
	v_mfma_f32_16x16x32_bf16 v[22:25], v[226:229], v[210:213], 0
	v_mfma_f32_16x16x32_bf16 v[22:25], v[230:233], v[214:217], v[22:25]
	v_mfma_f32_16x16x32_bf16 v[18:21], v[234:237], v[210:213], 0
	ds_read_b128 v[210:213], v166 offset:36864
	v_mfma_f32_16x16x32_bf16 v[18:21], v[238:241], v[214:217], v[18:21]
	ds_read_b128 v[214:217], v166 offset:37888
	v_mfma_f32_16x16x32_bf16 v[6:9], v[226:229], v[218:221], 0
	v_mfma_f32_16x16x32_bf16 v[6:9], v[230:233], v[222:225], v[6:9]
	v_mfma_f32_16x16x32_bf16 v[2:5], v[234:237], v[218:221], 0
	ds_read_b128 v[218:221], v166 offset:38912
	s_barrier
	v_mfma_f32_16x16x32_bf16 v[2:5], v[238:241], v[222:225], v[2:5]
	s_setprio 0
	s_add_i32 s39, 0, 0x18000
	s_add_u32 s24, vcc_lo, 0x40000
	s_addc_u32 s25, vcc_hi, 0
	s_mov_b32 m0, s97
	ds_read_b128 v[222:225], v166 offset:39936
	global_load_lds_dwordx4 v136, s[24:25]
	s_mov_b32 m0, s98
	s_nop 0
	global_load_lds_dwordx4 v132, s[24:25]
	s_waitcnt lgkmcnt(8)
	s_barrier
	s_waitcnt lgkmcnt(0)
	s_setprio 1
	s_waitcnt lgkmcnt(0)
	v_mfma_f32_16x16x32_bf16 v[126:129], v[142:145], v[194:197], v[126:129]
	v_mfma_f32_16x16x32_bf16 v[126:129], v[182:185], v[198:201], v[126:129]
	v_mfma_f32_16x16x32_bf16 v[122:125], v[186:189], v[194:197], v[122:125]
	v_mfma_f32_16x16x32_bf16 v[122:125], v[190:193], v[198:201], v[122:125]
	v_mfma_f32_16x16x32_bf16 v[110:113], v[142:145], v[202:205], v[110:113]
	v_mfma_f32_16x16x32_bf16 v[110:113], v[182:185], v[206:209], v[110:113]
	v_mfma_f32_16x16x32_bf16 v[106:109], v[186:189], v[202:205], v[106:109]
	v_mfma_f32_16x16x32_bf16 v[106:109], v[190:193], v[206:209], v[106:109]
	v_mfma_f32_16x16x32_bf16 v[94:97], v[142:145], v[210:213], v[94:97]
	v_mfma_f32_16x16x32_bf16 v[94:97], v[182:185], v[214:217], v[94:97]
	v_mfma_f32_16x16x32_bf16 v[90:93], v[186:189], v[210:213], v[90:93]
	v_mfma_f32_16x16x32_bf16 v[90:93], v[190:193], v[214:217], v[90:93]
	v_mfma_f32_16x16x32_bf16 v[78:81], v[142:145], v[218:221], v[78:81]
	v_mfma_f32_16x16x32_bf16 v[78:81], v[182:185], v[222:225], v[78:81]
	v_mfma_f32_16x16x32_bf16 v[74:77], v[186:189], v[218:221], v[74:77]
	s_barrier
	v_mfma_f32_16x16x32_bf16 v[74:77], v[190:193], v[222:225], v[74:77]
	s_setprio 0
	s_add_i32 s51, 0, 0x1c000
	s_add_i32 s24, s39, s94
	s_add_i32 m0, s24, 0xffffff80
	ds_read_b128 v[226:229], v249 offset:49152
	ds_read_b128 v[230:233], v249 offset:50176
	ds_read_b128 v[234:237], v249 offset:51200
	ds_read_b128 v[238:241], v249 offset:52224
	global_load_lds_dwordx4 v134, s[48:49] offset:128
	s_add_i32 m0, s24, 0x1f80
	s_nop 0
	global_load_lds_dwordx4 v130, s[48:49] offset:128
	s_barrier
	s_waitcnt lgkmcnt(0)
	s_setprio 1
	s_waitcnt lgkmcnt(0)
	v_mfma_f32_16x16x32_bf16 v[118:121], v[226:229], v[194:197], v[118:121]
	v_mfma_f32_16x16x32_bf16 v[118:121], v[230:233], v[198:201], v[118:121]
	v_mfma_f32_16x16x32_bf16 v[114:117], v[234:237], v[194:197], v[114:117]
	v_mfma_f32_16x16x32_bf16 v[114:117], v[238:241], v[198:201], v[114:117]
	v_mfma_f32_16x16x32_bf16 v[102:105], v[226:229], v[202:205], v[102:105]
	v_mfma_f32_16x16x32_bf16 v[102:105], v[230:233], v[206:209], v[102:105]
	v_mfma_f32_16x16x32_bf16 v[98:101], v[234:237], v[202:205], v[98:101]
	v_mfma_f32_16x16x32_bf16 v[98:101], v[238:241], v[206:209], v[98:101]
	v_mfma_f32_16x16x32_bf16 v[86:89], v[226:229], v[210:213], v[86:89]
	v_mfma_f32_16x16x32_bf16 v[86:89], v[230:233], v[214:217], v[86:89]
	v_mfma_f32_16x16x32_bf16 v[82:85], v[234:237], v[210:213], v[82:85]
	v_mfma_f32_16x16x32_bf16 v[82:85], v[238:241], v[214:217], v[82:85]
	v_mfma_f32_16x16x32_bf16 v[70:73], v[226:229], v[218:221], v[70:73]
	v_mfma_f32_16x16x32_bf16 v[70:73], v[230:233], v[222:225], v[70:73]
	v_mfma_f32_16x16x32_bf16 v[66:69], v[234:237], v[218:221], v[66:69]
	s_barrier
	v_mfma_f32_16x16x32_bf16 v[66:69], v[238:241], v[222:225], v[66:69]
	s_setprio 0
	s_add_i32 m0, s99, 0xffffff80
	ds_read_b128 v[194:197], v166 offset:49152
	ds_read_b128 v[198:201], v166 offset:50176
	ds_read_b128 v[202:205], v166 offset:51200
	ds_read_b128 v[206:209], v166 offset:52224
	ds_read_b128 v[210:213], v166 offset:53248
	ds_read_b128 v[214:217], v166 offset:54272
	ds_read_b128 v[218:221], v166 offset:55296
	ds_read_b128 v[222:225], v166 offset:56320
	global_load_lds_dwordx4 v136, vcc offset:128
	s_add_i32 m0, s82, 0xffffff80
	s_nop 0
	global_load_lds_dwordx4 v132, vcc offset:128
	s_waitcnt vmcnt(8)
	s_barrier
; #define PG8_STAGE(bufoff, gbase, voff) do { _Pragma("unroll") for (int _i = 0; _i < 2; ++_i) \
;         __builtin_amdgcn_global_load_lds((const unsigned*)((const char*)(gbase) + (voff)[_i]), (LAS unsigned*)(lds + (bufoff) + ldsw + _i * 8192), 16, 0, 0); } while (0)
; #define PG8_LDA(dst, b, h) do { _Pragma("unroll") for (int m = 0; m < 4; ++m) _Pragma("unroll") for (int k = 0; k < 2; ++k) dst[m][k] = *(const LAS bf16x8*)(lds + PG8_SA(b, h) + aoff + m * 2048 + k * 1024); } while (0)
; #define PG8_LDB(dst, b, h) do { _Pragma("unroll") for (int n = 0; n < 2; ++n) _Pragma("unroll") for (int k = 0; k < 2; ++k) dst[n][k] = *(const LAS bf16x8*)(lds + PG8_SB(b, h) + boff + n * 2048 + k * 1024); } while (0)
; #define PG8_WAIT_V(n) asm volatile("s_waitcnt vmcnt(" #n ")" ::: "memory")
; #define PG8_WAIT_L(n) asm volatile("s_waitcnt lgkmcnt(" #n ")" ::: "memory")
; #define PG8_BAR __builtin_amdgcn_s_barrier()
; #define PG8_SCHED __builtin_amdgcn_sched_barrier(0)
; template <class Epi, class Sched>
; __device__ __forceinline__ void gemm_phase(LAS unsigned char* lds, const Gemm g, const Sched& S, const Epi& E) {
;     ...
;             const bool last = (t == nt - 2);
;             const char* a1 = cA + (size_t)(t + 1) * kstep;
;             const char* a2 = last ? nA : cA + (size_t)(t + 2) * kstep; const char* b2 = last ? nB : cB + (size_t)(t + 2) * kstep;
;             const char* a3 = a2 + kstep; const char* b3 = b2 + kstep;
;             PG8_LDB(B0, 0, 0); PG8_SCHED; PG8_LDA(At, 0, 0); PG8_STAGE(PG8_SA(1, 1), a1 + hstep, voffA);
;             PG8_WAIT_L(8); PG8_BAR; PG8_WAIT_L(0); PG8_MMA(0, 0, At, B0); PG8_BAR; PG8_SCHED;
;             PG8_LDB(B1, 0, 1); PG8_STAGE(PG8_SB(0, 0), b2, voffB);
;     ...
;             PG8_LDB(B0, 1, 0); PG8_SCHED; PG8_LDA(At, 1, 0); PG8_STAGE(PG8_SA(0, 1), a2 + hstep, voffA);
;             PG8_WAIT_L(8); PG8_BAR; PG8_WAIT_L(0); PG8_MMA(0, 0, At, B0); PG8_BAR; PG8_SCHED;
;             PG8_LDB(B1, 1, 1); PG8_STAGE(PG8_SB(1, 0), b3, voffB);
;             PG8_BAR; PG8_WAIT_L(0); PG8_MMA(0, 1, At, B1); PG8_BAR;
;             PG8_LDA(At, 1, 1); PG8_STAGE(PG8_SA(1, 0), a3, voffA);
;             PG8_BAR; PG8_WAIT_L(0); PG8_MMA(1, 0, At, B0); PG8_BAR; PG8_SCHED;
;             PG8_STAGE(PG8_SB(1, 1), b3 + hstep, voffB);
;             PG8_WAIT_V(6); PG8_BAR; PG8_MMA(1, 1, At, B1); PG8_BAR;
	s_waitcnt lgkmcnt(0)
	s_setprio 1
	s_waitcnt lgkmcnt(0)
	v_mfma_f32_16x16x32_bf16 v[62:65], v[142:145], v[194:197], v[62:65]
	v_mfma_f32_16x16x32_bf16 v[62:65], v[182:185], v[198:201], v[62:65]
	v_mfma_f32_16x16x32_bf16 v[58:61], v[186:189], v[194:197], v[58:61]
	v_mfma_f32_16x16x32_bf16 v[58:61], v[190:193], v[198:201], v[58:61]
	v_mfma_f32_16x16x32_bf16 v[46:49], v[142:145], v[202:205], v[46:49]
	v_mfma_f32_16x16x32_bf16 v[46:49], v[182:185], v[206:209], v[46:49]
	v_mfma_f32_16x16x32_bf16 v[42:45], v[186:189], v[202:205], v[42:45]
	v_mfma_f32_16x16x32_bf16 v[42:45], v[190:193], v[206:209], v[42:45]
	v_mfma_f32_16x16x32_bf16 v[30:33], v[142:145], v[210:213], v[30:33]
	v_mfma_f32_16x16x32_bf16 v[30:33], v[182:185], v[214:217], v[30:33]
	v_mfma_f32_16x16x32_bf16 v[26:29], v[186:189], v[210:213], v[26:29]
	v_mfma_f32_16x16x32_bf16 v[26:29], v[190:193], v[214:217], v[26:29]
	v_mfma_f32_16x16x32_bf16 v[14:17], v[142:145], v[218:221], v[14:17]
	v_mfma_f32_16x16x32_bf16 v[14:17], v[182:185], v[222:225], v[14:17]
	v_mfma_f32_16x16x32_bf16 v[10:13], v[186:189], v[218:221], v[10:13]
	s_barrier
	v_mfma_f32_16x16x32_bf16 v[10:13], v[190:193], v[222:225], v[10:13]
	s_setprio 0
	s_add_u32 s24, s48, 0x40080
	s_addc_u32 s25, s49, 0
	s_add_i32 s39, s51, s94
	s_mov_b32 m0, s39
	s_nop 0
	global_load_lds_dwordx4 v134, s[24:25]
	s_add_i32 m0, s39, 0x2000
	s_nop 0
	global_load_lds_dwordx4 v130, s[24:25]
	s_waitcnt vmcnt(6)
	s_barrier
	s_setprio 1
	v_mfma_f32_16x16x32_bf16 v[54:57], v[226:229], v[194:197], v[54:57]
	ds_read_b128 v[142:145], v249
	ds_read_b128 v[182:185], v249 offset:1024
	v_mfma_f32_16x16x32_bf16 v[54:57], v[230:233], v[198:201], v[54:57]
	ds_read_b128 v[186:189], v249 offset:2048
	ds_read_b128 v[190:193], v249 offset:3072
	v_mfma_f32_16x16x32_bf16 v[50:53], v[234:237], v[194:197], v[50:53]
	ds_read_b128 v[194:197], v166
	v_mfma_f32_16x16x32_bf16 v[50:53], v[238:241], v[198:201], v[50:53]
	ds_read_b128 v[198:201], v166 offset:1024
	v_mfma_f32_16x16x32_bf16 v[38:41], v[226:229], v[202:205], v[38:41]
	v_mfma_f32_16x16x32_bf16 v[38:41], v[230:233], v[206:209], v[38:41]
	v_mfma_f32_16x16x32_bf16 v[34:37], v[234:237], v[202:205], v[34:37]
	ds_read_b128 v[202:205], v166 offset:2048
	v_mfma_f32_16x16x32_bf16 v[34:37], v[238:241], v[206:209], v[34:37]
	ds_read_b128 v[206:209], v166 offset:3072
	v_mfma_f32_16x16x32_bf16 v[22:25], v[226:229], v[210:213], v[22:25]
	v_mfma_f32_16x16x32_bf16 v[22:25], v[230:233], v[214:217], v[22:25]
	v_mfma_f32_16x16x32_bf16 v[18:21], v[234:237], v[210:213], v[18:21]
	ds_read_b128 v[210:213], v166 offset:4096
	v_mfma_f32_16x16x32_bf16 v[18:21], v[238:241], v[214:217], v[18:21]
	ds_read_b128 v[214:217], v166 offset:5120
	v_mfma_f32_16x16x32_bf16 v[6:9], v[226:229], v[218:221], v[6:9]
	v_mfma_f32_16x16x32_bf16 v[6:9], v[230:233], v[222:225], v[6:9]
	v_mfma_f32_16x16x32_bf16 v[2:5], v[234:237], v[218:221], v[2:5]
	ds_read_b128 v[218:221], v166 offset:6144
	s_barrier
	v_mfma_f32_16x16x32_bf16 v[2:5], v[238:241], v[222:225], v[2:5]
	s_setprio 0
	s_add_i32 s38, s38, 2
	s_add_u32 s35, s35, 0x100
	s_addc_u32 s50, s50, 0
	s_add_u32 s0, s0, 0x100
	s_addc_u32 s1, s1, 0
	s_cmp_gt_u32 s38, 13
.LBB0_557:
	s_add_u32 s24, s0, 0xfffc0080
	s_addc_u32 s25, s1, -1
	s_add_i32 s39, 0, 0x10000
	s_cmp_eq_u32 s38, 12
	s_cselect_b32 vcc_hi, s77, s25
	s_cselect_b32 vcc_lo, s76, s24
	s_cselect_b32 s49, s45, s50
	s_cselect_b32 s48, s47, s35
	s_add_i32 m0, s95, 0xc000
	ds_read_b128 v[222:225], v166 offset:7168
	global_load_lds_dwordx4 v140, s[0:1]
	s_add_i32 m0, s95, 0xe000
	s_nop 0
	global_load_lds_dwordx4 v138, s[0:1]
	s_waitcnt lgkmcnt(8)
	s_barrier
	s_waitcnt lgkmcnt(0)
	s_setprio 1
	s_waitcnt lgkmcnt(0)
	v_mfma_f32_16x16x32_bf16 v[126:129], v[142:145], v[194:197], v[126:129]
	v_mfma_f32_16x16x32_bf16 v[126:129], v[182:185], v[198:201], v[126:129]
	v_mfma_f32_16x16x32_bf16 v[122:125], v[186:189], v[194:197], v[122:125]
	v_mfma_f32_16x16x32_bf16 v[122:125], v[190:193], v[198:201], v[122:125]
	v_mfma_f32_16x16x32_bf16 v[110:113], v[142:145], v[202:205], v[110:113]
	v_mfma_f32_16x16x32_bf16 v[110:113], v[182:185], v[206:209], v[110:113]
	v_mfma_f32_16x16x32_bf16 v[106:109], v[186:189], v[202:205], v[106:109]
	v_mfma_f32_16x16x32_bf16 v[106:109], v[190:193], v[206:209], v[106:109]
	v_mfma_f32_16x16x32_bf16 v[94:97], v[142:145], v[210:213], v[94:97]
	v_mfma_f32_16x16x32_bf16 v[94:97], v[182:185], v[214:217], v[94:97]
	v_mfma_f32_16x16x32_bf16 v[90:93], v[186:189], v[210:213], v[90:93]
	v_mfma_f32_16x16x32_bf16 v[90:93], v[190:193], v[214:217], v[90:93]
	v_mfma_f32_16x16x32_bf16 v[78:81], v[142:145], v[218:221], v[78:81]
	v_mfma_f32_16x16x32_bf16 v[78:81], v[182:185], v[222:225], v[78:81]
	v_mfma_f32_16x16x32_bf16 v[74:77], v[186:189], v[218:221], v[74:77]
	s_barrier
	v_mfma_f32_16x16x32_bf16 v[74:77], v[190:193], v[222:225], v[74:77]
	s_setprio 0
	s_add_i32 s51, 0, 0x14000
	s_add_i32 s24, s39, s94
	ds_read_b128 v[226:229], v249 offset:16384
	ds_read_b128 v[230:233], v249 offset:17408
	ds_read_b128 v[234:237], v249 offset:18432
	ds_read_b128 v[238:241], v249 offset:19456
	s_mov_b32 m0, s24
	global_load_lds_dwordx4 v134, s[48:49]
	s_add_i32 m0, s24, 0x2000
	s_nop 0
	global_load_lds_dwordx4 v130, s[48:49]
	s_barrier
; #define PG8_STAGE(bufoff, gbase, voff) do { _Pragma("unroll") for (int _i = 0; _i < 2; ++_i) \
;         __builtin_amdgcn_global_load_lds((const unsigned*)((const char*)(gbase) + (voff)[_i]), (LAS unsigned*)(lds + (bufoff) + ldsw + _i * 8192), 16, 0, 0); } while (0)
; #define PG8_LDA(dst, b, h) do { _Pragma("unroll") for (int m = 0; m < 4; ++m) _Pragma("unroll") for (int k = 0; k < 2; ++k) dst[m][k] = *(const LAS bf16x8*)(lds + PG8_SA(b, h) + aoff + m * 2048 + k * 1024); } while (0)
; #define PG8_LDB(dst, b, h) do { _Pragma("unroll") for (int n = 0; n < 2; ++n) _Pragma("unroll") for (int k = 0; k < 2; ++k) dst[n][k] = *(const LAS bf16x8*)(lds + PG8_SB(b, h) + boff + n * 2048 + k * 1024); } while (0)
; #define PG8_MMA(ai, bj, At, Bt) do { __builtin_amdgcn_s_setprio(1); _Pragma("unroll") for (int m = 0; m < 4; ++m) _Pragma("unroll") for (int n = 0; n < 2; ++n) _Pragma("unroll") for (int k = 0; k < 2; ++k) \
;         acc[ai][bj][m][n] = __builtin_amdgcn_mfma_f32_16x16x32_bf16(Bt[n][k], At[m][k], acc[ai][bj][m][n], 0, 0, 0); __builtin_amdgcn_s_setprio(0); } while (0)
; #define PG8_WAIT_V(n) asm volatile("s_waitcnt vmcnt(" #n ")" ::: "memory")
; #define PG8_WAIT_L(n) asm volatile("s_waitcnt lgkmcnt(" #n ")" ::: "memory")
; #define PG8_BAR __builtin_amdgcn_s_barrier()
; #define PG8_SCHED __builtin_amdgcn_sched_barrier(0)
; template <class Epi, class Sched>
; __device__ __forceinline__ void gemm_phase(LAS unsigned char* lds, const Gemm g, const Sched& S, const Epi& E) {
;     ...
;             PG8_BAR; PG8_WAIT_L(0); PG8_MMA(0, 1, At, B1); PG8_BAR;
;             PG8_LDA(At, 0, 1); PG8_STAGE(PG8_SA(0, 0), a2, voffA);
;             PG8_BAR; PG8_WAIT_L(0); PG8_MMA(1, 0, At, B0); PG8_BAR; PG8_SCHED;
;             PG8_STAGE(PG8_SB(0, 1), b2 + hstep, voffB);
;             PG8_WAIT_V(6); PG8_BAR; PG8_MMA(1, 1, At, B1); PG8_BAR;
;             PG8_LDB(B0, 1, 0); PG8_SCHED; PG8_LDA(At, 1, 0); PG8_STAGE(PG8_SA(0, 1), a2 + hstep, voffA);
;             PG8_WAIT_L(8); PG8_BAR; PG8_WAIT_L(0); PG8_MMA(0, 0, At, B0); PG8_BAR; PG8_SCHED;
	s_waitcnt lgkmcnt(0)
	s_setprio 1
	s_waitcnt lgkmcnt(0)
	v_mfma_f32_16x16x32_bf16 v[118:121], v[226:229], v[194:197], v[118:121]
	v_mfma_f32_16x16x32_bf16 v[118:121], v[230:233], v[198:201], v[118:121]
	v_mfma_f32_16x16x32_bf16 v[114:117], v[234:237], v[194:197], v[114:117]
	v_mfma_f32_16x16x32_bf16 v[114:117], v[238:241], v[198:201], v[114:117]
	v_mfma_f32_16x16x32_bf16 v[102:105], v[226:229], v[202:205], v[102:105]
	v_mfma_f32_16x16x32_bf16 v[102:105], v[230:233], v[206:209], v[102:105]
	v_mfma_f32_16x16x32_bf16 v[98:101], v[234:237], v[202:205], v[98:101]
	v_mfma_f32_16x16x32_bf16 v[98:101], v[238:241], v[206:209], v[98:101]
	v_mfma_f32_16x16x32_bf16 v[86:89], v[226:229], v[210:213], v[86:89]
	v_mfma_f32_16x16x32_bf16 v[86:89], v[230:233], v[214:217], v[86:89]
	v_mfma_f32_16x16x32_bf16 v[82:85], v[234:237], v[210:213], v[82:85]
	v_mfma_f32_16x16x32_bf16 v[82:85], v[238:241], v[214:217], v[82:85]
	v_mfma_f32_16x16x32_bf16 v[70:73], v[226:229], v[218:221], v[70:73]
	v_mfma_f32_16x16x32_bf16 v[70:73], v[230:233], v[222:225], v[70:73]
	v_mfma_f32_16x16x32_bf16 v[66:69], v[234:237], v[218:221], v[66:69]
	s_barrier
	v_mfma_f32_16x16x32_bf16 v[66:69], v[238:241], v[222:225], v[66:69]
	s_setprio 0
	s_mov_b32 m0, s95
	ds_read_b128 v[194:197], v166 offset:16384
	ds_read_b128 v[198:201], v166 offset:17408
	ds_read_b128 v[202:205], v166 offset:18432
	ds_read_b128 v[206:209], v166 offset:19456
	ds_read_b128 v[210:213], v166 offset:20480
	ds_read_b128 v[214:217], v166 offset:21504
	ds_read_b128 v[218:221], v166 offset:22528
	ds_read_b128 v[222:225], v166 offset:23552
	global_load_lds_dwordx4 v136, vcc
	s_mov_b32 m0, s96
	s_nop 0
	global_load_lds_dwordx4 v132, vcc
	s_waitcnt vmcnt(8)
	s_barrier
	s_waitcnt lgkmcnt(0)
	s_setprio 1
	s_waitcnt lgkmcnt(0)
	v_mfma_f32_16x16x32_bf16 v[62:65], v[142:145], v[194:197], v[62:65]
	v_mfma_f32_16x16x32_bf16 v[62:65], v[182:185], v[198:201], v[62:65]
	v_mfma_f32_16x16x32_bf16 v[58:61], v[186:189], v[194:197], v[58:61]
	v_mfma_f32_16x16x32_bf16 v[58:61], v[190:193], v[198:201], v[58:61]
	v_mfma_f32_16x16x32_bf16 v[46:49], v[142:145], v[202:205], v[46:49]
	v_mfma_f32_16x16x32_bf16 v[46:49], v[182:185], v[206:209], v[46:49]
	v_mfma_f32_16x16x32_bf16 v[42:45], v[186:189], v[202:205], v[42:45]
	v_mfma_f32_16x16x32_bf16 v[42:45], v[190:193], v[206:209], v[42:45]
	v_mfma_f32_16x16x32_bf16 v[30:33], v[142:145], v[210:213], v[30:33]
	v_mfma_f32_16x16x32_bf16 v[30:33], v[182:185], v[214:217], v[30:33]
	v_mfma_f32_16x16x32_bf16 v[26:29], v[186:189], v[210:213], v[26:29]
	v_mfma_f32_16x16x32_bf16 v[26:29], v[190:193], v[214:217], v[26:29]
	v_mfma_f32_16x16x32_bf16 v[14:17], v[142:145], v[218:221], v[14:17]
	v_mfma_f32_16x16x32_bf16 v[14:17], v[182:185], v[222:225], v[14:17]
	v_mfma_f32_16x16x32_bf16 v[10:13], v[186:189], v[218:221], v[10:13]
	s_barrier
	v_mfma_f32_16x16x32_bf16 v[10:13], v[190:193], v[222:225], v[10:13]
	s_setprio 0
	s_add_u32 s24, s48, 0x40000
	s_addc_u32 s25, s49, 0
	s_add_i32 s39, s51, s94
	s_mov_b32 m0, s39
	s_nop 0
	global_load_lds_dwordx4 v134, s[24:25]
	s_add_i32 m0, s39, 0x2000
	s_nop 0
	global_load_lds_dwordx4 v130, s[24:25]
	s_waitcnt vmcnt(6)
	s_barrier
	s_setprio 1
	v_mfma_f32_16x16x32_bf16 v[54:57], v[226:229], v[194:197], v[54:57]
	ds_read_b128 v[142:145], v249 offset:32768
	ds_read_b128 v[182:185], v249 offset:33792
	v_mfma_f32_16x16x32_bf16 v[54:57], v[230:233], v[198:201], v[54:57]
	ds_read_b128 v[186:189], v249 offset:34816
	ds_read_b128 v[190:193], v249 offset:35840
	v_mfma_f32_16x16x32_bf16 v[50:53], v[234:237], v[194:197], v[50:53]
	ds_read_b128 v[194:197], v166 offset:32768
	v_mfma_f32_16x16x32_bf16 v[50:53], v[238:241], v[198:201], v[50:53]
	ds_read_b128 v[198:201], v166 offset:33792
	v_mfma_f32_16x16x32_bf16 v[38:41], v[226:229], v[202:205], v[38:41]
	v_mfma_f32_16x16x32_bf16 v[38:41], v[230:233], v[206:209], v[38:41]
	v_mfma_f32_16x16x32_bf16 v[34:37], v[234:237], v[202:205], v[34:37]
	ds_read_b128 v[202:205], v166 offset:34816
	v_mfma_f32_16x16x32_bf16 v[34:37], v[238:241], v[206:209], v[34:37]
	ds_read_b128 v[206:209], v166 offset:35840
	v_mfma_f32_16x16x32_bf16 v[22:25], v[226:229], v[210:213], v[22:25]
	v_mfma_f32_16x16x32_bf16 v[22:25], v[230:233], v[214:217], v[22:25]
	v_mfma_f32_16x16x32_bf16 v[18:21], v[234:237], v[210:213], v[18:21]
	ds_read_b128 v[210:213], v166 offset:36864
	v_mfma_f32_16x16x32_bf16 v[18:21], v[238:241], v[214:217], v[18:21]
	ds_read_b128 v[214:217], v166 offset:37888
	v_mfma_f32_16x16x32_bf16 v[6:9], v[226:229], v[218:221], v[6:9]
	v_mfma_f32_16x16x32_bf16 v[6:9], v[230:233], v[222:225], v[6:9]
	v_mfma_f32_16x16x32_bf16 v[2:5], v[234:237], v[218:221], v[2:5]
	ds_read_b128 v[218:221], v166 offset:38912
	s_barrier
	v_mfma_f32_16x16x32_bf16 v[2:5], v[238:241], v[222:225], v[2:5]
	s_setprio 0
	s_add_i32 s39, 0, 0x18000
	s_add_u32 s24, vcc_lo, 0x40000
	s_addc_u32 s25, vcc_hi, 0
	s_mov_b32 m0, s97
	ds_read_b128 v[222:225], v166 offset:39936
	global_load_lds_dwordx4 v136, s[24:25]
	s_mov_b32 m0, s98
	s_nop 0
	global_load_lds_dwordx4 v132, s[24:25]
	s_waitcnt lgkmcnt(8)
	s_barrier
	s_waitcnt lgkmcnt(0)
	s_setprio 1
	s_waitcnt lgkmcnt(0)
	v_mfma_f32_16x16x32_bf16 v[126:129], v[142:145], v[194:197], v[126:129]
	v_mfma_f32_16x16x32_bf16 v[126:129], v[182:185], v[198:201], v[126:129]
	v_mfma_f32_16x16x32_bf16 v[122:125], v[186:189], v[194:197], v[122:125]
	v_mfma_f32_16x16x32_bf16 v[122:125], v[190:193], v[198:201], v[122:125]
	v_mfma_f32_16x16x32_bf16 v[110:113], v[142:145], v[202:205], v[110:113]
	v_mfma_f32_16x16x32_bf16 v[110:113], v[182:185], v[206:209], v[110:113]
	v_mfma_f32_16x16x32_bf16 v[106:109], v[186:189], v[202:205], v[106:109]
	v_mfma_f32_16x16x32_bf16 v[106:109], v[190:193], v[206:209], v[106:109]
	v_mfma_f32_16x16x32_bf16 v[94:97], v[142:145], v[210:213], v[94:97]
	v_mfma_f32_16x16x32_bf16 v[94:97], v[182:185], v[214:217], v[94:97]
	v_mfma_f32_16x16x32_bf16 v[90:93], v[186:189], v[210:213], v[90:93]
	v_mfma_f32_16x16x32_bf16 v[90:93], v[190:193], v[214:217], v[90:93]
	v_mfma_f32_16x16x32_bf16 v[78:81], v[142:145], v[218:221], v[78:81]
	v_mfma_f32_16x16x32_bf16 v[78:81], v[182:185], v[222:225], v[78:81]
	v_mfma_f32_16x16x32_bf16 v[74:77], v[186:189], v[218:221], v[74:77]
	s_barrier
; #define PG8_STAGE(bufoff, gbase, voff) do { _Pragma("unroll") for (int _i = 0; _i < 2; ++_i) \
;         __builtin_amdgcn_global_load_lds((const unsigned*)((const char*)(gbase) + (voff)[_i]), (LAS unsigned*)(lds + (bufoff) + ldsw + _i * 8192), 16, 0, 0); } while (0)
; #define PG8_LDA(dst, b, h) do { _Pragma("unroll") for (int m = 0; m < 4; ++m) _Pragma("unroll") for (int k = 0; k < 2; ++k) dst[m][k] = *(const LAS bf16x8*)(lds + PG8_SA(b, h) + aoff + m * 2048 + k * 1024); } while (0)
; #define PG8_LDB(dst, b, h) do { _Pragma("unroll") for (int n = 0; n < 2; ++n) _Pragma("unroll") for (int k = 0; k < 2; ++k) dst[n][k] = *(const LAS bf16x8*)(lds + PG8_SB(b, h) + boff + n * 2048 + k * 1024); } while (0)
; #define PG8_MMA(ai, bj, At, Bt) do { __builtin_amdgcn_s_setprio(1); _Pragma("unroll") for (int m = 0; m < 4; ++m) _Pragma("unroll") for (int n = 0; n < 2; ++n) _Pragma("unroll") for (int k = 0; k < 2; ++k) \
;         acc[ai][bj][m][n] = __builtin_amdgcn_mfma_f32_16x16x32_bf16(Bt[n][k], At[m][k], acc[ai][bj][m][n], 0, 0, 0); __builtin_amdgcn_s_setprio(0); } while (0)
; #define PG8_WAIT_V(n) asm volatile("s_waitcnt vmcnt(" #n ")" ::: "memory")
; #define PG8_WAIT_L(n) asm volatile("s_waitcnt lgkmcnt(" #n ")" ::: "memory")
; #define PG8_BAR __builtin_amdgcn_s_barrier()
; #define PG8_SCHED __builtin_amdgcn_sched_barrier(0)
; template <class Epi, class Sched>
; __device__ __forceinline__ void gemm_phase(LAS unsigned char* lds, const Gemm g, const Sched& S, const Epi& E) {
;     ...
;             PG8_WAIT_L(8); PG8_BAR; PG8_WAIT_L(0); PG8_MMA(0, 0, At, B0); PG8_BAR; PG8_SCHED;
;             PG8_LDB(B1, 1, 1); PG8_STAGE(PG8_SB(1, 0), b3, voffB);
;             PG8_BAR; PG8_WAIT_L(0); PG8_MMA(0, 1, At, B1); PG8_BAR;
;             PG8_LDA(At, 1, 1); PG8_STAGE(PG8_SA(1, 0), a3, voffA);
;             PG8_BAR; PG8_WAIT_L(0); PG8_MMA(1, 0, At, B0); PG8_BAR; PG8_SCHED;
;             PG8_STAGE(PG8_SB(1, 1), b3 + hstep, voffB);
;             PG8_WAIT_V(6); PG8_BAR; PG8_MMA(1, 1, At, B1); PG8_BAR;
;         }
;         if (wr == 0) PG8_BAR;
	v_mfma_f32_16x16x32_bf16 v[74:77], v[190:193], v[222:225], v[74:77]
	s_setprio 0
	s_add_i32 s51, 0, 0x1c000
	s_add_i32 s24, s39, s94
	s_add_i32 m0, s24, 0xffffff80
	ds_read_b128 v[226:229], v249 offset:49152
	ds_read_b128 v[230:233], v249 offset:50176
	ds_read_b128 v[234:237], v249 offset:51200
	ds_read_b128 v[238:241], v249 offset:52224
	global_load_lds_dwordx4 v134, s[48:49] offset:128
	s_add_i32 m0, s24, 0x1f80
	s_nop 0
	global_load_lds_dwordx4 v130, s[48:49] offset:128
	s_barrier
	s_waitcnt lgkmcnt(0)
	s_setprio 1
	s_waitcnt lgkmcnt(0)
	v_mfma_f32_16x16x32_bf16 v[118:121], v[226:229], v[194:197], v[118:121]
	v_mfma_f32_16x16x32_bf16 v[118:121], v[230:233], v[198:201], v[118:121]
	v_mfma_f32_16x16x32_bf16 v[114:117], v[234:237], v[194:197], v[114:117]
	v_mfma_f32_16x16x32_bf16 v[114:117], v[238:241], v[198:201], v[114:117]
	v_mfma_f32_16x16x32_bf16 v[102:105], v[226:229], v[202:205], v[102:105]
	v_mfma_f32_16x16x32_bf16 v[102:105], v[230:233], v[206:209], v[102:105]
	v_mfma_f32_16x16x32_bf16 v[98:101], v[234:237], v[202:205], v[98:101]
	v_mfma_f32_16x16x32_bf16 v[98:101], v[238:241], v[206:209], v[98:101]
	v_mfma_f32_16x16x32_bf16 v[86:89], v[226:229], v[210:213], v[86:89]
	v_mfma_f32_16x16x32_bf16 v[86:89], v[230:233], v[214:217], v[86:89]
	v_mfma_f32_16x16x32_bf16 v[82:85], v[234:237], v[210:213], v[82:85]
	v_mfma_f32_16x16x32_bf16 v[82:85], v[238:241], v[214:217], v[82:85]
	v_mfma_f32_16x16x32_bf16 v[70:73], v[226:229], v[218:221], v[70:73]
	v_mfma_f32_16x16x32_bf16 v[70:73], v[230:233], v[222:225], v[70:73]
	v_mfma_f32_16x16x32_bf16 v[66:69], v[234:237], v[218:221], v[66:69]
	s_barrier
	v_mfma_f32_16x16x32_bf16 v[66:69], v[238:241], v[222:225], v[66:69]
	s_setprio 0
	s_add_i32 m0, s99, 0xffffff80
	ds_read_b128 v[194:197], v166 offset:49152
	ds_read_b128 v[198:201], v166 offset:50176
	ds_read_b128 v[202:205], v166 offset:51200
	ds_read_b128 v[206:209], v166 offset:52224
	ds_read_b128 v[210:213], v166 offset:53248
	ds_read_b128 v[214:217], v166 offset:54272
	ds_read_b128 v[218:221], v166 offset:55296
	ds_read_b128 v[222:225], v166 offset:56320
	global_load_lds_dwordx4 v136, vcc offset:128
	s_add_i32 m0, s82, 0xffffff80
	s_nop 0
	global_load_lds_dwordx4 v132, vcc offset:128
	s_waitcnt vmcnt(8)
	s_barrier
	s_waitcnt lgkmcnt(0)
	s_setprio 1
	s_waitcnt lgkmcnt(0)
	v_mfma_f32_16x16x32_bf16 v[62:65], v[142:145], v[194:197], v[62:65]
	v_mfma_f32_16x16x32_bf16 v[62:65], v[182:185], v[198:201], v[62:65]
	v_mfma_f32_16x16x32_bf16 v[58:61], v[186:189], v[194:197], v[58:61]
	v_mfma_f32_16x16x32_bf16 v[58:61], v[190:193], v[198:201], v[58:61]
	v_mfma_f32_16x16x32_bf16 v[46:49], v[142:145], v[202:205], v[46:49]
	v_mfma_f32_16x16x32_bf16 v[46:49], v[182:185], v[206:209], v[46:49]
	v_mfma_f32_16x16x32_bf16 v[42:45], v[186:189], v[202:205], v[42:45]
	v_mfma_f32_16x16x32_bf16 v[42:45], v[190:193], v[206:209], v[42:45]
	v_mfma_f32_16x16x32_bf16 v[30:33], v[142:145], v[210:213], v[30:33]
	v_mfma_f32_16x16x32_bf16 v[30:33], v[182:185], v[214:217], v[30:33]
	v_mfma_f32_16x16x32_bf16 v[26:29], v[186:189], v[210:213], v[26:29]
	v_mfma_f32_16x16x32_bf16 v[26:29], v[190:193], v[214:217], v[26:29]
	v_mfma_f32_16x16x32_bf16 v[14:17], v[142:145], v[218:221], v[14:17]
	v_mfma_f32_16x16x32_bf16 v[14:17], v[182:185], v[222:225], v[14:17]
	v_mfma_f32_16x16x32_bf16 v[10:13], v[186:189], v[218:221], v[10:13]
	s_barrier
	v_mfma_f32_16x16x32_bf16 v[10:13], v[190:193], v[222:225], v[10:13]
	s_setprio 0
	s_add_u32 s24, s48, 0x40080
	s_addc_u32 s25, s49, 0
	s_add_i32 s39, s51, s94
	s_mov_b32 m0, s39
	s_nop 0
	global_load_lds_dwordx4 v134, s[24:25]
	s_add_i32 m0, s39, 0x2000
	s_nop 0
	global_load_lds_dwordx4 v130, s[24:25]
	s_waitcnt vmcnt(6)
	s_barrier
	s_setprio 1
	v_mfma_f32_16x16x32_bf16 v[54:57], v[226:229], v[194:197], v[54:57]
	ds_read_b128 v[142:145], v249
	ds_read_b128 v[182:185], v249 offset:1024
	v_mfma_f32_16x16x32_bf16 v[54:57], v[230:233], v[198:201], v[54:57]
	ds_read_b128 v[186:189], v249 offset:2048
	ds_read_b128 v[190:193], v249 offset:3072
	v_mfma_f32_16x16x32_bf16 v[50:53], v[234:237], v[194:197], v[50:53]
	ds_read_b128 v[194:197], v166
	v_mfma_f32_16x16x32_bf16 v[50:53], v[238:241], v[198:201], v[50:53]
	ds_read_b128 v[198:201], v166 offset:1024
	v_mfma_f32_16x16x32_bf16 v[38:41], v[226:229], v[202:205], v[38:41]
	v_mfma_f32_16x16x32_bf16 v[38:41], v[230:233], v[206:209], v[38:41]
	v_mfma_f32_16x16x32_bf16 v[34:37], v[234:237], v[202:205], v[34:37]
	ds_read_b128 v[202:205], v166 offset:2048
	v_mfma_f32_16x16x32_bf16 v[34:37], v[238:241], v[206:209], v[34:37]
	ds_read_b128 v[206:209], v166 offset:3072
	v_mfma_f32_16x16x32_bf16 v[22:25], v[226:229], v[210:213], v[22:25]
	v_mfma_f32_16x16x32_bf16 v[22:25], v[230:233], v[214:217], v[22:25]
	v_mfma_f32_16x16x32_bf16 v[18:21], v[234:237], v[210:213], v[18:21]
	ds_read_b128 v[210:213], v166 offset:4096
	v_mfma_f32_16x16x32_bf16 v[18:21], v[238:241], v[214:217], v[18:21]
	ds_read_b128 v[214:217], v166 offset:5120
	v_mfma_f32_16x16x32_bf16 v[6:9], v[226:229], v[218:221], v[6:9]
	v_mfma_f32_16x16x32_bf16 v[6:9], v[230:233], v[222:225], v[6:9]
	v_mfma_f32_16x16x32_bf16 v[2:5], v[234:237], v[218:221], v[2:5]
	ds_read_b128 v[218:221], v166 offset:6144
	s_barrier
	v_mfma_f32_16x16x32_bf16 v[2:5], v[238:241], v[222:225], v[2:5]
	s_setprio 0
	s_add_i32 s38, s38, 2
	s_add_u32 s35, s35, 0x100
	s_addc_u32 s50, s50, 0
	s_add_u32 s0, s0, 0x100
	s_addc_u32 s1, s1, 0
	s_cmp_gt_u32 s38, 13
	s_cbranch_scc0 .LBB0_557
	s_waitcnt lgkmcnt(0)
	s_and_b64 vcc, exec, s[42:43]
	s_cbranch_vccz .LBB0_560
	s_barrier

; #define PG8_STAGE(bufoff, gbase, voff) do { _Pragma("unroll") for (int _i = 0; _i < 2; ++_i) \
;         __builtin_amdgcn_global_load_lds((const unsigned*)((const char*)(gbase) + (voff)[_i]), (LAS unsigned*)(lds + (bufoff) + ldsw + _i * 8192), 16, 0, 0); } while (0)
; #define PG8_LDA(dst, b, h) do { _Pragma("unroll") for (int m = 0; m < 4; ++m) _Pragma("unroll") for (int k = 0; k < 2; ++k) dst[m][k] = *(const LAS bf16x8*)(lds + PG8_SA(b, h) + aoff + m * 2048 + k * 1024); } while (0)
; #define PG8_LDB(dst, b, h) do { _Pragma("unroll") for (int n = 0; n < 2; ++n) _Pragma("unroll") for (int k = 0; k < 2; ++k) dst[n][k] = *(const LAS bf16x8*)(lds + PG8_SB(b, h) + boff + n * 2048 + k * 1024); } while (0)
; #define PG8_MMA(ai, bj, At, Bt) do { __builtin_amdgcn_s_setprio(1); _Pragma("unroll") for (int m = 0; m < 4; ++m) _Pragma("unroll") for (int n = 0; n < 2; ++n) _Pragma("unroll") for (int k = 0; k < 2; ++k) \
;         acc[ai][bj][m][n] = __builtin_amdgcn_mfma_f32_16x16x32_bf16(Bt[n][k], At[m][k], acc[ai][bj][m][n], 0, 0, 0); __builtin_amdgcn_s_setprio(0); } while (0)
; #define PG8_WAIT_L(n) asm volatile("s_waitcnt lgkmcnt(" #n ")" ::: "memory")
; template <class Epi, class Sched>
; __device__ __forceinline__ void gemm_phase(LAS unsigned char* lds, const Gemm g, const Sched& S, const Epi& E) {
;     ...
;         const bool has_next = S.next(ui + 1, nxt);
;         const char* nA = has_next ? PG8_APANEL(nxt.pm) : cA; const char* nB = has_next ? (const char*)g.Bt + (size_t)nxt.pn * tstep : cB;
;         for (int t = 0; t < nt; t += 2) {
;             const bool last = (t == nt - 2);
;             const char* a1 = cA + (size_t)(t + 1) * kstep;
;             const char* a2 = last ? nA : cA + (size_t)(t + 2) * kstep; const char* b2 = last ? nB : cB + (size_t)(t + 2) * kstep;
;             const char* a3 = a2 + kstep; const char* b3 = b2 + kstep;
;             PG8_LDB(B0, 0, 0); PG8_SCHED; PG8_LDA(At, 0, 0); PG8_STAGE(PG8_SA(1, 1), a1 + hstep, voffA);
;             PG8_WAIT_L(8); PG8_BAR; PG8_WAIT_L(0); PG8_MMA(0, 0, At, B0); PG8_BAR; PG8_SCHED;
;             PG8_LDB(B1, 0, 1); PG8_STAGE(PG8_SB(0, 0), b2, voffB);
;             PG8_BAR; PG8_WAIT_L(0); PG8_MMA(0, 1, At, B1); PG8_BAR;
;             PG8_LDA(At, 0, 1); PG8_STAGE(PG8_SA(0, 0), a2, voffA);
;             PG8_BAR; PG8_WAIT_L(0); PG8_MMA(1, 0, At, B0); PG8_BAR; PG8_SCHED;
.LBB0_626:
	s_ashr_i32 s43, s42, 31
	s_lshl_b64 s[24:25], s[42:43], 21
	s_add_u32 s60, s55, s24
	s_addc_u32 s61, s82, s25
	s_and_b64 s[0:1], s[0:1], exec
	s_cselect_b32 s43, s61, s49
	s_cselect_b32 s45, s60, s48
	s_add_u32 s35, s48, 0x100
	s_addc_u32 s50, s49, 0
	s_add_u32 s0, s76, 0x100080
	s_addc_u32 s1, s77, 0
	s_mov_b32 s98, -2
	v_add_u32_e32 v249, 0x10000, v144
	ds_read_b128 v[164:167], v249
	ds_read_b128 v[182:185], v249 offset:1024
	ds_read_b128 v[186:189], v249 offset:2048
	ds_read_b128 v[190:193], v249 offset:3072
	ds_read_b128 v[194:197], v162
	ds_read_b128 v[198:201], v162 offset:1024
	ds_read_b128 v[202:205], v162 offset:2048
	ds_read_b128 v[206:209], v162 offset:3072
	ds_read_b128 v[210:213], v162 offset:4096
	ds_read_b128 v[214:217], v162 offset:5120
	ds_read_b128 v[218:221], v162 offset:6144
	s_add_u32 s24, s0, 0xfff00080
	s_addc_u32 s25, s1, -1
	s_add_i32 s51, 0, 0x10000
	s_cmp_eq_u32 s98, 60
	s_cselect_b32 s77, s47, s25
	s_cselect_b32 s76, s46, s24
	s_cselect_b32 s49, s43, s50
	s_cselect_b32 s48, s45, s35
	s_add_i32 m0, s86, 0xc000
	ds_read_b128 v[222:225], v162 offset:7168
	global_load_lds_dwordx4 v140, s[0:1]
	s_add_i32 m0, s86, 0xe000
	s_nop 0
	global_load_lds_dwordx4 v138, s[0:1]
	s_waitcnt lgkmcnt(8)
	s_barrier
	s_waitcnt lgkmcnt(0)
	s_setprio 1
	s_waitcnt lgkmcnt(0)
	v_mfma_f32_16x16x32_bf16 v[126:129], v[164:167], v[194:197], 0
	v_mfma_f32_16x16x32_bf16 v[126:129], v[182:185], v[198:201], v[126:129]
	v_mfma_f32_16x16x32_bf16 v[122:125], v[186:189], v[194:197], 0
	v_mfma_f32_16x16x32_bf16 v[122:125], v[190:193], v[198:201], v[122:125]
	v_mfma_f32_16x16x32_bf16 v[118:121], v[164:167], v[202:205], 0
	v_mfma_f32_16x16x32_bf16 v[118:121], v[182:185], v[206:209], v[118:121]
	v_mfma_f32_16x16x32_bf16 v[110:113], v[186:189], v[202:205], 0
	v_mfma_f32_16x16x32_bf16 v[110:113], v[190:193], v[206:209], v[110:113]
	v_mfma_f32_16x16x32_bf16 v[102:105], v[164:167], v[210:213], 0
	v_mfma_f32_16x16x32_bf16 v[102:105], v[182:185], v[214:217], v[102:105]
	v_mfma_f32_16x16x32_bf16 v[94:97], v[186:189], v[210:213], 0
	v_mfma_f32_16x16x32_bf16 v[94:97], v[190:193], v[214:217], v[94:97]
	v_mfma_f32_16x16x32_bf16 v[86:89], v[164:167], v[218:221], 0
	v_mfma_f32_16x16x32_bf16 v[86:89], v[182:185], v[222:225], v[86:89]
	v_mfma_f32_16x16x32_bf16 v[78:81], v[186:189], v[218:221], 0
	s_barrier
	v_mfma_f32_16x16x32_bf16 v[78:81], v[190:193], v[222:225], v[78:81]
	s_setprio 0
	s_add_i32 s99, 0, 0x14000
	s_add_i32 s24, s51, s83
	ds_read_b128 v[226:229], v249 offset:16384
	ds_read_b128 v[230:233], v249 offset:17408
	ds_read_b128 v[234:237], v249 offset:18432
	ds_read_b128 v[238:241], v249 offset:19456
	s_mov_b32 m0, s24
	global_load_lds_dwordx4 v134, s[48:49]
	s_add_i32 m0, s24, 0x2000
	s_nop 0
	global_load_lds_dwordx4 v130, s[48:49]
	s_barrier
	s_waitcnt lgkmcnt(0)
	s_setprio 1
	s_waitcnt lgkmcnt(0)
	v_mfma_f32_16x16x32_bf16 v[114:117], v[226:229], v[194:197], 0
	v_mfma_f32_16x16x32_bf16 v[114:117], v[230:233], v[198:201], v[114:117]
	v_mfma_f32_16x16x32_bf16 v[106:109], v[234:237], v[194:197], 0
	v_mfma_f32_16x16x32_bf16 v[106:109], v[238:241], v[198:201], v[106:109]
	v_mfma_f32_16x16x32_bf16 v[98:101], v[226:229], v[202:205], 0
	v_mfma_f32_16x16x32_bf16 v[98:101], v[230:233], v[206:209], v[98:101]
	v_mfma_f32_16x16x32_bf16 v[90:93], v[234:237], v[202:205], 0
	v_mfma_f32_16x16x32_bf16 v[90:93], v[238:241], v[206:209], v[90:93]
	v_mfma_f32_16x16x32_bf16 v[82:85], v[226:229], v[210:213], 0
	v_mfma_f32_16x16x32_bf16 v[82:85], v[230:233], v[214:217], v[82:85]
	v_mfma_f32_16x16x32_bf16 v[74:77], v[234:237], v[210:213], 0
	v_mfma_f32_16x16x32_bf16 v[74:77], v[238:241], v[214:217], v[74:77]
	v_mfma_f32_16x16x32_bf16 v[70:73], v[226:229], v[218:221], 0
	v_mfma_f32_16x16x32_bf16 v[70:73], v[230:233], v[222:225], v[70:73]
	v_mfma_f32_16x16x32_bf16 v[66:69], v[234:237], v[218:221], 0
	s_barrier
	v_mfma_f32_16x16x32_bf16 v[66:69], v[238:241], v[222:225], v[66:69]
	s_setprio 0
	s_mov_b32 m0, s86
	s_mov_b64 s[100:101], s[76:77]
	ds_read_b128 v[194:197], v162 offset:16384
	ds_read_b128 v[198:201], v162 offset:17408
	ds_read_b128 v[202:205], v162 offset:18432
	ds_read_b128 v[206:209], v162 offset:19456
	ds_read_b128 v[210:213], v162 offset:20480
	ds_read_b128 v[214:217], v162 offset:21504
	ds_read_b128 v[218:221], v162 offset:22528
	ds_read_b128 v[222:225], v162 offset:23552
	global_load_lds_dwordx4 v136, s[76:77]
	s_mov_b64 s[100:101], s[76:77]
	s_mov_b32 m0, s92
	s_nop 0
	global_load_lds_dwordx4 v132, s[76:77]
	s_waitcnt vmcnt(8)
	s_barrier
	s_waitcnt lgkmcnt(0)
	s_setprio 1
	s_waitcnt lgkmcnt(0)
	v_mfma_f32_16x16x32_bf16 v[62:65], v[164:167], v[194:197], 0
	v_mfma_f32_16x16x32_bf16 v[62:65], v[182:185], v[198:201], v[62:65]
	v_mfma_f32_16x16x32_bf16 v[58:61], v[186:189], v[194:197], 0
	v_mfma_f32_16x16x32_bf16 v[58:61], v[190:193], v[198:201], v[58:61]
	v_mfma_f32_16x16x32_bf16 v[54:57], v[164:167], v[202:205], 0
	v_mfma_f32_16x16x32_bf16 v[54:57], v[182:185], v[206:209], v[54:57]
	v_mfma_f32_16x16x32_bf16 v[46:49], v[186:189], v[202:205], 0
	v_mfma_f32_16x16x32_bf16 v[46:49], v[190:193], v[206:209], v[46:49]
	v_mfma_f32_16x16x32_bf16 v[38:41], v[164:167], v[210:213], 0
	v_mfma_f32_16x16x32_bf16 v[38:41], v[182:185], v[214:217], v[38:41]
	v_mfma_f32_16x16x32_bf16 v[30:33], v[186:189], v[210:213], 0
	v_mfma_f32_16x16x32_bf16 v[30:33], v[190:193], v[214:217], v[30:33]
	v_mfma_f32_16x16x32_bf16 v[22:25], v[164:167], v[218:221], 0
	v_mfma_f32_16x16x32_bf16 v[22:25], v[182:185], v[222:225], v[22:25]
	v_mfma_f32_16x16x32_bf16 v[14:17], v[186:189], v[218:221], 0
	s_barrier
; #define PG8_STAGE(bufoff, gbase, voff) do { _Pragma("unroll") for (int _i = 0; _i < 2; ++_i) \
;         __builtin_amdgcn_global_load_lds((const unsigned*)((const char*)(gbase) + (voff)[_i]), (LAS unsigned*)(lds + (bufoff) + ldsw + _i * 8192), 16, 0, 0); } while (0)
; #define PG8_LDA(dst, b, h) do { _Pragma("unroll") for (int m = 0; m < 4; ++m) _Pragma("unroll") for (int k = 0; k < 2; ++k) dst[m][k] = *(const LAS bf16x8*)(lds + PG8_SA(b, h) + aoff + m * 2048 + k * 1024); } while (0)
; #define PG8_LDB(dst, b, h) do { _Pragma("unroll") for (int n = 0; n < 2; ++n) _Pragma("unroll") for (int k = 0; k < 2; ++k) dst[n][k] = *(const LAS bf16x8*)(lds + PG8_SB(b, h) + boff + n * 2048 + k * 1024); } while (0)
; #define PG8_MMA(ai, bj, At, Bt) do { __builtin_amdgcn_s_setprio(1); _Pragma("unroll") for (int m = 0; m < 4; ++m) _Pragma("unroll") for (int n = 0; n < 2; ++n) _Pragma("unroll") for (int k = 0; k < 2; ++k) \
;         acc[ai][bj][m][n] = __builtin_amdgcn_mfma_f32_16x16x32_bf16(Bt[n][k], At[m][k], acc[ai][bj][m][n], 0, 0, 0); __builtin_amdgcn_s_setprio(0); } while (0)
; #define PG8_WAIT_V(n) asm volatile("s_waitcnt vmcnt(" #n ")" ::: "memory")
; #define PG8_WAIT_L(n) asm volatile("s_waitcnt lgkmcnt(" #n ")" ::: "memory")
; #define PG8_BAR __builtin_amdgcn_s_barrier()
; #define PG8_SCHED __builtin_amdgcn_sched_barrier(0)
; template <class Epi, class Sched>
; __device__ __forceinline__ void gemm_phase(LAS unsigned char* lds, const Gemm g, const Sched& S, const Epi& E) {
;     ...
;             PG8_BAR; PG8_WAIT_L(0); PG8_MMA(1, 0, At, B0); PG8_BAR; PG8_SCHED;
;             PG8_STAGE(PG8_SB(0, 1), b2 + hstep, voffB);
;             PG8_WAIT_V(6); PG8_BAR; PG8_MMA(1, 1, At, B1); PG8_BAR;
;             PG8_LDB(B0, 1, 0); PG8_SCHED; PG8_LDA(At, 1, 0); PG8_STAGE(PG8_SA(0, 1), a2 + hstep, voffA);
;             PG8_WAIT_L(8); PG8_BAR; PG8_WAIT_L(0); PG8_MMA(0, 0, At, B0); PG8_BAR; PG8_SCHED;
;             PG8_LDB(B1, 1, 1); PG8_STAGE(PG8_SB(1, 0), b3, voffB);
;             PG8_BAR; PG8_WAIT_L(0); PG8_MMA(0, 1, At, B1); PG8_BAR;
;             PG8_LDA(At, 1, 1); PG8_STAGE(PG8_SA(1, 0), a3, voffA);
	v_mfma_f32_16x16x32_bf16 v[14:17], v[190:193], v[222:225], v[14:17]
	s_setprio 0
	s_add_u32 s24, s48, 0x100000
	s_addc_u32 s25, s49, 0
	s_add_i32 s51, s99, s83
	s_mov_b32 m0, s51
	s_nop 0
	global_load_lds_dwordx4 v134, s[24:25]
	s_add_i32 m0, s51, 0x2000
	s_nop 0
	global_load_lds_dwordx4 v130, s[24:25]
	s_waitcnt vmcnt(6)
	s_barrier
	s_setprio 1
	v_mfma_f32_16x16x32_bf16 v[50:53], v[226:229], v[194:197], 0
	ds_read_b128 v[164:167], v249 offset:32768
	ds_read_b128 v[182:185], v249 offset:33792
	v_mfma_f32_16x16x32_bf16 v[50:53], v[230:233], v[198:201], v[50:53]
	ds_read_b128 v[186:189], v249 offset:34816
	ds_read_b128 v[190:193], v249 offset:35840
	v_mfma_f32_16x16x32_bf16 v[42:45], v[234:237], v[194:197], 0
	ds_read_b128 v[194:197], v162 offset:32768
	v_mfma_f32_16x16x32_bf16 v[42:45], v[238:241], v[198:201], v[42:45]
	ds_read_b128 v[198:201], v162 offset:33792
	v_mfma_f32_16x16x32_bf16 v[34:37], v[226:229], v[202:205], 0
	v_mfma_f32_16x16x32_bf16 v[34:37], v[230:233], v[206:209], v[34:37]
	v_mfma_f32_16x16x32_bf16 v[26:29], v[234:237], v[202:205], 0
	ds_read_b128 v[202:205], v162 offset:34816
	v_mfma_f32_16x16x32_bf16 v[26:29], v[238:241], v[206:209], v[26:29]
	ds_read_b128 v[206:209], v162 offset:35840
	v_mfma_f32_16x16x32_bf16 v[18:21], v[226:229], v[210:213], 0
	v_mfma_f32_16x16x32_bf16 v[18:21], v[230:233], v[214:217], v[18:21]
	v_mfma_f32_16x16x32_bf16 v[10:13], v[234:237], v[210:213], 0
	ds_read_b128 v[210:213], v162 offset:36864
	v_mfma_f32_16x16x32_bf16 v[10:13], v[238:241], v[214:217], v[10:13]
	ds_read_b128 v[214:217], v162 offset:37888
	v_mfma_f32_16x16x32_bf16 v[6:9], v[226:229], v[218:221], 0
	v_mfma_f32_16x16x32_bf16 v[6:9], v[230:233], v[222:225], v[6:9]
	v_mfma_f32_16x16x32_bf16 v[2:5], v[234:237], v[218:221], 0
	ds_read_b128 v[218:221], v162 offset:38912
	s_barrier
	v_mfma_f32_16x16x32_bf16 v[2:5], v[238:241], v[222:225], v[2:5]
	s_setprio 0
	s_add_i32 s51, 0, 0x18000
	s_add_u32 s24, s76, 0x100000
	s_addc_u32 s25, s77, 0
	s_mov_b32 m0, s93
	ds_read_b128 v[222:225], v162 offset:39936
	global_load_lds_dwordx4 v136, s[24:25]
	s_mov_b32 m0, s94
	s_nop 0
	global_load_lds_dwordx4 v132, s[24:25]
	s_waitcnt lgkmcnt(8)
	s_barrier
	s_waitcnt lgkmcnt(0)
	s_setprio 1
	s_waitcnt lgkmcnt(0)
	v_mfma_f32_16x16x32_bf16 v[126:129], v[164:167], v[194:197], v[126:129]
	v_mfma_f32_16x16x32_bf16 v[126:129], v[182:185], v[198:201], v[126:129]
	v_mfma_f32_16x16x32_bf16 v[122:125], v[186:189], v[194:197], v[122:125]
	v_mfma_f32_16x16x32_bf16 v[122:125], v[190:193], v[198:201], v[122:125]
	v_mfma_f32_16x16x32_bf16 v[118:121], v[164:167], v[202:205], v[118:121]
	v_mfma_f32_16x16x32_bf16 v[118:121], v[182:185], v[206:209], v[118:121]
	v_mfma_f32_16x16x32_bf16 v[110:113], v[186:189], v[202:205], v[110:113]
	v_mfma_f32_16x16x32_bf16 v[110:113], v[190:193], v[206:209], v[110:113]
	v_mfma_f32_16x16x32_bf16 v[102:105], v[164:167], v[210:213], v[102:105]
	v_mfma_f32_16x16x32_bf16 v[102:105], v[182:185], v[214:217], v[102:105]
	v_mfma_f32_16x16x32_bf16 v[94:97], v[186:189], v[210:213], v[94:97]
	v_mfma_f32_16x16x32_bf16 v[94:97], v[190:193], v[214:217], v[94:97]
	v_mfma_f32_16x16x32_bf16 v[86:89], v[164:167], v[218:221], v[86:89]
	v_mfma_f32_16x16x32_bf16 v[86:89], v[182:185], v[222:225], v[86:89]
	v_mfma_f32_16x16x32_bf16 v[78:81], v[186:189], v[218:221], v[78:81]
	s_barrier
	v_mfma_f32_16x16x32_bf16 v[78:81], v[190:193], v[222:225], v[78:81]
	s_setprio 0
	s_add_i32 s76, 0, 0x1c000
	s_add_i32 s24, s51, s83
	s_add_i32 m0, s24, 0xffffff80
	ds_read_b128 v[226:229], v249 offset:49152
	ds_read_b128 v[230:233], v249 offset:50176
	ds_read_b128 v[234:237], v249 offset:51200
	ds_read_b128 v[238:241], v249 offset:52224
	global_load_lds_dwordx4 v134, s[48:49] offset:128
	s_add_i32 m0, s24, 0x1f80
	s_nop 0
	global_load_lds_dwordx4 v130, s[48:49] offset:128
	s_barrier
	s_waitcnt lgkmcnt(0)
	s_setprio 1
	s_waitcnt lgkmcnt(0)
	v_mfma_f32_16x16x32_bf16 v[114:117], v[226:229], v[194:197], v[114:117]
	v_mfma_f32_16x16x32_bf16 v[114:117], v[230:233], v[198:201], v[114:117]
	v_mfma_f32_16x16x32_bf16 v[106:109], v[234:237], v[194:197], v[106:109]
	v_mfma_f32_16x16x32_bf16 v[106:109], v[238:241], v[198:201], v[106:109]
	v_mfma_f32_16x16x32_bf16 v[98:101], v[226:229], v[202:205], v[98:101]
	v_mfma_f32_16x16x32_bf16 v[98:101], v[230:233], v[206:209], v[98:101]
	v_mfma_f32_16x16x32_bf16 v[90:93], v[234:237], v[202:205], v[90:93]
	v_mfma_f32_16x16x32_bf16 v[90:93], v[238:241], v[206:209], v[90:93]
	v_mfma_f32_16x16x32_bf16 v[82:85], v[226:229], v[210:213], v[82:85]
	v_mfma_f32_16x16x32_bf16 v[82:85], v[230:233], v[214:217], v[82:85]
	v_mfma_f32_16x16x32_bf16 v[74:77], v[234:237], v[210:213], v[74:77]
	v_mfma_f32_16x16x32_bf16 v[74:77], v[238:241], v[214:217], v[74:77]
	v_mfma_f32_16x16x32_bf16 v[70:73], v[226:229], v[218:221], v[70:73]
	v_mfma_f32_16x16x32_bf16 v[70:73], v[230:233], v[222:225], v[70:73]
	v_mfma_f32_16x16x32_bf16 v[66:69], v[234:237], v[218:221], v[66:69]
	s_barrier
	v_mfma_f32_16x16x32_bf16 v[66:69], v[238:241], v[222:225], v[66:69]
	s_setprio 0
	s_add_i32 m0, s95, 0xffffff80
	ds_read_b128 v[194:197], v162 offset:49152
	ds_read_b128 v[198:201], v162 offset:50176
	ds_read_b128 v[202:205], v162 offset:51200
	ds_read_b128 v[206:209], v162 offset:52224
	ds_read_b128 v[210:213], v162 offset:53248
	ds_read_b128 v[214:217], v162 offset:54272
	ds_read_b128 v[218:221], v162 offset:55296
	ds_read_b128 v[222:225], v162 offset:56320
	global_load_lds_dwordx4 v136, s[100:101] offset:128
	s_add_i32 m0, s96, 0xffffff80
	s_nop 0
	global_load_lds_dwordx4 v132, s[100:101] offset:128
	s_waitcnt vmcnt(8)
	s_barrier
; #define PG8_STAGE(bufoff, gbase, voff) do { _Pragma("unroll") for (int _i = 0; _i < 2; ++_i) \
;         __builtin_amdgcn_global_load_lds((const unsigned*)((const char*)(gbase) + (voff)[_i]), (LAS unsigned*)(lds + (bufoff) + ldsw + _i * 8192), 16, 0, 0); } while (0)
; #define PG8_LDA(dst, b, h) do { _Pragma("unroll") for (int m = 0; m < 4; ++m) _Pragma("unroll") for (int k = 0; k < 2; ++k) dst[m][k] = *(const LAS bf16x8*)(lds + PG8_SA(b, h) + aoff + m * 2048 + k * 1024); } while (0)
; #define PG8_LDB(dst, b, h) do { _Pragma("unroll") for (int n = 0; n < 2; ++n) _Pragma("unroll") for (int k = 0; k < 2; ++k) dst[n][k] = *(const LAS bf16x8*)(lds + PG8_SB(b, h) + boff + n * 2048 + k * 1024); } while (0)
; #define PG8_WAIT_V(n) asm volatile("s_waitcnt vmcnt(" #n ")" ::: "memory")
; #define PG8_WAIT_L(n) asm volatile("s_waitcnt lgkmcnt(" #n ")" ::: "memory")
; #define PG8_BAR __builtin_amdgcn_s_barrier()
; #define PG8_SCHED __builtin_amdgcn_sched_barrier(0)
; template <class Epi, class Sched>
; __device__ __forceinline__ void gemm_phase(LAS unsigned char* lds, const Gemm g, const Sched& S, const Epi& E) {
;     ...
;             const bool last = (t == nt - 2);
;             const char* a1 = cA + (size_t)(t + 1) * kstep;
;             const char* a2 = last ? nA : cA + (size_t)(t + 2) * kstep; const char* b2 = last ? nB : cB + (size_t)(t + 2) * kstep;
;             const char* a3 = a2 + kstep; const char* b3 = b2 + kstep;
;             PG8_LDB(B0, 0, 0); PG8_SCHED; PG8_LDA(At, 0, 0); PG8_STAGE(PG8_SA(1, 1), a1 + hstep, voffA);
;             PG8_WAIT_L(8); PG8_BAR; PG8_WAIT_L(0); PG8_MMA(0, 0, At, B0); PG8_BAR; PG8_SCHED;
;             PG8_LDB(B1, 0, 1); PG8_STAGE(PG8_SB(0, 0), b2, voffB);
;     ...
;             PG8_LDB(B0, 1, 0); PG8_SCHED; PG8_LDA(At, 1, 0); PG8_STAGE(PG8_SA(0, 1), a2 + hstep, voffA);
;             PG8_WAIT_L(8); PG8_BAR; PG8_WAIT_L(0); PG8_MMA(0, 0, At, B0); PG8_BAR; PG8_SCHED;
;             PG8_LDB(B1, 1, 1); PG8_STAGE(PG8_SB(1, 0), b3, voffB);
;             PG8_BAR; PG8_WAIT_L(0); PG8_MMA(0, 1, At, B1); PG8_BAR;
;             PG8_LDA(At, 1, 1); PG8_STAGE(PG8_SA(1, 0), a3, voffA);
;             PG8_BAR; PG8_WAIT_L(0); PG8_MMA(1, 0, At, B0); PG8_BAR; PG8_SCHED;
;             PG8_STAGE(PG8_SB(1, 1), b3 + hstep, voffB);
;             PG8_WAIT_V(6); PG8_BAR; PG8_MMA(1, 1, At, B1); PG8_BAR;
	s_waitcnt lgkmcnt(0)
	s_setprio 1
	s_waitcnt lgkmcnt(0)
	v_mfma_f32_16x16x32_bf16 v[62:65], v[164:167], v[194:197], v[62:65]
	v_mfma_f32_16x16x32_bf16 v[62:65], v[182:185], v[198:201], v[62:65]
	v_mfma_f32_16x16x32_bf16 v[58:61], v[186:189], v[194:197], v[58:61]
	v_mfma_f32_16x16x32_bf16 v[58:61], v[190:193], v[198:201], v[58:61]
	v_mfma_f32_16x16x32_bf16 v[54:57], v[164:167], v[202:205], v[54:57]
	v_mfma_f32_16x16x32_bf16 v[54:57], v[182:185], v[206:209], v[54:57]
	v_mfma_f32_16x16x32_bf16 v[46:49], v[186:189], v[202:205], v[46:49]
	v_mfma_f32_16x16x32_bf16 v[46:49], v[190:193], v[206:209], v[46:49]
	v_mfma_f32_16x16x32_bf16 v[38:41], v[164:167], v[210:213], v[38:41]
	v_mfma_f32_16x16x32_bf16 v[38:41], v[182:185], v[214:217], v[38:41]
	v_mfma_f32_16x16x32_bf16 v[30:33], v[186:189], v[210:213], v[30:33]
	v_mfma_f32_16x16x32_bf16 v[30:33], v[190:193], v[214:217], v[30:33]
	v_mfma_f32_16x16x32_bf16 v[22:25], v[164:167], v[218:221], v[22:25]
	v_mfma_f32_16x16x32_bf16 v[22:25], v[182:185], v[222:225], v[22:25]
	v_mfma_f32_16x16x32_bf16 v[14:17], v[186:189], v[218:221], v[14:17]
	s_barrier
	v_mfma_f32_16x16x32_bf16 v[14:17], v[190:193], v[222:225], v[14:17]
	s_setprio 0
	s_add_u32 s24, s48, 0x100080
	s_addc_u32 s25, s49, 0
	s_add_i32 s48, s76, s83
	s_mov_b32 m0, s48
	s_nop 0
	global_load_lds_dwordx4 v134, s[24:25]
	s_add_i32 m0, s48, 0x2000
	s_nop 0
	global_load_lds_dwordx4 v130, s[24:25]
	s_waitcnt vmcnt(6)
	s_barrier
	s_setprio 1
	v_mfma_f32_16x16x32_bf16 v[50:53], v[226:229], v[194:197], v[50:53]
	ds_read_b128 v[164:167], v249
	ds_read_b128 v[182:185], v249 offset:1024
	v_mfma_f32_16x16x32_bf16 v[50:53], v[230:233], v[198:201], v[50:53]
	ds_read_b128 v[186:189], v249 offset:2048
	ds_read_b128 v[190:193], v249 offset:3072
	v_mfma_f32_16x16x32_bf16 v[42:45], v[234:237], v[194:197], v[42:45]
	ds_read_b128 v[194:197], v162
	v_mfma_f32_16x16x32_bf16 v[42:45], v[238:241], v[198:201], v[42:45]
	ds_read_b128 v[198:201], v162 offset:1024
	v_mfma_f32_16x16x32_bf16 v[34:37], v[226:229], v[202:205], v[34:37]
	v_mfma_f32_16x16x32_bf16 v[34:37], v[230:233], v[206:209], v[34:37]
	v_mfma_f32_16x16x32_bf16 v[26:29], v[234:237], v[202:205], v[26:29]
	ds_read_b128 v[202:205], v162 offset:2048
	v_mfma_f32_16x16x32_bf16 v[26:29], v[238:241], v[206:209], v[26:29]
	ds_read_b128 v[206:209], v162 offset:3072
	v_mfma_f32_16x16x32_bf16 v[18:21], v[226:229], v[210:213], v[18:21]
	v_mfma_f32_16x16x32_bf16 v[18:21], v[230:233], v[214:217], v[18:21]
	v_mfma_f32_16x16x32_bf16 v[10:13], v[234:237], v[210:213], v[10:13]
	ds_read_b128 v[210:213], v162 offset:4096
	v_mfma_f32_16x16x32_bf16 v[10:13], v[238:241], v[214:217], v[10:13]
	ds_read_b128 v[214:217], v162 offset:5120
	v_mfma_f32_16x16x32_bf16 v[6:9], v[226:229], v[218:221], v[6:9]
	v_mfma_f32_16x16x32_bf16 v[6:9], v[230:233], v[222:225], v[6:9]
	v_mfma_f32_16x16x32_bf16 v[2:5], v[234:237], v[218:221], v[2:5]
	ds_read_b128 v[218:221], v162 offset:6144
	s_barrier
	v_mfma_f32_16x16x32_bf16 v[2:5], v[238:241], v[222:225], v[2:5]
	s_setprio 0
	s_add_i32 s98, s98, 2
	s_add_u32 s35, s35, 0x100
	s_addc_u32 s50, s50, 0
	s_add_u32 s0, s0, 0x100
	s_addc_u32 s1, s1, 0
	s_cmp_gt_u32 s98, 61
.LBB0_627:
	s_add_u32 s24, s0, 0xfff00080
	s_addc_u32 s25, s1, -1
	s_add_i32 s51, 0, 0x10000
	s_cmp_eq_u32 s98, 60
	s_cselect_b32 s77, s47, s25
	s_cselect_b32 s76, s46, s24
	s_cselect_b32 s49, s43, s50
	s_cselect_b32 s48, s45, s35
	s_add_i32 m0, s86, 0xc000
	ds_read_b128 v[222:225], v162 offset:7168
	global_load_lds_dwordx4 v140, s[0:1]
	s_add_i32 m0, s86, 0xe000
	s_nop 0
	global_load_lds_dwordx4 v138, s[0:1]
	s_waitcnt lgkmcnt(8)
	s_barrier
	s_waitcnt lgkmcnt(0)
	s_setprio 1
	s_waitcnt lgkmcnt(0)
	v_mfma_f32_16x16x32_bf16 v[126:129], v[164:167], v[194:197], v[126:129]
	v_mfma_f32_16x16x32_bf16 v[126:129], v[182:185], v[198:201], v[126:129]
	v_mfma_f32_16x16x32_bf16 v[122:125], v[186:189], v[194:197], v[122:125]
	v_mfma_f32_16x16x32_bf16 v[122:125], v[190:193], v[198:201], v[122:125]
	v_mfma_f32_16x16x32_bf16 v[118:121], v[164:167], v[202:205], v[118:121]
	v_mfma_f32_16x16x32_bf16 v[118:121], v[182:185], v[206:209], v[118:121]
	v_mfma_f32_16x16x32_bf16 v[110:113], v[186:189], v[202:205], v[110:113]
	v_mfma_f32_16x16x32_bf16 v[110:113], v[190:193], v[206:209], v[110:113]
	v_mfma_f32_16x16x32_bf16 v[102:105], v[164:167], v[210:213], v[102:105]
	v_mfma_f32_16x16x32_bf16 v[102:105], v[182:185], v[214:217], v[102:105]
	v_mfma_f32_16x16x32_bf16 v[94:97], v[186:189], v[210:213], v[94:97]
	v_mfma_f32_16x16x32_bf16 v[94:97], v[190:193], v[214:217], v[94:97]
	v_mfma_f32_16x16x32_bf16 v[86:89], v[164:167], v[218:221], v[86:89]
	v_mfma_f32_16x16x32_bf16 v[86:89], v[182:185], v[222:225], v[86:89]
	v_mfma_f32_16x16x32_bf16 v[78:81], v[186:189], v[218:221], v[78:81]
	s_barrier
	v_mfma_f32_16x16x32_bf16 v[78:81], v[190:193], v[222:225], v[78:81]
	s_setprio 0
	s_add_i32 s99, 0, 0x14000
	s_add_i32 s24, s51, s83
	ds_read_b128 v[226:229], v249 offset:16384
	ds_read_b128 v[230:233], v249 offset:17408
	ds_read_b128 v[234:237], v249 offset:18432
	ds_read_b128 v[238:241], v249 offset:19456
	s_mov_b32 m0, s24
	global_load_lds_dwordx4 v134, s[48:49]
	s_add_i32 m0, s24, 0x2000
	s_nop 0
	global_load_lds_dwordx4 v130, s[48:49]
	s_barrier
; #define PG8_STAGE(bufoff, gbase, voff) do { _Pragma("unroll") for (int _i = 0; _i < 2; ++_i) \
;         __builtin_amdgcn_global_load_lds((const unsigned*)((const char*)(gbase) + (voff)[_i]), (LAS unsigned*)(lds + (bufoff) + ldsw + _i * 8192), 16, 0, 0); } while (0)
; #define PG8_LDA(dst, b, h) do { _Pragma("unroll") for (int m = 0; m < 4; ++m) _Pragma("unroll") for (int k = 0; k < 2; ++k) dst[m][k] = *(const LAS bf16x8*)(lds + PG8_SA(b, h) + aoff + m * 2048 + k * 1024); } while (0)
; #define PG8_LDB(dst, b, h) do { _Pragma("unroll") for (int n = 0; n < 2; ++n) _Pragma("unroll") for (int k = 0; k < 2; ++k) dst[n][k] = *(const LAS bf16x8*)(lds + PG8_SB(b, h) + boff + n * 2048 + k * 1024); } while (0)
; #define PG8_MMA(ai, bj, At, Bt) do { __builtin_amdgcn_s_setprio(1); _Pragma("unroll") for (int m = 0; m < 4; ++m) _Pragma("unroll") for (int n = 0; n < 2; ++n) _Pragma("unroll") for (int k = 0; k < 2; ++k) \
;         acc[ai][bj][m][n] = __builtin_amdgcn_mfma_f32_16x16x32_bf16(Bt[n][k], At[m][k], acc[ai][bj][m][n], 0, 0, 0); __builtin_amdgcn_s_setprio(0); } while (0)
; #define PG8_WAIT_V(n) asm volatile("s_waitcnt vmcnt(" #n ")" ::: "memory")
; #define PG8_WAIT_L(n) asm volatile("s_waitcnt lgkmcnt(" #n ")" ::: "memory")
; #define PG8_BAR __builtin_amdgcn_s_barrier()
; #define PG8_SCHED __builtin_amdgcn_sched_barrier(0)
; template <class Epi, class Sched>
; __device__ __forceinline__ void gemm_phase(LAS unsigned char* lds, const Gemm g, const Sched& S, const Epi& E) {
;     ...
;             PG8_BAR; PG8_WAIT_L(0); PG8_MMA(0, 1, At, B1); PG8_BAR;
;             PG8_LDA(At, 0, 1); PG8_STAGE(PG8_SA(0, 0), a2, voffA);
;             PG8_BAR; PG8_WAIT_L(0); PG8_MMA(1, 0, At, B0); PG8_BAR; PG8_SCHED;
;             PG8_STAGE(PG8_SB(0, 1), b2 + hstep, voffB);
;             PG8_WAIT_V(6); PG8_BAR; PG8_MMA(1, 1, At, B1); PG8_BAR;
;             PG8_LDB(B0, 1, 0); PG8_SCHED; PG8_LDA(At, 1, 0); PG8_STAGE(PG8_SA(0, 1), a2 + hstep, voffA);
;             PG8_WAIT_L(8); PG8_BAR; PG8_WAIT_L(0); PG8_MMA(0, 0, At, B0); PG8_BAR; PG8_SCHED;
	s_waitcnt lgkmcnt(0)
	s_setprio 1
	s_waitcnt lgkmcnt(0)
	v_mfma_f32_16x16x32_bf16 v[114:117], v[226:229], v[194:197], v[114:117]
	v_mfma_f32_16x16x32_bf16 v[114:117], v[230:233], v[198:201], v[114:117]
	v_mfma_f32_16x16x32_bf16 v[106:109], v[234:237], v[194:197], v[106:109]
	v_mfma_f32_16x16x32_bf16 v[106:109], v[238:241], v[198:201], v[106:109]
	v_mfma_f32_16x16x32_bf16 v[98:101], v[226:229], v[202:205], v[98:101]
	v_mfma_f32_16x16x32_bf16 v[98:101], v[230:233], v[206:209], v[98:101]
	v_mfma_f32_16x16x32_bf16 v[90:93], v[234:237], v[202:205], v[90:93]
	v_mfma_f32_16x16x32_bf16 v[90:93], v[238:241], v[206:209], v[90:93]
	v_mfma_f32_16x16x32_bf16 v[82:85], v[226:229], v[210:213], v[82:85]
	v_mfma_f32_16x16x32_bf16 v[82:85], v[230:233], v[214:217], v[82:85]
	v_mfma_f32_16x16x32_bf16 v[74:77], v[234:237], v[210:213], v[74:77]
	v_mfma_f32_16x16x32_bf16 v[74:77], v[238:241], v[214:217], v[74:77]
	v_mfma_f32_16x16x32_bf16 v[70:73], v[226:229], v[218:221], v[70:73]
	v_mfma_f32_16x16x32_bf16 v[70:73], v[230:233], v[222:225], v[70:73]
	v_mfma_f32_16x16x32_bf16 v[66:69], v[234:237], v[218:221], v[66:69]
	s_barrier
	v_mfma_f32_16x16x32_bf16 v[66:69], v[238:241], v[222:225], v[66:69]
	s_setprio 0
	s_mov_b32 m0, s86
	s_mov_b64 s[100:101], s[76:77]
	ds_read_b128 v[194:197], v162 offset:16384
	ds_read_b128 v[198:201], v162 offset:17408
	ds_read_b128 v[202:205], v162 offset:18432
	ds_read_b128 v[206:209], v162 offset:19456
	ds_read_b128 v[210:213], v162 offset:20480
	ds_read_b128 v[214:217], v162 offset:21504
	ds_read_b128 v[218:221], v162 offset:22528
	ds_read_b128 v[222:225], v162 offset:23552
	global_load_lds_dwordx4 v136, s[76:77]
	s_mov_b64 s[100:101], s[76:77]
	s_mov_b32 m0, s92
	s_nop 0
	global_load_lds_dwordx4 v132, s[76:77]
	s_waitcnt vmcnt(8)
	s_barrier
	s_waitcnt lgkmcnt(0)
	s_setprio 1
	s_waitcnt lgkmcnt(0)
	v_mfma_f32_16x16x32_bf16 v[62:65], v[164:167], v[194:197], v[62:65]
	v_mfma_f32_16x16x32_bf16 v[62:65], v[182:185], v[198:201], v[62:65]
	v_mfma_f32_16x16x32_bf16 v[58:61], v[186:189], v[194:197], v[58:61]
	v_mfma_f32_16x16x32_bf16 v[58:61], v[190:193], v[198:201], v[58:61]
	v_mfma_f32_16x16x32_bf16 v[54:57], v[164:167], v[202:205], v[54:57]
	v_mfma_f32_16x16x32_bf16 v[54:57], v[182:185], v[206:209], v[54:57]
	v_mfma_f32_16x16x32_bf16 v[46:49], v[186:189], v[202:205], v[46:49]
	v_mfma_f32_16x16x32_bf16 v[46:49], v[190:193], v[206:209], v[46:49]
	v_mfma_f32_16x16x32_bf16 v[38:41], v[164:167], v[210:213], v[38:41]
	v_mfma_f32_16x16x32_bf16 v[38:41], v[182:185], v[214:217], v[38:41]
	v_mfma_f32_16x16x32_bf16 v[30:33], v[186:189], v[210:213], v[30:33]
	v_mfma_f32_16x16x32_bf16 v[30:33], v[190:193], v[214:217], v[30:33]
	v_mfma_f32_16x16x32_bf16 v[22:25], v[164:167], v[218:221], v[22:25]
	v_mfma_f32_16x16x32_bf16 v[22:25], v[182:185], v[222:225], v[22:25]
	v_mfma_f32_16x16x32_bf16 v[14:17], v[186:189], v[218:221], v[14:17]
	s_barrier
	v_mfma_f32_16x16x32_bf16 v[14:17], v[190:193], v[222:225], v[14:17]
	s_setprio 0
	s_add_u32 s24, s48, 0x100000
	s_addc_u32 s25, s49, 0
	s_add_i32 s51, s99, s83
	s_mov_b32 m0, s51
	s_nop 0
	global_load_lds_dwordx4 v134, s[24:25]
	s_add_i32 m0, s51, 0x2000
	s_nop 0
	global_load_lds_dwordx4 v130, s[24:25]
	s_waitcnt vmcnt(6)
	s_barrier
	s_setprio 1
	v_mfma_f32_16x16x32_bf16 v[50:53], v[226:229], v[194:197], v[50:53]
	ds_read_b128 v[164:167], v249 offset:32768
	ds_read_b128 v[182:185], v249 offset:33792
	v_mfma_f32_16x16x32_bf16 v[50:53], v[230:233], v[198:201], v[50:53]
	ds_read_b128 v[186:189], v249 offset:34816
	ds_read_b128 v[190:193], v249 offset:35840
	v_mfma_f32_16x16x32_bf16 v[42:45], v[234:237], v[194:197], v[42:45]
	ds_read_b128 v[194:197], v162 offset:32768
	v_mfma_f32_16x16x32_bf16 v[42:45], v[238:241], v[198:201], v[42:45]
	ds_read_b128 v[198:201], v162 offset:33792
	v_mfma_f32_16x16x32_bf16 v[34:37], v[226:229], v[202:205], v[34:37]
	v_mfma_f32_16x16x32_bf16 v[34:37], v[230:233], v[206:209], v[34:37]
	v_mfma_f32_16x16x32_bf16 v[26:29], v[234:237], v[202:205], v[26:29]
	ds_read_b128 v[202:205], v162 offset:34816
	v_mfma_f32_16x16x32_bf16 v[26:29], v[238:241], v[206:209], v[26:29]
	ds_read_b128 v[206:209], v162 offset:35840
	v_mfma_f32_16x16x32_bf16 v[18:21], v[226:229], v[210:213], v[18:21]
	v_mfma_f32_16x16x32_bf16 v[18:21], v[230:233], v[214:217], v[18:21]
	v_mfma_f32_16x16x32_bf16 v[10:13], v[234:237], v[210:213], v[10:13]
	ds_read_b128 v[210:213], v162 offset:36864
	v_mfma_f32_16x16x32_bf16 v[10:13], v[238:241], v[214:217], v[10:13]
	ds_read_b128 v[214:217], v162 offset:37888
	v_mfma_f32_16x16x32_bf16 v[6:9], v[226:229], v[218:221], v[6:9]
	v_mfma_f32_16x16x32_bf16 v[6:9], v[230:233], v[222:225], v[6:9]
	v_mfma_f32_16x16x32_bf16 v[2:5], v[234:237], v[218:221], v[2:5]
	ds_read_b128 v[218:221], v162 offset:38912
	s_barrier
	v_mfma_f32_16x16x32_bf16 v[2:5], v[238:241], v[222:225], v[2:5]
	s_setprio 0
	s_add_i32 s51, 0, 0x18000
	s_add_u32 s24, s76, 0x100000
	s_addc_u32 s25, s77, 0
	s_mov_b32 m0, s93
	ds_read_b128 v[222:225], v162 offset:39936
	global_load_lds_dwordx4 v136, s[24:25]
	s_mov_b32 m0, s94
	s_nop 0
	global_load_lds_dwordx4 v132, s[24:25]
	s_waitcnt lgkmcnt(8)
	s_barrier
; #define PG8_STAGE(bufoff, gbase, voff) do { _Pragma("unroll") for (int _i = 0; _i < 2; ++_i) \
;         __builtin_amdgcn_global_load_lds((const unsigned*)((const char*)(gbase) + (voff)[_i]), (LAS unsigned*)(lds + (bufoff) + ldsw + _i * 8192), 16, 0, 0); } while (0)
; #define PG8_LDA(dst, b, h) do { _Pragma("unroll") for (int m = 0; m < 4; ++m) _Pragma("unroll") for (int k = 0; k < 2; ++k) dst[m][k] = *(const LAS bf16x8*)(lds + PG8_SA(b, h) + aoff + m * 2048 + k * 1024); } while (0)
; #define PG8_LDB(dst, b, h) do { _Pragma("unroll") for (int n = 0; n < 2; ++n) _Pragma("unroll") for (int k = 0; k < 2; ++k) dst[n][k] = *(const LAS bf16x8*)(lds + PG8_SB(b, h) + boff + n * 2048 + k * 1024); } while (0)
; #define PG8_MMA(ai, bj, At, Bt) do { __builtin_amdgcn_s_setprio(1); _Pragma("unroll") for (int m = 0; m < 4; ++m) _Pragma("unroll") for (int n = 0; n < 2; ++n) _Pragma("unroll") for (int k = 0; k < 2; ++k) \
;         acc[ai][bj][m][n] = __builtin_amdgcn_mfma_f32_16x16x32_bf16(Bt[n][k], At[m][k], acc[ai][bj][m][n], 0, 0, 0); __builtin_amdgcn_s_setprio(0); } while (0)
; #define PG8_WAIT_V(n) asm volatile("s_waitcnt vmcnt(" #n ")" ::: "memory")
; #define PG8_WAIT_L(n) asm volatile("s_waitcnt lgkmcnt(" #n ")" ::: "memory")
; #define PG8_BAR __builtin_amdgcn_s_barrier()
; #define PG8_SCHED __builtin_amdgcn_sched_barrier(0)
; template <class Epi, class Sched>
; __device__ __forceinline__ void gemm_phase(LAS unsigned char* lds, const Gemm g, const Sched& S, const Epi& E) {
;     ...
;             PG8_WAIT_L(8); PG8_BAR; PG8_WAIT_L(0); PG8_MMA(0, 0, At, B0); PG8_BAR; PG8_SCHED;
;             PG8_LDB(B1, 1, 1); PG8_STAGE(PG8_SB(1, 0), b3, voffB);
;             PG8_BAR; PG8_WAIT_L(0); PG8_MMA(0, 1, At, B1); PG8_BAR;
;             PG8_LDA(At, 1, 1); PG8_STAGE(PG8_SA(1, 0), a3, voffA);
;             PG8_BAR; PG8_WAIT_L(0); PG8_MMA(1, 0, At, B0); PG8_BAR; PG8_SCHED;
;             PG8_STAGE(PG8_SB(1, 1), b3 + hstep, voffB);
;             PG8_WAIT_V(6); PG8_BAR; PG8_MMA(1, 1, At, B1); PG8_BAR;
;         }
;         if (wr == 0) PG8_BAR;
	s_waitcnt lgkmcnt(0)
	s_setprio 1
	s_waitcnt lgkmcnt(0)
	v_mfma_f32_16x16x32_bf16 v[126:129], v[164:167], v[194:197], v[126:129]
	v_mfma_f32_16x16x32_bf16 v[126:129], v[182:185], v[198:201], v[126:129]
	v_mfma_f32_16x16x32_bf16 v[122:125], v[186:189], v[194:197], v[122:125]
	v_mfma_f32_16x16x32_bf16 v[122:125], v[190:193], v[198:201], v[122:125]
	v_mfma_f32_16x16x32_bf16 v[118:121], v[164:167], v[202:205], v[118:121]
	v_mfma_f32_16x16x32_bf16 v[118:121], v[182:185], v[206:209], v[118:121]
	v_mfma_f32_16x16x32_bf16 v[110:113], v[186:189], v[202:205], v[110:113]
	v_mfma_f32_16x16x32_bf16 v[110:113], v[190:193], v[206:209], v[110:113]
	v_mfma_f32_16x16x32_bf16 v[102:105], v[164:167], v[210:213], v[102:105]
	v_mfma_f32_16x16x32_bf16 v[102:105], v[182:185], v[214:217], v[102:105]
	v_mfma_f32_16x16x32_bf16 v[94:97], v[186:189], v[210:213], v[94:97]
	v_mfma_f32_16x16x32_bf16 v[94:97], v[190:193], v[214:217], v[94:97]
	v_mfma_f32_16x16x32_bf16 v[86:89], v[164:167], v[218:221], v[86:89]
	v_mfma_f32_16x16x32_bf16 v[86:89], v[182:185], v[222:225], v[86:89]
	v_mfma_f32_16x16x32_bf16 v[78:81], v[186:189], v[218:221], v[78:81]
	s_barrier
	v_mfma_f32_16x16x32_bf16 v[78:81], v[190:193], v[222:225], v[78:81]
	s_setprio 0
	s_add_i32 s76, 0, 0x1c000
	s_add_i32 s24, s51, s83
	s_add_i32 m0, s24, 0xffffff80
	ds_read_b128 v[226:229], v249 offset:49152
	ds_read_b128 v[230:233], v249 offset:50176
	ds_read_b128 v[234:237], v249 offset:51200
	ds_read_b128 v[238:241], v249 offset:52224
	global_load_lds_dwordx4 v134, s[48:49] offset:128
	s_add_i32 m0, s24, 0x1f80
	s_nop 0
	global_load_lds_dwordx4 v130, s[48:49] offset:128
	s_barrier
	s_waitcnt lgkmcnt(0)
	s_setprio 1
	s_waitcnt lgkmcnt(0)
	v_mfma_f32_16x16x32_bf16 v[114:117], v[226:229], v[194:197], v[114:117]
	v_mfma_f32_16x16x32_bf16 v[114:117], v[230:233], v[198:201], v[114:117]
	v_mfma_f32_16x16x32_bf16 v[106:109], v[234:237], v[194:197], v[106:109]
	v_mfma_f32_16x16x32_bf16 v[106:109], v[238:241], v[198:201], v[106:109]
	v_mfma_f32_16x16x32_bf16 v[98:101], v[226:229], v[202:205], v[98:101]
	v_mfma_f32_16x16x32_bf16 v[98:101], v[230:233], v[206:209], v[98:101]
	v_mfma_f32_16x16x32_bf16 v[90:93], v[234:237], v[202:205], v[90:93]
	v_mfma_f32_16x16x32_bf16 v[90:93], v[238:241], v[206:209], v[90:93]
	v_mfma_f32_16x16x32_bf16 v[82:85], v[226:229], v[210:213], v[82:85]
	v_mfma_f32_16x16x32_bf16 v[82:85], v[230:233], v[214:217], v[82:85]
	v_mfma_f32_16x16x32_bf16 v[74:77], v[234:237], v[210:213], v[74:77]
	v_mfma_f32_16x16x32_bf16 v[74:77], v[238:241], v[214:217], v[74:77]
	v_mfma_f32_16x16x32_bf16 v[70:73], v[226:229], v[218:221], v[70:73]
	v_mfma_f32_16x16x32_bf16 v[70:73], v[230:233], v[222:225], v[70:73]
	v_mfma_f32_16x16x32_bf16 v[66:69], v[234:237], v[218:221], v[66:69]
	s_barrier
	v_mfma_f32_16x16x32_bf16 v[66:69], v[238:241], v[222:225], v[66:69]
	s_setprio 0
	s_add_i32 m0, s95, 0xffffff80
	ds_read_b128 v[194:197], v162 offset:49152
	ds_read_b128 v[198:201], v162 offset:50176
	ds_read_b128 v[202:205], v162 offset:51200
	ds_read_b128 v[206:209], v162 offset:52224
	ds_read_b128 v[210:213], v162 offset:53248
	ds_read_b128 v[214:217], v162 offset:54272
	ds_read_b128 v[218:221], v162 offset:55296
	ds_read_b128 v[222:225], v162 offset:56320
	global_load_lds_dwordx4 v136, s[100:101] offset:128
	s_add_i32 m0, s96, 0xffffff80
	s_nop 0
	global_load_lds_dwordx4 v132, s[100:101] offset:128
	s_waitcnt vmcnt(8)
	s_barrier
	s_waitcnt lgkmcnt(0)
	s_setprio 1
	s_waitcnt lgkmcnt(0)
	v_mfma_f32_16x16x32_bf16 v[62:65], v[164:167], v[194:197], v[62:65]
	v_mfma_f32_16x16x32_bf16 v[62:65], v[182:185], v[198:201], v[62:65]
	v_mfma_f32_16x16x32_bf16 v[58:61], v[186:189], v[194:197], v[58:61]
	v_mfma_f32_16x16x32_bf16 v[58:61], v[190:193], v[198:201], v[58:61]
	v_mfma_f32_16x16x32_bf16 v[54:57], v[164:167], v[202:205], v[54:57]
	v_mfma_f32_16x16x32_bf16 v[54:57], v[182:185], v[206:209], v[54:57]
	v_mfma_f32_16x16x32_bf16 v[46:49], v[186:189], v[202:205], v[46:49]
	v_mfma_f32_16x16x32_bf16 v[46:49], v[190:193], v[206:209], v[46:49]
	v_mfma_f32_16x16x32_bf16 v[38:41], v[164:167], v[210:213], v[38:41]
	v_mfma_f32_16x16x32_bf16 v[38:41], v[182:185], v[214:217], v[38:41]
	v_mfma_f32_16x16x32_bf16 v[30:33], v[186:189], v[210:213], v[30:33]
	v_mfma_f32_16x16x32_bf16 v[30:33], v[190:193], v[214:217], v[30:33]
	v_mfma_f32_16x16x32_bf16 v[22:25], v[164:167], v[218:221], v[22:25]
	v_mfma_f32_16x16x32_bf16 v[22:25], v[182:185], v[222:225], v[22:25]
	v_mfma_f32_16x16x32_bf16 v[14:17], v[186:189], v[218:221], v[14:17]
	s_barrier
	v_mfma_f32_16x16x32_bf16 v[14:17], v[190:193], v[222:225], v[14:17]
	s_setprio 0
	s_add_u32 s24, s48, 0x100080
	s_addc_u32 s25, s49, 0
	s_add_i32 s48, s76, s83
	s_mov_b32 m0, s48
	s_nop 0
	global_load_lds_dwordx4 v134, s[24:25]
	s_add_i32 m0, s48, 0x2000
	s_nop 0
	global_load_lds_dwordx4 v130, s[24:25]
	s_waitcnt vmcnt(6)
	s_barrier
	s_setprio 1
	v_mfma_f32_16x16x32_bf16 v[50:53], v[226:229], v[194:197], v[50:53]
	ds_read_b128 v[164:167], v249
	ds_read_b128 v[182:185], v249 offset:1024
	v_mfma_f32_16x16x32_bf16 v[50:53], v[230:233], v[198:201], v[50:53]
	ds_read_b128 v[186:189], v249 offset:2048
	ds_read_b128 v[190:193], v249 offset:3072
	v_mfma_f32_16x16x32_bf16 v[42:45], v[234:237], v[194:197], v[42:45]
	ds_read_b128 v[194:197], v162
	v_mfma_f32_16x16x32_bf16 v[42:45], v[238:241], v[198:201], v[42:45]
	ds_read_b128 v[198:201], v162 offset:1024
	v_mfma_f32_16x16x32_bf16 v[34:37], v[226:229], v[202:205], v[34:37]
	v_mfma_f32_16x16x32_bf16 v[34:37], v[230:233], v[206:209], v[34:37]
	v_mfma_f32_16x16x32_bf16 v[26:29], v[234:237], v[202:205], v[26:29]
	ds_read_b128 v[202:205], v162 offset:2048
	v_mfma_f32_16x16x32_bf16 v[26:29], v[238:241], v[206:209], v[26:29]
	ds_read_b128 v[206:209], v162 offset:3072
	v_mfma_f32_16x16x32_bf16 v[18:21], v[226:229], v[210:213], v[18:21]
	v_mfma_f32_16x16x32_bf16 v[18:21], v[230:233], v[214:217], v[18:21]
	v_mfma_f32_16x16x32_bf16 v[10:13], v[234:237], v[210:213], v[10:13]
	ds_read_b128 v[210:213], v162 offset:4096
	v_mfma_f32_16x16x32_bf16 v[10:13], v[238:241], v[214:217], v[10:13]
	ds_read_b128 v[214:217], v162 offset:5120
	v_mfma_f32_16x16x32_bf16 v[6:9], v[226:229], v[218:221], v[6:9]
	v_mfma_f32_16x16x32_bf16 v[6:9], v[230:233], v[222:225], v[6:9]
	v_mfma_f32_16x16x32_bf16 v[2:5], v[234:237], v[218:221], v[2:5]
	ds_read_b128 v[218:221], v162 offset:6144
	s_barrier
	v_mfma_f32_16x16x32_bf16 v[2:5], v[238:241], v[222:225], v[2:5]
	s_setprio 0
	s_add_i32 s98, s98, 2
	s_add_u32 s35, s35, 0x100
	s_addc_u32 s50, s50, 0
	s_add_u32 s0, s0, 0x100
	s_addc_u32 s1, s1, 0
	s_cmp_gt_u32 s98, 61
	s_cbranch_scc0 .LBB0_627
	s_waitcnt lgkmcnt(0)
	s_and_b64 vcc, exec, s[40:41]
	s_cbranch_vccz .LBB0_630
	s_barrier
